# GEMM epilogue lane exchanges use a precomputed partner-lane address instead of recomputing it before each ds_bpermute
# speedup vs baseline: 1.0225x; 1.0130x over previous
.LBB0_1157:
	s_mov_b64 s[0:1], s[60:61]
	s_load_dwordx2 s[4:5], s[0:1], 0xe8
	s_mov_b64 s[0:1], s[60:61]
	s_load_dwordx2 s[10:11], s[0:1], 0xe8
	s_mov_b64 s[2:3], s[60:61]
	s_waitcnt lgkmcnt(0)
	s_add_u32 s0, s4, 0x5210000
	v_writelane_b32 v252, s4, 39
	s_addc_u32 s1, s5, 0
	s_mov_b64 s[16:17], s[60:61]
	v_writelane_b32 v252, s5, 40
	v_writelane_b32 v252, s0, 41
	s_mov_b64 s[4:5], s[60:61]
	s_mov_b64 s[14:15], s[60:61]
	v_writelane_b32 v252, s1, 42
	s_load_dwordx2 s[0:1], s[2:3], 0xe8
	s_mov_b64 s[2:3], s[60:61]
	s_load_dwordx2 s[2:3], s[2:3], 0xe8
	s_waitcnt lgkmcnt(0)
	s_add_u32 s0, s0, 0x11210000
	s_load_dwordx2 s[4:5], s[4:5], 0xe8
	s_addc_u32 s1, s1, 0
	v_writelane_b32 v252, s0, 43
	s_mov_b64 s[12:13], s[60:61]
	s_mov_b64 s[6:7], s[60:61]
	v_writelane_b32 v252, s1, 44
	s_add_u32 s0, s2, 0x15210000
	s_addc_u32 s1, s3, 0
	v_writelane_b32 v252, s0, 45
	s_mov_b64 s[2:3], s[60:61]
	v_mov_b32_e32 v0, v163
	v_writelane_b32 v252, s1, 46
	s_waitcnt lgkmcnt(0)
	s_add_u32 s0, s4, 0x17210000
	s_addc_u32 s1, s5, 0
	v_writelane_b32 v252, s0, 47
	s_mov_b64 s[4:5], s[60:61]
	v_mov_b32_e32 v1, v228
	v_writelane_b32 v252, s1, 48
	s_and_b64 s[0:1], s[8:9], exec
	s_mov_b64 s[0:1], s[60:61]
	s_cselect_b32 s50, 64, 0
	v_readfirstlane_b32 s20, v1
	s_cselect_b32 s51, 0x3000, 0
	s_cselect_b32 s52, 0x1000, 0
	s_ashr_i32 s30, s20, 3
	s_cmpk_gt_i32 s30, 0xc7
	s_cbranch_scc1 .LBB0_1818
	s_load_dwordx2 s[16:17], s[16:17], 0xe8
	s_nop 0
	s_load_dwordx2 s[14:15], s[14:15], 0xe8
	s_nop 0
	s_load_dwordx2 s[18:19], s[12:13], 0x68
	s_load_dwordx2 s[22:23], s[2:3], 0x58
	v_ashrrev_i32_e32 v2, 1, v0
	s_waitcnt lgkmcnt(0)
	s_add_u32 s2, s16, 0x19213600
	s_addc_u32 s3, s17, 0
	s_add_u32 s12, s14, 0x108000
	s_addc_u32 s13, s15, 0
	s_lshl_b32 s14, s50, 2
	s_add_u32 s14, s18, s14
	s_load_dwordx2 s[6:7], s[6:7], 0x60
	v_and_b32_e32 v159, 0xffffff80, v2
	v_bfe_u32 v6, v0, 5, 1
	v_lshrrev_b32_e32 v2, 2, v0
	s_addc_u32 s15, s19, 0
	s_lshl_b32 s16, s51, 2
	v_bfe_u32 v3, v0, 2, 2
	v_bitop3_b32 v2, v6, v2, 3 bitop3:0x78
	s_add_u32 s16, s22, s16
	v_lshlrev_b32_e32 v200, 4, v2
	v_bitop3_b32 v2, v6, v3, 2 bitop3:0x36
	s_addc_u32 s17, s23, 0
	s_load_dwordx2 s[0:1], s[0:1], 0xe8
	s_nop 0
	s_load_dwordx2 s[22:23], s[4:5], 0xe8
	v_lshlrev_b32_e32 v201, 4, v2
	v_lshlrev_b32_e32 v2, 6, v0
	v_lshrrev_b32_e32 v7, 4, v0
	s_lshl_b32 s18, s52, 2
	v_and_b32_e32 v202, 0x37c0, v2
	v_xor_b32_e32 v2, v7, v0
	s_waitcnt lgkmcnt(0)
	s_add_u32 s18, s6, s18
	v_and_b32_e32 v197, 31, v0
	v_lshlrev_b32_e32 v2, 4, v2
	s_addc_u32 s19, s7, 0
	v_or_b32_e32 v4, v159, v197
	s_lshl_b32 s4, s20, 3
	v_and_b32_e32 v2, 48, v2
	v_mov_b32_e32 v3, v129
	v_lshlrev_b32_e32 v199, 6, v4
	s_and_b32 s34, s4, 56
	v_lshl_add_u64 v[4:5], s[0:1], 0, v[2:3]
	s_mov_b64 s[4:5], 0x3210000
	v_lshl_add_u64 v[154:155], v[4:5], 0, s[4:5]
	v_lshl_add_u64 v[2:3], s[22:23], 0, v[2:3]
	s_mov_b64 s[4:5], 0x1110000
	v_and_b32_e32 v1, 63, v0
	v_and_b32_e32 v196, 0xc0, v0
	v_ashrrev_i32_e32 v198, 2, v0
	v_lshl_add_u64 v[156:157], v[2:3], 0, s[4:5]
	v_lshlrev_b32_e32 v2, 4, v0
	v_readlane_b32 s24, v252, 41
	v_bitop3_b32 v0, v7, 3, v0 bitop3:0x48
	v_and_b32_e32 v203, 0xfffffc00, v2
	v_cmp_gt_u32_e64 s[4:5], 32, v1
	v_cmp_lt_u32_e64 s[6:7], 31, v1
	v_lshlrev_b32_e32 v2, 1, v197
	v_mov_b32_e32 v3, v129
	v_readlane_b32 s25, v252, 42
	v_lshlrev_b32_e32 v0, 4, v0
	v_mov_b32_e32 v1, v129
	v_lshl_add_u64 v[160:161], s[24:25], 0, v[2:3]
	v_lshl_add_u64 v[2:3], s[0:1], 0, v[0:1]
	s_mov_b64 s[0:1], 0x32100c0
	v_lshl_add_u64 v[168:169], v[2:3], 0, s[0:1]
	s_and_b32 s0, s20, 7
	v_lshlrev_b32_e32 v158, 2, v6
	v_lshl_add_u32 v238, s0, 11, v198
	v_lshl_add_u64 v[0:1], s[22:23], 0, v[0:1]
	s_mov_b64 s[0:1], 0x11100c0
	s_lshr_b32 s31, s20, 3
	v_or_b32_e32 v204, 8, v158
	v_or_b32_e32 v205, 16, v158
	v_or_b32_e32 v206, 24, v158
	v_or_b32_e32 v207, 32, v158
	v_or_b32_e32 v208, 40, v158
	v_or_b32_e32 v209, 48, v158
	v_or_b32_e32 v210, 56, v158
	v_or_b32_e32 v211, 64, v158
	v_or_b32_e32 v212, 0x48, v158
	v_or_b32_e32 v213, 0x50, v158
	v_or_b32_e32 v214, 0x58, v158
	v_or_b32_e32 v215, 0x60, v158
	v_or_b32_e32 v216, 0x68, v158
	v_or_b32_e32 v217, 0x70, v158
	v_or_b32_e32 v233, 0x78, v158
	v_or_b32_e32 v234, 0x18000, v202
	v_add_u32_e32 v235, 0x18000, v199
	v_or_b32_e32 v236, 0x10000, v202
	v_add_u32_e32 v237, 0x10000, v199
	v_lshl_add_u64 v[170:171], v[0:1], 0, s[0:1]
	s_lshl_b32 s35, s30, 5
	v_xor_b32_e32 v244, 32, v221
	v_lshlrev_b32_e32 v244, 2, v244
	s_branch .LBB0_1160

.LBB0_1169:
	s_or_b64 exec, exec, s[0:1]
	v_cvt_pk_bf16_f32 v131, v131, s0
	v_lshl_add_u64 v[136:137], v[136:137], 0, v[138:139]
	global_store_short v[136:137], v131, off
	ds_bpermute_b32 v135, v244, v112
	v_mov_b32_e32 v139, v112
	ds_bpermute_b32 v131, v244, v115
	ds_bpermute_b32 v136, v244, v116
	v_pk_mov_b32 v[140:141], v[114:115], v[114:115] op_sel:[1,0]
	s_waitcnt lgkmcnt(1)
	v_cndmask_b32_e64 v138, v131, 0, s[4:5]
	s_waitcnt vmcnt(1)
	v_pk_fma_f32 v[138:139], v[188:189], v[138:139], v[190:191] op_sel_hi:[0,1,0]
	v_pk_fma_f32 v[138:139], v[134:135], v[112:113], v[138:139] op_sel_hi:[0,1,1]
	v_mov_b32_e32 v142, v113
	v_mov_b32_e32 v143, v141
	v_pk_fma_f32 v[138:139], v[186:187], v[142:143], v[138:139] op_sel_hi:[0,1,1]
	s_waitcnt lgkmcnt(0)
	v_cndmask_b32_e64 v146, v136, v135, s[4:5]
	v_mul_f32_e32 v135, 0xbfb8aa3b, v138
	v_exp_f32_e32 v144, v135
	v_mul_f32_e32 v135, 0xbfb8aa3b, v139
	v_exp_f32_e32 v145, v135
	s_cmpk_gt_u32 s24, 0xfff
	s_cselect_b64 s[26:27], -1, 0
	s_cmpk_lt_u32 s24, 0x1400
	v_pk_add_f32 v[144:145], v[144:145], 1.0 op_sel_hi:[1,0]
	s_cselect_b64 s[24:25], -1, 0
	v_rcp_f32_e32 v137, v145
	s_nop 0
	v_mul_f32_e32 v135, v139, v137
	v_rcp_f32_e32 v139, v144
	s_nop 0
	v_mul_f32_e32 v137, v138, v139
	v_pk_fma_f32 v[138:139], v[188:189], v[142:143], v[190:191] op_sel_hi:[0,1,0]
	v_pk_fma_f32 v[138:139], v[114:115], v[134:135], v[138:139] op_sel_hi:[1,0,1]
	v_mov_b32_e32 v141, v146
	v_pk_fma_f32 v[140:141], v[140:141], v[186:187], v[138:139] op_sel_hi:[1,0,1]
	s_nop 0
	v_mul_f32_e32 v138, 0xbfb8aa3b, v140
	v_mul_f32_e32 v139, 0xbfb8aa3b, v141
	v_exp_f32_e32 v138, v138
	v_exp_f32_e32 v139, v139
	s_nop 0
	v_pk_add_f32 v[142:143], v[138:139], 1.0 op_sel_hi:[1,0]
	s_nop 0
	v_rcp_f32_e32 v139, v143
	s_nop 0
	v_mul_f32_e32 v138, v141, v139
	v_rcp_f32_e32 v141, v142
	s_mov_b64 s[0:1], -1
	v_mul_f32_e32 v139, v140, v141
	s_and_b64 vcc, exec, s[26:27]
	s_cbranch_vccz .LBB0_1171
	s_and_b64 s[0:1], s[24:25], exec
	v_or_b32_e32 v140, v239, v158
	v_readlane_b32 s0, v252, 45
	v_readlane_b32 s28, v252, 47
	v_ashrrev_i32_e32 v141, 31, v140
	v_readlane_b32 s1, v252, 46
	v_readlane_b32 s29, v252, 48
	v_lshlrev_b64 v[140:141], 11, v[140:141]
	s_cselect_b32 s1, s1, s29
	s_cselect_b32 s0, s0, s28
	v_readlane_b32 s36, v252, 26
	s_movk_i32 s28, 0xf000
	v_readlane_b32 s37, v252, 27
	v_lshl_add_u64 v[140:141], s[0:1], 0, v[140:141]
	s_mov_b32 s29, s37
	s_cselect_b32 s28, s28, 0xffffe800
	v_lshl_add_u64 v[140:141], v[128:129], 1, v[140:141]
	s_mov_b32 s1, s37
	v_writelane_b32 v252, s0, 26
	v_lshl_add_u64 v[140:141], v[140:141], 0, s[28:29]
	s_nop 0
	v_cvt_pk_bf16_f32 v142, v137, s0
	global_store_short v[140:141], v142, off
	v_cvt_pk_bf16_f32 v142, v135, s0
	global_store_short v[140:141], v142, off offset:2048
	v_add_co_u32_e32 v140, vcc, 0x1000, v140
	v_cvt_pk_bf16_f32 v142, v139, s0
	s_nop 0
	v_addc_co_u32_e32 v141, vcc, 0, v141, vcc
	global_store_short v[140:141], v142, off
	v_cvt_pk_bf16_f32 v142, v138, s0
	v_writelane_b32 v252, s1, 27
	global_store_short v[140:141], v142, off offset:2048
	s_mov_b64 s[0:1], 0

.LBB0_1173:
	v_mov_b32_e32 v189, v188
	ds_bpermute_b32 v138, v244, v119
	v_mov_b32_e32 v191, v190
	v_mov_b32_e32 v141, v116
	v_mov_b32_e32 v135, v134
	v_mov_b32_e32 v187, v186
	s_waitcnt lgkmcnt(0)
	v_cndmask_b32_e64 v140, v138, v131, s[4:5]
	v_pk_fma_f32 v[140:141], v[188:189], v[140:141], v[190:191]
	v_mov_b32_e32 v142, v117
	v_pk_fma_f32 v[140:141], v[116:117], v[134:135], v[140:141]
	v_mov_b32_e32 v143, v118
	v_pk_fma_f32 v[140:141], v[142:143], v[186:187], v[140:141]
	v_mul_f32_e32 v131, 0xbfb8aa3b, v140
	v_exp_f32_e32 v144, v131
	v_mul_f32_e32 v131, 0xbfb8aa3b, v141
	v_exp_f32_e32 v145, v131
	v_or_b32_e32 v182, v239, v204
	v_pk_add_f32 v[144:145], v[144:145], 1.0 op_sel_hi:[1,0]
	ds_bpermute_b32 v139, v244, v120
	v_rcp_f32_e32 v133, v145
	s_mov_b64 s[28:29], -1
	s_waitcnt lgkmcnt(0)
	v_cndmask_b32_e64 v137, v139, v136, s[4:5]
	v_ashrrev_i32_e32 v183, 31, v182
	v_mul_f32_e32 v131, v141, v133
	v_rcp_f32_e32 v136, v144
	s_nop 0
	v_mul_f32_e32 v133, v140, v136
	v_pk_fma_f32 v[140:141], v[142:143], v[188:189], v[190:191]
	v_mov_b32_e32 v136, v119
	v_pk_fma_f32 v[140:141], v[118:119], v[134:135], v[140:141]
	s_nop 0
	v_pk_fma_f32 v[140:141], v[136:137], v[186:187], v[140:141]
	s_nop 0
	v_mul_f32_e32 v136, 0xbfb8aa3b, v140
	v_mul_f32_e32 v137, 0xbfb8aa3b, v141
	v_exp_f32_e32 v136, v136
	v_exp_f32_e32 v137, v137
	s_nop 0
	v_pk_add_f32 v[142:143], v[136:137], 1.0 op_sel_hi:[1,0]
	s_nop 0
	v_rcp_f32_e32 v137, v143
	s_nop 0
	v_mul_f32_e32 v136, v141, v137
	v_rcp_f32_e32 v141, v142
	s_nop 0
	v_mul_f32_e32 v137, v140, v141
	v_cndmask_b32_e64 v140, 0, 1, s[26:27]
	v_cmp_ne_u32_e64 s[0:1], 1, v140
	s_andn2_b64 vcc, exec, s[26:27]
	s_cbranch_vccnz .LBB0_1175
	s_and_b64 s[26:27], s[24:25], exec
	v_readlane_b32 s26, v252, 45
	v_readlane_b32 s28, v252, 47
	v_readlane_b32 s27, v252, 46
	v_readlane_b32 s29, v252, 48
	v_lshlrev_b64 v[140:141], 11, v[182:183]
	s_cselect_b32 s27, s27, s29
	s_cselect_b32 s26, s26, s28
	v_readlane_b32 s36, v252, 26
	s_movk_i32 s28, 0xf000
	v_readlane_b32 s37, v252, 27
	v_lshl_add_u64 v[140:141], s[26:27], 0, v[140:141]
	s_mov_b32 s29, s37
	s_cselect_b32 s28, s28, 0xffffe800
	v_lshl_add_u64 v[140:141], v[128:129], 1, v[140:141]
	v_lshl_add_u64 v[140:141], v[140:141], 0, s[28:29]
	v_cvt_pk_bf16_f32 v142, v133, s0
	global_store_short v[140:141], v142, off
	v_cvt_pk_bf16_f32 v142, v131, s0
	s_mov_b32 s27, s37
	global_store_short v[140:141], v142, off offset:2048
	v_add_co_u32_e32 v140, vcc, 0x1000, v140
	v_writelane_b32 v252, s26, 26
	v_cvt_pk_bf16_f32 v142, v137, s0
	v_addc_co_u32_e32 v141, vcc, 0, v141, vcc
	v_writelane_b32 v252, s27, 27
	global_store_short v[140:141], v142, off
	v_cvt_pk_bf16_f32 v142, v136, s0
	s_mov_b64 s[28:29], 0
	global_store_short v[140:141], v142, off offset:2048

.LBB0_1177:
	v_mov_b32_e32 v142, v121
	ds_bpermute_b32 v131, v244, v123
	ds_bpermute_b32 v137, v244, v124
	v_mov_b32_e32 v143, v122
	v_or_b32_e32 v180, v239, v205
	v_ashrrev_i32_e32 v181, 31, v180
	s_waitcnt lgkmcnt(1)
	v_cndmask_b32_e64 v138, v131, v138, s[4:5]
	s_waitcnt lgkmcnt(0)
	v_cndmask_b32_e64 v141, v137, v139, s[4:5]
	v_mov_b32_e32 v139, v120
	v_pk_fma_f32 v[138:139], v[188:189], v[138:139], v[190:191]
	s_nop 0
	v_pk_fma_f32 v[138:139], v[120:121], v[134:135], v[138:139]
	s_nop 0
	v_pk_fma_f32 v[138:139], v[142:143], v[186:187], v[138:139]
	s_nop 0
	v_mul_f32_e32 v133, 0xbfb8aa3b, v138
	v_exp_f32_e32 v144, v133
	v_mul_f32_e32 v133, 0xbfb8aa3b, v139
	v_exp_f32_e32 v145, v133
	s_nop 0
	v_pk_add_f32 v[144:145], v[144:145], 1.0 op_sel_hi:[1,0]
	s_nop 0
	v_rcp_f32_e32 v136, v145
	s_nop 0
	v_mul_f32_e32 v133, v139, v136
	v_rcp_f32_e32 v139, v144
	s_nop 0
	v_mul_f32_e32 v136, v138, v139
	v_pk_fma_f32 v[138:139], v[142:143], v[188:189], v[190:191]
	v_mov_b32_e32 v140, v123
	v_pk_fma_f32 v[138:139], v[122:123], v[134:135], v[138:139]
	s_nop 0
	v_pk_fma_f32 v[140:141], v[140:141], v[186:187], v[138:139]
	s_nop 0
	v_mul_f32_e32 v138, 0xbfb8aa3b, v140
	v_mul_f32_e32 v139, 0xbfb8aa3b, v141
	v_exp_f32_e32 v138, v138
	v_exp_f32_e32 v139, v139
	s_nop 0
	v_pk_add_f32 v[142:143], v[138:139], 1.0 op_sel_hi:[1,0]
	s_nop 0
	v_rcp_f32_e32 v139, v143
	s_nop 0
	v_mul_f32_e32 v138, v141, v139
	v_rcp_f32_e32 v141, v142
	s_mov_b64 s[26:27], -1
	v_mul_f32_e32 v139, v140, v141
	s_and_b64 vcc, exec, s[0:1]
	s_cbranch_vccnz .LBB0_1179
	s_and_b64 s[26:27], s[24:25], exec
	v_readlane_b32 s26, v252, 45
	v_readlane_b32 s28, v252, 47
	v_readlane_b32 s27, v252, 46
	v_readlane_b32 s29, v252, 48
	v_lshlrev_b64 v[140:141], 11, v[180:181]
	s_cselect_b32 s27, s27, s29
	s_cselect_b32 s26, s26, s28
	v_readlane_b32 s36, v252, 26
	s_movk_i32 s28, 0xf000
	v_readlane_b32 s37, v252, 27
	v_lshl_add_u64 v[140:141], s[26:27], 0, v[140:141]
	s_mov_b32 s29, s37
	s_cselect_b32 s28, s28, 0xffffe800
	v_lshl_add_u64 v[140:141], v[128:129], 1, v[140:141]
	v_lshl_add_u64 v[140:141], v[140:141], 0, s[28:29]
	v_cvt_pk_bf16_f32 v142, v136, s0
	global_store_short v[140:141], v142, off
	v_cvt_pk_bf16_f32 v142, v133, s0
	s_mov_b32 s27, s37
	global_store_short v[140:141], v142, off offset:2048
	v_add_co_u32_e32 v140, vcc, 0x1000, v140
	v_writelane_b32 v252, s26, 26
	v_cvt_pk_bf16_f32 v142, v139, s0
	v_addc_co_u32_e32 v141, vcc, 0, v141, vcc
	v_writelane_b32 v252, s27, 27
	global_store_short v[140:141], v142, off
	v_cvt_pk_bf16_f32 v142, v138, s0
	s_mov_b64 s[26:27], 0
	global_store_short v[140:141], v142, off offset:2048

.LBB0_1181:
	v_mov_b32_e32 v141, v124
	ds_bpermute_b32 v136, v244, v127
	v_mov_b32_e32 v144, v125
	v_mov_b32_e32 v145, v126
	s_waitcnt lgkmcnt(0)
	v_cndmask_b32_e64 v140, v136, v131, s[4:5]
	v_pk_fma_f32 v[140:141], v[188:189], v[140:141], v[190:191]
	v_pk_fma_f32 v[140:141], v[124:125], v[134:135], v[140:141]
	v_pk_fma_f32 v[140:141], v[144:145], v[186:187], v[140:141]
	ds_bpermute_b32 v138, v244, v80
	v_mul_f32_e32 v131, 0xbfb8aa3b, v140
	v_exp_f32_e32 v146, v131
	v_mul_f32_e32 v131, 0xbfb8aa3b, v141
	v_exp_f32_e32 v147, v131
	s_waitcnt lgkmcnt(0)
	v_cndmask_b32_e64 v143, v138, v137, s[4:5]
	v_or_b32_e32 v176, v239, v206
	v_ashrrev_i32_e32 v177, 31, v176
	v_pk_add_f32 v[146:147], v[146:147], 1.0 op_sel_hi:[1,0]
	s_nop 0
	v_rcp_f32_e32 v133, v147
	s_nop 0
	v_mul_f32_e32 v131, v141, v133
	v_rcp_f32_e32 v137, v146
	s_nop 0
	v_mul_f32_e32 v133, v140, v137
	v_pk_fma_f32 v[140:141], v[144:145], v[188:189], v[190:191]
	v_mov_b32_e32 v142, v127
	v_pk_fma_f32 v[140:141], v[126:127], v[134:135], v[140:141]
	s_nop 0
	v_pk_fma_f32 v[140:141], v[142:143], v[186:187], v[140:141]
	s_nop 0
	v_mul_f32_e32 v137, 0xbfb8aa3b, v140
	v_exp_f32_e32 v142, v137
	v_mul_f32_e32 v137, 0xbfb8aa3b, v141
	v_exp_f32_e32 v143, v137
	s_nop 0
	v_pk_add_f32 v[142:143], v[142:143], 1.0 op_sel_hi:[1,0]
	s_nop 0
	v_rcp_f32_e32 v139, v143
	s_nop 0
	v_mul_f32_e32 v137, v141, v139
	v_rcp_f32_e32 v141, v142
	s_mov_b64 s[26:27], -1
	v_mul_f32_e32 v139, v140, v141
	s_and_b64 vcc, exec, s[0:1]
	s_cbranch_vccnz .LBB0_1183
	s_and_b64 s[26:27], s[24:25], exec
	v_readlane_b32 s26, v252, 45
	v_readlane_b32 s28, v252, 47
	v_readlane_b32 s27, v252, 46
	v_readlane_b32 s29, v252, 48
	v_lshlrev_b64 v[140:141], 11, v[176:177]
	s_cselect_b32 s27, s27, s29
	s_cselect_b32 s26, s26, s28
	v_readlane_b32 s36, v252, 26
	s_movk_i32 s28, 0xf000
	v_readlane_b32 s37, v252, 27
	v_lshl_add_u64 v[140:141], s[26:27], 0, v[140:141]
	s_mov_b32 s29, s37
	s_cselect_b32 s28, s28, 0xffffe800
	v_lshl_add_u64 v[140:141], v[128:129], 1, v[140:141]
	v_lshl_add_u64 v[140:141], v[140:141], 0, s[28:29]
	v_cvt_pk_bf16_f32 v142, v133, s0
	global_store_short v[140:141], v142, off
	v_cvt_pk_bf16_f32 v142, v131, s0
	s_mov_b32 s27, s37
	global_store_short v[140:141], v142, off offset:2048
	v_add_co_u32_e32 v140, vcc, 0x1000, v140
	v_writelane_b32 v252, s26, 26
	v_cvt_pk_bf16_f32 v142, v139, s0
	v_addc_co_u32_e32 v141, vcc, 0, v141, vcc
	v_writelane_b32 v252, s27, 27
	global_store_short v[140:141], v142, off
	v_cvt_pk_bf16_f32 v142, v137, s0
	s_mov_b64 s[26:27], 0
	global_store_short v[140:141], v142, off offset:2048

.LBB0_1185:
	v_mov_b32_e32 v141, v80
	ds_bpermute_b32 v137, v244, v83
	v_mov_b32_e32 v144, v81
	s_waitcnt lgkmcnt(0)
	v_cndmask_b32_e64 v140, v137, v136, s[4:5]
	v_pk_fma_f32 v[140:141], v[188:189], v[140:141], v[190:191]
	v_mov_b32_e32 v145, v82
	v_pk_fma_f32 v[140:141], v[80:81], v[134:135], v[140:141]
	v_pk_fma_f32 v[140:141], v[144:145], v[186:187], v[140:141]
	ds_bpermute_b32 v139, v244, v84
	v_mul_f32_e32 v131, 0xbfb8aa3b, v140
	v_exp_f32_e32 v146, v131
	v_mul_f32_e32 v131, 0xbfb8aa3b, v141
	v_exp_f32_e32 v147, v131
	s_waitcnt lgkmcnt(0)
	v_cndmask_b32_e64 v143, v139, v138, s[4:5]
	v_or_b32_e32 v174, v239, v207
	v_ashrrev_i32_e32 v175, 31, v174
	v_pk_add_f32 v[146:147], v[146:147], 1.0 op_sel_hi:[1,0]
	s_nop 0
	v_rcp_f32_e32 v133, v147
	s_nop 0
	v_mul_f32_e32 v131, v141, v133
	v_rcp_f32_e32 v136, v146
	s_nop 0
	v_mul_f32_e32 v133, v140, v136
	v_pk_fma_f32 v[140:141], v[144:145], v[188:189], v[190:191]
	v_mov_b32_e32 v142, v83
	v_pk_fma_f32 v[140:141], v[82:83], v[134:135], v[140:141]
	s_nop 0
	v_pk_fma_f32 v[140:141], v[142:143], v[186:187], v[140:141]
	s_nop 0
	v_mul_f32_e32 v136, 0xbfb8aa3b, v140
	v_exp_f32_e32 v142, v136
	v_mul_f32_e32 v136, 0xbfb8aa3b, v141
	v_exp_f32_e32 v143, v136
	s_nop 0
	v_pk_add_f32 v[142:143], v[142:143], 1.0 op_sel_hi:[1,0]
	s_nop 0
	v_rcp_f32_e32 v138, v143
	s_nop 0
	v_mul_f32_e32 v136, v141, v138
	v_rcp_f32_e32 v141, v142
	s_mov_b64 s[26:27], -1
	v_mul_f32_e32 v138, v140, v141
	s_and_b64 vcc, exec, s[0:1]
	s_cbranch_vccnz .LBB0_1187
	s_and_b64 s[26:27], s[24:25], exec
	v_readlane_b32 s26, v252, 45
	v_readlane_b32 s28, v252, 47
	v_readlane_b32 s27, v252, 46
	v_readlane_b32 s29, v252, 48
	v_lshlrev_b64 v[140:141], 11, v[174:175]
	s_cselect_b32 s27, s27, s29
	s_cselect_b32 s26, s26, s28
	v_readlane_b32 s36, v252, 26
	s_movk_i32 s28, 0xf000
	v_readlane_b32 s37, v252, 27
	v_lshl_add_u64 v[140:141], s[26:27], 0, v[140:141]
	s_mov_b32 s29, s37
	s_cselect_b32 s28, s28, 0xffffe800
	v_lshl_add_u64 v[140:141], v[128:129], 1, v[140:141]
	v_lshl_add_u64 v[140:141], v[140:141], 0, s[28:29]
	v_cvt_pk_bf16_f32 v142, v133, s0
	global_store_short v[140:141], v142, off
	v_cvt_pk_bf16_f32 v142, v131, s0
	s_mov_b32 s27, s37
	global_store_short v[140:141], v142, off offset:2048
	v_add_co_u32_e32 v140, vcc, 0x1000, v140
	v_writelane_b32 v252, s26, 26
	v_cvt_pk_bf16_f32 v142, v138, s0
	v_addc_co_u32_e32 v141, vcc, 0, v141, vcc
	v_writelane_b32 v252, s27, 27
	global_store_short v[140:141], v142, off
	v_cvt_pk_bf16_f32 v142, v136, s0
	s_mov_b64 s[26:27], 0
	global_store_short v[140:141], v142, off offset:2048

.LBB0_1189:
	ds_bpermute_b32 v131, v244, v87
	v_mov_b32_e32 v142, v85
	v_mov_b32_e32 v143, v86
	s_waitcnt lgkmcnt(0)
	v_cndmask_b32_e64 v136, v131, v137, s[4:5]
	v_mov_b32_e32 v137, v84
	v_pk_fma_f32 v[136:137], v[188:189], v[136:137], v[190:191]
	v_pk_fma_f32 v[136:137], v[84:85], v[134:135], v[136:137]
	ds_bpermute_b32 v138, v244, v88
	v_pk_fma_f32 v[136:137], v[142:143], v[186:187], v[136:137]
	v_pk_fma_f32 v[142:143], v[142:143], v[188:189], v[190:191]
	v_mul_f32_e32 v133, 0xbfb8aa3b, v136
	v_exp_f32_e32 v144, v133
	v_mul_f32_e32 v133, 0xbfb8aa3b, v137
	v_exp_f32_e32 v145, v133
	s_waitcnt lgkmcnt(0)
	v_cndmask_b32_e64 v141, v138, v139, s[4:5]
	v_pk_fma_f32 v[142:143], v[86:87], v[134:135], v[142:143]
	v_or_b32_e32 v172, v239, v208
	v_pk_add_f32 v[144:145], v[144:145], 1.0 op_sel_hi:[1,0]
	v_ashrrev_i32_e32 v173, 31, v172
	v_rcp_f32_e32 v139, v145
	s_nop 0
	v_mul_f32_e32 v133, v137, v139
	v_rcp_f32_e32 v139, v144
	s_nop 0
	v_mov_b32_e32 v140, v87
	v_mul_f32_e32 v137, v136, v139
	v_pk_fma_f32 v[140:141], v[140:141], v[186:187], v[142:143]
	v_mov_b32_e32 v136, v137
	v_mul_f32_e32 v137, 0xbfb8aa3b, v140
	v_exp_f32_e32 v142, v137
	v_mul_f32_e32 v137, 0xbfb8aa3b, v141
	v_exp_f32_e32 v143, v137
	s_nop 0
	v_pk_add_f32 v[142:143], v[142:143], 1.0 op_sel_hi:[1,0]
	s_nop 0
	v_rcp_f32_e32 v139, v143
	s_nop 0
	v_mul_f32_e32 v137, v141, v139
	v_rcp_f32_e32 v141, v142
	s_mov_b64 s[26:27], -1
	v_mul_f32_e32 v139, v140, v141
	s_and_b64 vcc, exec, s[0:1]
	s_cbranch_vccnz .LBB0_1191
	s_and_b64 s[26:27], s[24:25], exec
	v_readlane_b32 s26, v252, 45
	v_readlane_b32 s28, v252, 47
	v_readlane_b32 s27, v252, 46
	v_readlane_b32 s29, v252, 48
	v_lshlrev_b64 v[140:141], 11, v[172:173]
	s_cselect_b32 s27, s27, s29
	s_cselect_b32 s26, s26, s28
	v_readlane_b32 s36, v252, 26
	s_movk_i32 s28, 0xf000
	v_readlane_b32 s37, v252, 27
	v_lshl_add_u64 v[140:141], s[26:27], 0, v[140:141]
	s_mov_b32 s29, s37
	s_cselect_b32 s28, s28, 0xffffe800
	v_lshl_add_u64 v[140:141], v[128:129], 1, v[140:141]
	v_lshl_add_u64 v[140:141], v[140:141], 0, s[28:29]
	v_cvt_pk_bf16_f32 v142, v136, s0
	global_store_short v[140:141], v142, off
	v_cvt_pk_bf16_f32 v142, v133, s0
	s_mov_b32 s27, s37
	global_store_short v[140:141], v142, off offset:2048
	v_add_co_u32_e32 v140, vcc, 0x1000, v140
	v_writelane_b32 v252, s26, 26
	v_cvt_pk_bf16_f32 v142, v139, s0
	v_addc_co_u32_e32 v141, vcc, 0, v141, vcc
	v_writelane_b32 v252, s27, 27
	global_store_short v[140:141], v142, off
	v_cvt_pk_bf16_f32 v142, v137, s0
	s_mov_b64 s[26:27], 0
	global_store_short v[140:141], v142, off offset:2048

.LBB0_1193:
	v_mov_b32_e32 v141, v88
	ds_bpermute_b32 v136, v244, v91
	v_mov_b32_e32 v142, v89
	v_mov_b32_e32 v143, v90
	s_waitcnt lgkmcnt(0)
	v_cndmask_b32_e64 v140, v136, v131, s[4:5]
	v_pk_fma_f32 v[140:141], v[188:189], v[140:141], v[190:191]
	v_pk_fma_f32 v[140:141], v[88:89], v[134:135], v[140:141]
	v_pk_fma_f32 v[140:141], v[142:143], v[186:187], v[140:141]
	ds_bpermute_b32 v137, v244, v92
	v_mul_f32_e32 v131, 0xbfb8aa3b, v140
	v_exp_f32_e32 v144, v131
	v_mul_f32_e32 v131, 0xbfb8aa3b, v141
	v_exp_f32_e32 v145, v131
	s_waitcnt lgkmcnt(0)
	v_cndmask_b32_e64 v139, v137, v138, s[4:5]
	v_or_b32_e32 v152, v239, v209
	v_ashrrev_i32_e32 v153, 31, v152
	v_pk_add_f32 v[144:145], v[144:145], 1.0 op_sel_hi:[1,0]
	s_nop 0
	v_rcp_f32_e32 v133, v145
	s_nop 0
	v_mul_f32_e32 v131, v141, v133
	v_rcp_f32_e32 v138, v144
	s_nop 0
	v_mul_f32_e32 v133, v140, v138
	v_pk_fma_f32 v[140:141], v[142:143], v[188:189], v[190:191]
	v_mov_b32_e32 v138, v91
	v_pk_fma_f32 v[140:141], v[90:91], v[134:135], v[140:141]
	s_nop 0
	v_pk_fma_f32 v[140:141], v[138:139], v[186:187], v[140:141]
	s_nop 0
	v_mul_f32_e32 v138, 0xbfb8aa3b, v140
	v_mul_f32_e32 v139, 0xbfb8aa3b, v141
	v_exp_f32_e32 v138, v138
	v_exp_f32_e32 v139, v139
	s_nop 0
	v_pk_add_f32 v[142:143], v[138:139], 1.0 op_sel_hi:[1,0]
	s_nop 0
	v_rcp_f32_e32 v139, v143
	s_nop 0
	v_mul_f32_e32 v138, v141, v139
	v_rcp_f32_e32 v141, v142
	s_mov_b64 s[26:27], -1
	v_mul_f32_e32 v139, v140, v141
	s_and_b64 vcc, exec, s[0:1]
	s_cbranch_vccnz .LBB0_1195
	s_and_b64 s[26:27], s[24:25], exec
	v_readlane_b32 s26, v252, 45
	v_readlane_b32 s28, v252, 47
	v_readlane_b32 s27, v252, 46
	v_readlane_b32 s29, v252, 48
	v_lshlrev_b64 v[140:141], 11, v[152:153]
	s_cselect_b32 s27, s27, s29
	s_cselect_b32 s26, s26, s28
	v_readlane_b32 s36, v252, 26
	s_movk_i32 s28, 0xf000
	v_readlane_b32 s37, v252, 27
	v_lshl_add_u64 v[140:141], s[26:27], 0, v[140:141]
	s_mov_b32 s29, s37
	s_cselect_b32 s28, s28, 0xffffe800
	v_lshl_add_u64 v[140:141], v[128:129], 1, v[140:141]
	v_lshl_add_u64 v[140:141], v[140:141], 0, s[28:29]
	v_cvt_pk_bf16_f32 v142, v133, s0
	global_store_short v[140:141], v142, off
	v_cvt_pk_bf16_f32 v142, v131, s0
	s_mov_b32 s27, s37
	global_store_short v[140:141], v142, off offset:2048
	v_add_co_u32_e32 v140, vcc, 0x1000, v140
	v_writelane_b32 v252, s26, 26
	v_cvt_pk_bf16_f32 v142, v139, s0
	v_addc_co_u32_e32 v141, vcc, 0, v141, vcc
	v_writelane_b32 v252, s27, 27
	global_store_short v[140:141], v142, off
	v_cvt_pk_bf16_f32 v142, v138, s0
	s_mov_b64 s[26:27], 0
	global_store_short v[140:141], v142, off offset:2048

.LBB0_1197:
	v_mov_b32_e32 v142, v93
	ds_bpermute_b32 v131, v244, v95
	ds_bpermute_b32 v138, v244, v48
	v_mov_b32_e32 v143, v94
	v_or_b32_e32 v150, v239, v210
	v_ashrrev_i32_e32 v151, 31, v150
	s_waitcnt lgkmcnt(1)
	v_cndmask_b32_e64 v136, v131, v136, s[4:5]
	s_waitcnt lgkmcnt(0)
	v_cndmask_b32_e64 v141, v138, v137, s[4:5]
	v_mov_b32_e32 v137, v92
	v_pk_fma_f32 v[136:137], v[188:189], v[136:137], v[190:191]
	s_nop 0
	v_pk_fma_f32 v[136:137], v[92:93], v[134:135], v[136:137]
	s_nop 0
	v_pk_fma_f32 v[136:137], v[142:143], v[186:187], v[136:137]
	v_pk_fma_f32 v[142:143], v[142:143], v[188:189], v[190:191]
	v_mul_f32_e32 v133, 0xbfb8aa3b, v136
	v_exp_f32_e32 v144, v133
	v_mul_f32_e32 v133, 0xbfb8aa3b, v137
	v_exp_f32_e32 v145, v133
	v_pk_fma_f32 v[142:143], v[94:95], v[134:135], v[142:143]
	v_pk_add_f32 v[144:145], v[144:145], 1.0 op_sel_hi:[1,0]
	s_nop 0
	v_rcp_f32_e32 v139, v145
	s_nop 0
	v_mul_f32_e32 v133, v137, v139
	v_rcp_f32_e32 v139, v144
	s_nop 0
	v_mov_b32_e32 v140, v95
	v_mul_f32_e32 v137, v136, v139
	v_pk_fma_f32 v[140:141], v[140:141], v[186:187], v[142:143]
	v_mov_b32_e32 v136, v137
	v_mul_f32_e32 v137, 0xbfb8aa3b, v140
	v_exp_f32_e32 v142, v137
	v_mul_f32_e32 v137, 0xbfb8aa3b, v141
	v_exp_f32_e32 v143, v137
	s_nop 0
	v_pk_add_f32 v[142:143], v[142:143], 1.0 op_sel_hi:[1,0]
	s_nop 0
	v_rcp_f32_e32 v139, v143
	s_nop 0
	v_mul_f32_e32 v137, v141, v139
	v_rcp_f32_e32 v141, v142
	s_mov_b64 s[26:27], -1
	v_mul_f32_e32 v139, v140, v141
	s_and_b64 vcc, exec, s[0:1]
	s_cbranch_vccnz .LBB0_1199
	s_and_b64 s[26:27], s[24:25], exec
	v_readlane_b32 s26, v252, 45
	v_readlane_b32 s28, v252, 47
	v_readlane_b32 s27, v252, 46
	v_readlane_b32 s29, v252, 48
	v_lshlrev_b64 v[140:141], 11, v[150:151]
	s_cselect_b32 s27, s27, s29
	s_cselect_b32 s26, s26, s28
	v_readlane_b32 s36, v252, 26
	s_movk_i32 s28, 0xf000
	v_readlane_b32 s37, v252, 27
	v_lshl_add_u64 v[140:141], s[26:27], 0, v[140:141]
	s_mov_b32 s29, s37
	s_cselect_b32 s28, s28, 0xffffe800
	v_lshl_add_u64 v[140:141], v[128:129], 1, v[140:141]
	v_lshl_add_u64 v[140:141], v[140:141], 0, s[28:29]
	v_cvt_pk_bf16_f32 v142, v136, s0
	global_store_short v[140:141], v142, off
	v_cvt_pk_bf16_f32 v142, v133, s0
	s_mov_b32 s27, s37
	global_store_short v[140:141], v142, off offset:2048
	v_add_co_u32_e32 v140, vcc, 0x1000, v140
	v_writelane_b32 v252, s26, 26
	v_cvt_pk_bf16_f32 v142, v139, s0
	v_addc_co_u32_e32 v141, vcc, 0, v141, vcc
	v_writelane_b32 v252, s27, 27
	global_store_short v[140:141], v142, off
	v_cvt_pk_bf16_f32 v142, v137, s0
	s_mov_b64 s[26:27], 0
	global_store_short v[140:141], v142, off offset:2048

.LBB0_1201:
	v_mov_b32_e32 v141, v48
	ds_bpermute_b32 v136, v244, v51
	v_mov_b32_e32 v144, v49
	v_mov_b32_e32 v145, v50
	s_waitcnt lgkmcnt(0)
	v_cndmask_b32_e64 v140, v136, v131, s[4:5]
	v_pk_fma_f32 v[140:141], v[188:189], v[140:141], v[190:191]
	v_pk_fma_f32 v[140:141], v[48:49], v[134:135], v[140:141]
	v_pk_fma_f32 v[140:141], v[144:145], v[186:187], v[140:141]
	ds_bpermute_b32 v139, v244, v52
	v_mul_f32_e32 v131, 0xbfb8aa3b, v140
	v_exp_f32_e32 v146, v131
	v_mul_f32_e32 v131, 0xbfb8aa3b, v141
	v_exp_f32_e32 v147, v131
	s_waitcnt lgkmcnt(0)
	v_cndmask_b32_e64 v143, v139, v138, s[4:5]
	v_or_b32_e32 v148, v239, v211
	v_ashrrev_i32_e32 v149, 31, v148
	v_pk_add_f32 v[146:147], v[146:147], 1.0 op_sel_hi:[1,0]
	s_nop 0
	v_rcp_f32_e32 v133, v147
	s_nop 0
	v_mul_f32_e32 v131, v141, v133
	v_rcp_f32_e32 v137, v146
	s_nop 0
	v_mul_f32_e32 v133, v140, v137
	v_pk_fma_f32 v[140:141], v[144:145], v[188:189], v[190:191]
	v_mov_b32_e32 v142, v51
	v_pk_fma_f32 v[140:141], v[50:51], v[134:135], v[140:141]
	s_nop 0
	v_pk_fma_f32 v[140:141], v[142:143], v[186:187], v[140:141]
	s_nop 0
	v_mul_f32_e32 v137, 0xbfb8aa3b, v140
	v_exp_f32_e32 v142, v137
	v_mul_f32_e32 v137, 0xbfb8aa3b, v141
	v_exp_f32_e32 v143, v137
	s_nop 0
	v_pk_add_f32 v[142:143], v[142:143], 1.0 op_sel_hi:[1,0]
	s_nop 0
	v_rcp_f32_e32 v138, v143
	s_nop 0
	v_mul_f32_e32 v137, v141, v138
	v_rcp_f32_e32 v141, v142
	s_mov_b64 s[26:27], -1
	v_mul_f32_e32 v138, v140, v141
	s_and_b64 vcc, exec, s[0:1]
	s_cbranch_vccnz .LBB0_1203
	s_and_b64 s[26:27], s[24:25], exec
	v_readlane_b32 s26, v252, 45
	v_readlane_b32 s28, v252, 47
	v_readlane_b32 s27, v252, 46
	v_readlane_b32 s29, v252, 48
	v_lshlrev_b64 v[140:141], 11, v[148:149]
	s_cselect_b32 s27, s27, s29
	s_cselect_b32 s26, s26, s28
	v_readlane_b32 s36, v252, 26
	s_movk_i32 s28, 0xf000
	v_readlane_b32 s37, v252, 27
	v_lshl_add_u64 v[140:141], s[26:27], 0, v[140:141]
	s_mov_b32 s29, s37
	s_cselect_b32 s28, s28, 0xffffe800
	v_lshl_add_u64 v[140:141], v[128:129], 1, v[140:141]
	v_lshl_add_u64 v[140:141], v[140:141], 0, s[28:29]
	v_cvt_pk_bf16_f32 v142, v133, s0
	global_store_short v[140:141], v142, off
	v_cvt_pk_bf16_f32 v142, v131, s0
	s_mov_b32 s27, s37
	global_store_short v[140:141], v142, off offset:2048
	v_add_co_u32_e32 v140, vcc, 0x1000, v140
	v_writelane_b32 v252, s26, 26
	v_cvt_pk_bf16_f32 v142, v138, s0
	v_addc_co_u32_e32 v141, vcc, 0, v141, vcc
	v_writelane_b32 v252, s27, 27
	global_store_short v[140:141], v142, off
	v_cvt_pk_bf16_f32 v142, v137, s0
	s_mov_b64 s[26:27], 0
	global_store_short v[140:141], v142, off offset:2048

.LBB0_1205:
	v_mov_b32_e32 v142, v53
	ds_bpermute_b32 v131, v244, v55
	ds_bpermute_b32 v137, v244, v56
	v_mov_b32_e32 v143, v54
	s_waitcnt lgkmcnt(1)
	v_cndmask_b32_e64 v138, v131, v136, s[4:5]
	s_waitcnt lgkmcnt(0)
	v_cndmask_b32_e64 v141, v137, v139, s[4:5]
	v_mov_b32_e32 v139, v52
	v_pk_fma_f32 v[138:139], v[188:189], v[138:139], v[190:191]
	s_nop 0
	v_pk_fma_f32 v[138:139], v[52:53], v[134:135], v[138:139]
	s_nop 0
	v_pk_fma_f32 v[138:139], v[142:143], v[186:187], v[138:139]
	s_nop 0
	v_mul_f32_e32 v133, 0xbfb8aa3b, v138
	v_exp_f32_e32 v144, v133
	v_mul_f32_e32 v133, 0xbfb8aa3b, v139
	v_exp_f32_e32 v145, v133
	s_nop 0
	v_pk_add_f32 v[144:145], v[144:145], 1.0 op_sel_hi:[1,0]
	s_nop 0
	v_rcp_f32_e32 v136, v145
	s_nop 0
	v_mul_f32_e32 v133, v139, v136
	v_rcp_f32_e32 v139, v144
	s_nop 0
	v_mul_f32_e32 v136, v138, v139
	v_pk_fma_f32 v[138:139], v[142:143], v[188:189], v[190:191]
	v_mov_b32_e32 v140, v55
	v_pk_fma_f32 v[138:139], v[54:55], v[134:135], v[138:139]
	s_nop 0
	v_pk_fma_f32 v[140:141], v[140:141], v[186:187], v[138:139]
	s_nop 0
	v_mul_f32_e32 v138, 0xbfb8aa3b, v140
	v_mul_f32_e32 v139, 0xbfb8aa3b, v141
	v_exp_f32_e32 v138, v138
	v_exp_f32_e32 v139, v139
	s_nop 0
	v_pk_add_f32 v[142:143], v[138:139], 1.0 op_sel_hi:[1,0]
	s_nop 0
	v_rcp_f32_e32 v139, v143
	s_nop 0
	v_mul_f32_e32 v138, v141, v139
	v_rcp_f32_e32 v141, v142
	v_or_b32_e32 v146, v239, v212
	s_mov_b64 s[26:27], -1
	v_ashrrev_i32_e32 v147, 31, v146
	v_mul_f32_e32 v139, v140, v141
	s_and_b64 vcc, exec, s[0:1]
	s_cbranch_vccnz .LBB0_1207
	s_and_b64 s[26:27], s[24:25], exec
	v_readlane_b32 s26, v252, 45
	v_readlane_b32 s28, v252, 47
	v_readlane_b32 s27, v252, 46
	v_readlane_b32 s29, v252, 48
	v_lshlrev_b64 v[140:141], 11, v[146:147]
	s_cselect_b32 s27, s27, s29
	s_cselect_b32 s26, s26, s28
	v_readlane_b32 s36, v252, 26
	s_movk_i32 s28, 0xf000
	v_readlane_b32 s37, v252, 27
	v_lshl_add_u64 v[140:141], s[26:27], 0, v[140:141]
	s_mov_b32 s29, s37
	s_cselect_b32 s28, s28, 0xffffe800
	v_lshl_add_u64 v[140:141], v[128:129], 1, v[140:141]
	v_lshl_add_u64 v[140:141], v[140:141], 0, s[28:29]
	v_cvt_pk_bf16_f32 v142, v136, s0
	global_store_short v[140:141], v142, off
	v_cvt_pk_bf16_f32 v142, v133, s0
	s_mov_b32 s27, s37
	global_store_short v[140:141], v142, off offset:2048
	v_add_co_u32_e32 v140, vcc, 0x1000, v140
	v_writelane_b32 v252, s26, 26
	v_cvt_pk_bf16_f32 v142, v139, s0
	v_addc_co_u32_e32 v141, vcc, 0, v141, vcc
	v_writelane_b32 v252, s27, 27
	global_store_short v[140:141], v142, off
	v_cvt_pk_bf16_f32 v142, v138, s0
	s_mov_b64 s[26:27], 0
	global_store_short v[140:141], v142, off offset:2048

.LBB0_1209:
	v_mov_b32_e32 v141, v56
	ds_bpermute_b32 v136, v244, v59
	v_mov_b32_e32 v144, v57
	v_mov_b32_e32 v145, v58
	s_waitcnt lgkmcnt(0)
	v_cndmask_b32_e64 v140, v136, v131, s[4:5]
	v_pk_fma_f32 v[140:141], v[188:189], v[140:141], v[190:191]
	v_pk_fma_f32 v[140:141], v[56:57], v[134:135], v[140:141]
	v_pk_fma_f32 v[140:141], v[144:145], v[186:187], v[140:141]
	ds_bpermute_b32 v138, v244, v60
	v_mul_f32_e32 v131, 0xbfb8aa3b, v140
	v_exp_f32_e32 v194, v131
	v_mul_f32_e32 v131, 0xbfb8aa3b, v141
	v_exp_f32_e32 v195, v131
	s_waitcnt lgkmcnt(0)
	v_cndmask_b32_e64 v143, v138, v137, s[4:5]
	v_pk_add_f32 v[194:195], v[194:195], 1.0 op_sel_hi:[1,0]
	s_nop 0
	v_rcp_f32_e32 v133, v195
	s_nop 0
	v_mul_f32_e32 v131, v141, v133
	v_rcp_f32_e32 v137, v194
	s_nop 0
	v_mul_f32_e32 v133, v140, v137
	v_pk_fma_f32 v[140:141], v[144:145], v[188:189], v[190:191]
	v_mov_b32_e32 v142, v59
	v_pk_fma_f32 v[140:141], v[58:59], v[134:135], v[140:141]
	s_nop 0
	v_pk_fma_f32 v[140:141], v[142:143], v[186:187], v[140:141]
	s_nop 0
	v_mul_f32_e32 v137, 0xbfb8aa3b, v140
	v_exp_f32_e32 v142, v137
	v_mul_f32_e32 v137, 0xbfb8aa3b, v141
	v_exp_f32_e32 v143, v137
	s_nop 0
	v_pk_add_f32 v[142:143], v[142:143], 1.0 op_sel_hi:[1,0]
	s_nop 0
	v_rcp_f32_e32 v139, v143
	s_nop 0
	v_mul_f32_e32 v137, v141, v139
	v_rcp_f32_e32 v141, v142
	s_mov_b64 s[26:27], -1
	v_mul_f32_e32 v139, v140, v141
	v_or_b32_e32 v144, v239, v213
	s_and_b64 vcc, exec, s[0:1]
	v_ashrrev_i32_e32 v145, 31, v144
	s_cbranch_vccnz .LBB0_1211
	s_and_b64 s[26:27], s[24:25], exec
	v_readlane_b32 s26, v252, 45
	v_readlane_b32 s28, v252, 47
	v_readlane_b32 s27, v252, 46
	v_readlane_b32 s29, v252, 48
	v_lshlrev_b64 v[140:141], 11, v[144:145]
	s_cselect_b32 s27, s27, s29
	s_cselect_b32 s26, s26, s28
	v_readlane_b32 s36, v252, 26
	s_movk_i32 s28, 0xf000
	v_readlane_b32 s37, v252, 27
	v_lshl_add_u64 v[140:141], s[26:27], 0, v[140:141]
	s_mov_b32 s29, s37
	s_cselect_b32 s28, s28, 0xffffe800
	v_lshl_add_u64 v[140:141], v[128:129], 1, v[140:141]
	v_lshl_add_u64 v[140:141], v[140:141], 0, s[28:29]
	v_cvt_pk_bf16_f32 v142, v133, s0
	global_store_short v[140:141], v142, off
	v_cvt_pk_bf16_f32 v142, v131, s0
	s_mov_b32 s27, s37
	global_store_short v[140:141], v142, off offset:2048
	v_add_co_u32_e32 v140, vcc, 0x1000, v140
	v_writelane_b32 v252, s26, 26
	v_cvt_pk_bf16_f32 v142, v139, s0
	v_addc_co_u32_e32 v141, vcc, 0, v141, vcc
	v_writelane_b32 v252, s27, 27
	global_store_short v[140:141], v142, off
	v_cvt_pk_bf16_f32 v142, v137, s0
	s_mov_b64 s[26:27], 0
	global_store_short v[140:141], v142, off offset:2048

.LBB0_1213:
	ds_bpermute_b32 v131, v244, v63
	v_mov_b32_e32 v141, v60
	v_mov_b32_e32 v142, v61
	s_waitcnt lgkmcnt(0)
	v_cndmask_b32_e64 v140, v131, v136, s[4:5]
	v_pk_fma_f32 v[140:141], v[188:189], v[140:141], v[190:191]
	v_mov_b32_e32 v143, v62
	v_pk_fma_f32 v[140:141], v[60:61], v[134:135], v[140:141]
	v_pk_fma_f32 v[140:141], v[142:143], v[186:187], v[140:141]
	ds_bpermute_b32 v137, v244, v16
	v_mul_f32_e32 v133, 0xbfb8aa3b, v140
	v_exp_f32_e32 v194, v133
	v_mul_f32_e32 v133, 0xbfb8aa3b, v141
	v_exp_f32_e32 v195, v133
	s_waitcnt lgkmcnt(0)
	v_cndmask_b32_e64 v139, v137, v138, s[4:5]
	v_pk_add_f32 v[194:195], v[194:195], 1.0 op_sel_hi:[1,0]
	s_nop 0
	v_rcp_f32_e32 v136, v195
	s_nop 0
	v_mul_f32_e32 v133, v141, v136
	v_rcp_f32_e32 v138, v194
	s_nop 0
	v_mul_f32_e32 v136, v140, v138
	v_pk_fma_f32 v[140:141], v[142:143], v[188:189], v[190:191]
	v_mov_b32_e32 v138, v63
	v_pk_fma_f32 v[140:141], v[62:63], v[134:135], v[140:141]
	s_nop 0
	v_pk_fma_f32 v[140:141], v[138:139], v[186:187], v[140:141]
	s_nop 0
	v_mul_f32_e32 v138, 0xbfb8aa3b, v140
	v_mul_f32_e32 v139, 0xbfb8aa3b, v141
	v_exp_f32_e32 v138, v138
	v_exp_f32_e32 v139, v139
	s_nop 0
	v_pk_add_f32 v[142:143], v[138:139], 1.0 op_sel_hi:[1,0]
	s_nop 0
	v_rcp_f32_e32 v139, v143
	s_nop 0
	v_mul_f32_e32 v138, v141, v139
	v_rcp_f32_e32 v141, v142
	s_mov_b64 s[26:27], -1
	v_mul_f32_e32 v139, v140, v141
	v_or_b32_e32 v142, v239, v214
	s_and_b64 vcc, exec, s[0:1]
	v_ashrrev_i32_e32 v143, 31, v142
	s_cbranch_vccnz .LBB0_1215
	s_and_b64 s[26:27], s[24:25], exec
	v_readlane_b32 s26, v252, 45
	v_readlane_b32 s28, v252, 47
	v_readlane_b32 s27, v252, 46
	v_readlane_b32 s29, v252, 48
	v_lshlrev_b64 v[140:141], 11, v[142:143]
	s_cselect_b32 s27, s27, s29
	s_cselect_b32 s26, s26, s28
	v_readlane_b32 s36, v252, 26
	s_movk_i32 s28, 0xf000
	v_readlane_b32 s37, v252, 27
	v_lshl_add_u64 v[140:141], s[26:27], 0, v[140:141]
	s_mov_b32 s29, s37
	s_cselect_b32 s28, s28, 0xffffe800
	v_lshl_add_u64 v[140:141], v[128:129], 1, v[140:141]
	v_lshl_add_u64 v[140:141], v[140:141], 0, s[28:29]
	v_cvt_pk_bf16_f32 v194, v136, s0
	global_store_short v[140:141], v194, off
	v_cvt_pk_bf16_f32 v194, v133, s0
	s_mov_b32 s27, s37
	global_store_short v[140:141], v194, off offset:2048
	v_add_co_u32_e32 v140, vcc, 0x1000, v140
	v_writelane_b32 v252, s26, 26
	v_cvt_pk_bf16_f32 v194, v139, s0
	v_addc_co_u32_e32 v141, vcc, 0, v141, vcc
	v_writelane_b32 v252, s27, 27
	global_store_short v[140:141], v194, off
	v_cvt_pk_bf16_f32 v194, v138, s0
	s_mov_b64 s[26:27], 0
	global_store_short v[140:141], v194, off offset:2048

.LBB0_1217:
	v_mov_b32_e32 v141, v16
	ds_bpermute_b32 v136, v244, v19
	v_mov_b32_e32 v224, v17
	v_mov_b32_e32 v225, v18
	s_waitcnt lgkmcnt(0)
	v_cndmask_b32_e64 v140, v136, v131, s[4:5]
	v_pk_fma_f32 v[140:141], v[188:189], v[140:141], v[190:191]
	v_pk_fma_f32 v[140:141], v[16:17], v[134:135], v[140:141]
	v_pk_fma_f32 v[140:141], v[224:225], v[186:187], v[140:141]
	ds_bpermute_b32 v138, v244, v20
	v_mul_f32_e32 v131, 0xbfb8aa3b, v140
	v_exp_f32_e32 v226, v131
	v_mul_f32_e32 v131, 0xbfb8aa3b, v141
	v_exp_f32_e32 v227, v131
	s_waitcnt lgkmcnt(0)
	v_cndmask_b32_e64 v195, v138, v137, s[4:5]
	v_pk_add_f32 v[226:227], v[226:227], 1.0 op_sel_hi:[1,0]
	s_nop 0
	v_rcp_f32_e32 v133, v227
	s_nop 0
	v_mul_f32_e32 v131, v141, v133
	v_rcp_f32_e32 v137, v226
	s_nop 0
	v_mul_f32_e32 v133, v140, v137
	v_pk_fma_f32 v[140:141], v[224:225], v[188:189], v[190:191]
	v_mov_b32_e32 v194, v19
	v_pk_fma_f32 v[140:141], v[18:19], v[134:135], v[140:141]
	s_nop 0
	v_pk_fma_f32 v[140:141], v[194:195], v[186:187], v[140:141]
	s_nop 0
	v_mul_f32_e32 v137, 0xbfb8aa3b, v140
	v_exp_f32_e32 v194, v137
	v_mul_f32_e32 v137, 0xbfb8aa3b, v141
	v_exp_f32_e32 v195, v137
	s_nop 0
	v_pk_add_f32 v[194:195], v[194:195], 1.0 op_sel_hi:[1,0]
	s_nop 0
	v_rcp_f32_e32 v139, v195
	s_nop 0
	v_mul_f32_e32 v137, v141, v139
	v_rcp_f32_e32 v141, v194
	s_mov_b64 s[26:27], -1
	v_mul_f32_e32 v139, v140, v141
	v_or_b32_e32 v140, v239, v215
	s_and_b64 vcc, exec, s[0:1]
	v_ashrrev_i32_e32 v141, 31, v140
	s_cbranch_vccnz .LBB0_1219
	s_and_b64 s[26:27], s[24:25], exec
	v_readlane_b32 s26, v252, 45
	v_readlane_b32 s28, v252, 47
	v_readlane_b32 s27, v252, 46
	v_readlane_b32 s29, v252, 48
	v_lshlrev_b64 v[194:195], 11, v[140:141]
	s_cselect_b32 s27, s27, s29
	s_cselect_b32 s26, s26, s28
	v_readlane_b32 s36, v252, 26
	s_movk_i32 s28, 0xf000
	v_readlane_b32 s37, v252, 27
	v_lshl_add_u64 v[194:195], s[26:27], 0, v[194:195]
	s_mov_b32 s29, s37
	s_cselect_b32 s28, s28, 0xffffe800
	v_lshl_add_u64 v[194:195], v[128:129], 1, v[194:195]
	v_lshl_add_u64 v[194:195], v[194:195], 0, s[28:29]
	v_cvt_pk_bf16_f32 v222, v133, s0
	global_store_short v[194:195], v222, off
	v_cvt_pk_bf16_f32 v222, v131, s0
	s_mov_b32 s27, s37
	global_store_short v[194:195], v222, off offset:2048
	v_add_co_u32_e32 v194, vcc, 0x1000, v194
	v_writelane_b32 v252, s26, 26
	v_cvt_pk_bf16_f32 v222, v139, s0
	v_addc_co_u32_e32 v195, vcc, 0, v195, vcc
	v_writelane_b32 v252, s27, 27
	global_store_short v[194:195], v222, off
	v_cvt_pk_bf16_f32 v222, v137, s0
	s_mov_b64 s[26:27], 0
	global_store_short v[194:195], v222, off offset:2048

.LBB0_1221:
	ds_bpermute_b32 v131, v244, v23
	v_mov_b32_e32 v195, v20
	v_mov_b32_e32 v224, v21
	s_waitcnt lgkmcnt(0)
	v_cndmask_b32_e64 v194, v131, v136, s[4:5]
	v_pk_fma_f32 v[194:195], v[188:189], v[194:195], v[190:191]
	v_mov_b32_e32 v225, v22
	v_pk_fma_f32 v[194:195], v[20:21], v[134:135], v[194:195]
	v_pk_fma_f32 v[194:195], v[224:225], v[186:187], v[194:195]
	ds_bpermute_b32 v137, v244, v24
	v_mul_f32_e32 v133, 0xbfb8aa3b, v194
	v_exp_f32_e32 v226, v133
	v_mul_f32_e32 v133, 0xbfb8aa3b, v195
	v_exp_f32_e32 v227, v133
	s_waitcnt lgkmcnt(0)
	v_cndmask_b32_e64 v139, v137, v138, s[4:5]
	v_pk_add_f32 v[226:227], v[226:227], 1.0 op_sel_hi:[1,0]
	s_nop 0
	v_rcp_f32_e32 v136, v227
	s_nop 0
	v_mul_f32_e32 v133, v195, v136
	v_rcp_f32_e32 v138, v226
	s_nop 0
	v_mul_f32_e32 v136, v194, v138
	v_pk_fma_f32 v[194:195], v[224:225], v[188:189], v[190:191]
	v_mov_b32_e32 v138, v23
	v_pk_fma_f32 v[194:195], v[22:23], v[134:135], v[194:195]
	s_nop 0
	v_pk_fma_f32 v[138:139], v[138:139], v[186:187], v[194:195]
	s_nop 0
	v_mul_f32_e32 v194, 0xbfb8aa3b, v138
	v_mul_f32_e32 v195, 0xbfb8aa3b, v139
	v_exp_f32_e32 v194, v194
	v_exp_f32_e32 v195, v195
	s_nop 0
	v_pk_add_f32 v[224:225], v[194:195], 1.0 op_sel_hi:[1,0]
	s_nop 0
	v_rcp_f32_e32 v195, v225
	s_nop 0
	v_mul_f32_e32 v194, v139, v195
	v_rcp_f32_e32 v195, v224
	s_mov_b64 s[26:27], -1
	v_mul_f32_e32 v139, v138, v195
	v_mov_b32_e32 v195, v139
	v_or_b32_e32 v138, v239, v216
	s_and_b64 vcc, exec, s[0:1]
	v_ashrrev_i32_e32 v139, 31, v138
	s_cbranch_vccnz .LBB0_1223
	s_and_b64 s[26:27], s[24:25], exec
	v_readlane_b32 s26, v252, 45
	v_readlane_b32 s28, v252, 47
	v_readlane_b32 s27, v252, 46
	v_readlane_b32 s29, v252, 48
	v_lshlrev_b64 v[224:225], 11, v[138:139]
	s_cselect_b32 s27, s27, s29
	s_cselect_b32 s26, s26, s28
	v_readlane_b32 s36, v252, 26
	s_movk_i32 s28, 0xf000
	v_readlane_b32 s37, v252, 27
	v_lshl_add_u64 v[224:225], s[26:27], 0, v[224:225]
	s_mov_b32 s29, s37
	s_cselect_b32 s28, s28, 0xffffe800
	v_lshl_add_u64 v[224:225], v[128:129], 1, v[224:225]
	v_lshl_add_u64 v[224:225], v[224:225], 0, s[28:29]
	v_cvt_pk_bf16_f32 v222, v136, s0
	global_store_short v[224:225], v222, off
	v_cvt_pk_bf16_f32 v222, v133, s0
	s_mov_b32 s27, s37
	global_store_short v[224:225], v222, off offset:2048
	v_add_co_u32_e32 v224, vcc, 0x1000, v224
	v_writelane_b32 v252, s26, 26
	v_cvt_pk_bf16_f32 v222, v195, s0
	v_addc_co_u32_e32 v225, vcc, 0, v225, vcc
	v_writelane_b32 v252, s27, 27
	global_store_short v[224:225], v222, off
	v_cvt_pk_bf16_f32 v222, v194, s0
	s_mov_b64 s[26:27], 0
	global_store_short v[224:225], v222, off offset:2048

.LBB0_1225:
	v_mov_b32_e32 v226, v25
	ds_bpermute_b32 v194, v244, v27
	v_mov_b32_e32 v227, v26
	ds_bpermute_b32 v195, v244, v28
	s_waitcnt lgkmcnt(1)
	v_cndmask_b32_e64 v136, v194, v131, s[4:5]
	s_waitcnt lgkmcnt(0)
	v_cndmask_b32_e64 v225, v195, v137, s[4:5]
	v_mov_b32_e32 v137, v24
	v_pk_fma_f32 v[136:137], v[188:189], v[136:137], v[190:191]
	s_nop 0
	v_pk_fma_f32 v[136:137], v[24:25], v[134:135], v[136:137]
	s_nop 0
	v_pk_fma_f32 v[136:137], v[226:227], v[186:187], v[136:137]
	s_nop 0
	v_mul_f32_e32 v131, 0xbfb8aa3b, v136
	v_exp_f32_e32 v240, v131
	v_mul_f32_e32 v131, 0xbfb8aa3b, v137
	v_exp_f32_e32 v241, v131
	s_nop 0
	v_pk_add_f32 v[240:241], v[240:241], 1.0 op_sel_hi:[1,0]
	s_nop 0
	v_rcp_f32_e32 v133, v241
	s_nop 0
	v_mul_f32_e32 v131, v137, v133
	v_rcp_f32_e32 v137, v240
	s_nop 0
	v_mul_f32_e32 v133, v136, v137
	v_pk_fma_f32 v[136:137], v[226:227], v[188:189], v[190:191]
	v_mov_b32_e32 v224, v27
	v_pk_fma_f32 v[136:137], v[26:27], v[134:135], v[136:137]
	s_nop 0
	v_pk_fma_f32 v[136:137], v[224:225], v[186:187], v[136:137]
	s_nop 0
	v_mul_f32_e32 v222, 0xbfb8aa3b, v136
	v_exp_f32_e32 v224, v222
	v_mul_f32_e32 v222, 0xbfb8aa3b, v137
	v_exp_f32_e32 v225, v222
	s_nop 0
	v_pk_add_f32 v[224:225], v[224:225], 1.0 op_sel_hi:[1,0]
	s_nop 0
	v_rcp_f32_e32 v223, v225
	s_nop 0
	v_mul_f32_e32 v222, v137, v223
	v_mov_b32_e32 v240, v222
	v_rcp_f32_e32 v222, v224
	s_mov_b64 s[26:27], -1
	v_mul_f32_e32 v137, v136, v222
	v_mov_b32_e32 v241, v137
	v_or_b32_e32 v136, v239, v217
	s_and_b64 vcc, exec, s[0:1]
	v_ashrrev_i32_e32 v137, 31, v136
	s_cbranch_vccnz .LBB0_1227
	s_and_b64 s[26:27], s[24:25], exec
	v_readlane_b32 s26, v252, 45
	v_readlane_b32 s28, v252, 47
	v_readlane_b32 s27, v252, 46
	v_readlane_b32 s29, v252, 48
	v_lshlrev_b64 v[224:225], 11, v[136:137]
	s_cselect_b32 s27, s27, s29
	s_cselect_b32 s26, s26, s28
	v_readlane_b32 s36, v252, 26
	s_movk_i32 s28, 0xf000
	v_readlane_b32 s37, v252, 27
	v_lshl_add_u64 v[224:225], s[26:27], 0, v[224:225]
	s_mov_b32 s29, s37
	s_cselect_b32 s28, s28, 0xffffe800
	v_lshl_add_u64 v[224:225], v[128:129], 1, v[224:225]
	v_lshl_add_u64 v[224:225], v[224:225], 0, s[28:29]
	v_cvt_pk_bf16_f32 v222, v133, s0
	global_store_short v[224:225], v222, off
	v_cvt_pk_bf16_f32 v222, v131, s0
	s_mov_b32 s27, s37
	global_store_short v[224:225], v222, off offset:2048
	v_add_co_u32_e32 v224, vcc, 0x1000, v224
	v_writelane_b32 v252, s26, 26
	v_cvt_pk_bf16_f32 v222, v241, s0
	v_addc_co_u32_e32 v225, vcc, 0, v225, vcc
	v_writelane_b32 v252, s27, 27
	global_store_short v[224:225], v222, off
	v_cvt_pk_bf16_f32 v222, v240, s0
	s_mov_b64 s[26:27], 0
	global_store_short v[224:225], v222, off offset:2048

.LBB0_1229:
	v_cndmask_b32_e64 v225, 0, v195, s[4:5]
	ds_bpermute_b32 v131, v244, v31
	v_mov_b32_e32 v195, v28
	v_mov_b32_e32 v226, v29
	v_mov_b32_e32 v227, v30
	s_waitcnt lgkmcnt(0)
	v_cndmask_b32_e64 v194, v131, v194, s[4:5]
	v_pk_fma_f32 v[194:195], v[188:189], v[194:195], v[190:191]
	v_pk_fma_f32 v[188:189], v[226:227], v[188:189], v[190:191]
	v_pk_fma_f32 v[194:195], v[28:29], v[134:135], v[194:195]
	v_pk_fma_f32 v[134:135], v[30:31], v[134:135], v[188:189]
	v_pk_fma_f32 v[194:195], v[226:227], v[186:187], v[194:195]
	s_nop 0
	v_mul_f32_e32 v131, 0xbfb8aa3b, v194
	v_exp_f32_e32 v240, v131
	v_mul_f32_e32 v131, 0xbfb8aa3b, v195
	v_exp_f32_e32 v241, v131
	s_nop 0
	v_pk_add_f32 v[240:241], v[240:241], 1.0 op_sel_hi:[1,0]
	s_nop 0
	v_rcp_f32_e32 v133, v241
	s_nop 0
	v_mul_f32_e32 v131, v195, v133
	v_rcp_f32_e32 v195, v240
	s_nop 0
	v_mov_b32_e32 v224, v31
	v_pk_fma_f32 v[134:135], v[224:225], v[186:187], v[134:135]
	v_mul_f32_e32 v186, 0xbfb8aa3b, v134
	v_mul_f32_e32 v187, 0xbfb8aa3b, v135
	v_exp_f32_e32 v186, v186
	v_exp_f32_e32 v187, v187
	v_mul_f32_e32 v133, v194, v195
	v_pk_add_f32 v[188:189], v[186:187], 1.0 op_sel_hi:[1,0]
	s_nop 0
	v_rcp_f32_e32 v187, v189
	s_nop 0
	v_mul_f32_e32 v186, v135, v187
	v_rcp_f32_e32 v187, v188
	s_mov_b64 s[26:27], -1
	v_mul_f32_e32 v135, v134, v187
	v_mov_b32_e32 v187, v135
	v_or_b32_e32 v134, v239, v233
	s_and_b64 vcc, exec, s[0:1]
	v_ashrrev_i32_e32 v135, 31, v134
	s_cbranch_vccnz .LBB0_1231
	s_and_b64 s[26:27], s[24:25], exec
	v_readlane_b32 s26, v252, 45
	v_readlane_b32 s28, v252, 47
	v_readlane_b32 s27, v252, 46
	v_readlane_b32 s29, v252, 48
	v_lshlrev_b64 v[188:189], 11, v[134:135]
	s_cselect_b32 s27, s27, s29
	s_cselect_b32 s26, s26, s28
	v_readlane_b32 s36, v252, 26
	s_movk_i32 s28, 0xf000
	v_readlane_b32 s37, v252, 27
	v_lshl_add_u64 v[188:189], s[26:27], 0, v[188:189]
	s_mov_b32 s29, s37
	s_cselect_b32 s28, s28, 0xffffe800
	v_lshl_add_u64 v[188:189], v[128:129], 1, v[188:189]
	v_lshl_add_u64 v[188:189], v[188:189], 0, s[28:29]
	v_cvt_pk_bf16_f32 v128, v133, s0
	global_store_short v[188:189], v128, off
	v_cvt_pk_bf16_f32 v128, v131, s0
	s_mov_b32 s27, s37
	global_store_short v[188:189], v128, off offset:2048
	v_add_co_u32_e32 v188, vcc, 0x1000, v188
	v_writelane_b32 v252, s26, 26
	v_cvt_pk_bf16_f32 v128, v187, s0
	v_addc_co_u32_e32 v189, vcc, 0, v189, vcc
	v_writelane_b32 v252, s27, 27
	global_store_short v[188:189], v128, off
	v_cvt_pk_bf16_f32 v128, v186, s0
	s_mov_b64 s[26:27], 0
	global_store_short v[188:189], v128, off offset:2048

.LBB0_1237:
	s_or_b64 exec, exec, s[26:27]
	v_cvt_pk_bf16_f32 v131, v131, s0
	v_lshl_add_u64 v[178:179], v[178:179], 0, v[194:195]
	global_store_short v[178:179], v131, off
	ds_bpermute_b32 v133, v244, v96
	v_mov_b32_e32 v179, v96
	ds_bpermute_b32 v131, v244, v99
	ds_bpermute_b32 v194, v244, v100
	v_pk_mov_b32 v[224:225], v[98:99], v[98:99] op_sel:[1,0]
	v_mov_b32_e32 v226, v97
	s_waitcnt lgkmcnt(1)
	v_cndmask_b32_e64 v178, v131, 0, s[4:5]
	s_waitcnt vmcnt(1)
	v_pk_fma_f32 v[178:179], v[186:187], v[178:179], v[192:193] op_sel_hi:[0,1,0]
	s_waitcnt lgkmcnt(0)
	v_cndmask_b32_e64 v189, v194, v133, s[4:5]
	v_pk_fma_f32 v[178:179], v[188:189], v[96:97], v[178:179] op_sel_hi:[0,1,1]
	v_mov_b32_e32 v227, v225
	v_pk_fma_f32 v[178:179], v[190:191], v[226:227], v[178:179] op_sel_hi:[0,1,1]
	v_mul_f32_e32 v133, 0xbfb8aa3b, v178
	v_exp_f32_e32 v240, v133
	v_mul_f32_e32 v133, 0xbfb8aa3b, v179
	v_exp_f32_e32 v241, v133
	v_mov_b32_e32 v225, v189
	v_pk_add_f32 v[240:241], v[240:241], 1.0 op_sel_hi:[1,0]
	s_nop 0
	v_rcp_f32_e32 v187, v241
	s_nop 0
	v_mul_f32_e32 v133, v179, v187
	v_rcp_f32_e32 v187, v240
	s_nop 0
	v_mul_f32_e32 v179, v178, v187
	v_mov_b32_e32 v187, v179
	v_pk_fma_f32 v[178:179], v[186:187], v[226:227], v[192:193] op_sel_hi:[0,1,0]
	v_pk_fma_f32 v[178:179], v[98:99], v[188:189], v[178:179] op_sel_hi:[1,0,1]
	s_nop 0
	v_pk_fma_f32 v[178:179], v[224:225], v[190:191], v[178:179] op_sel_hi:[1,0,1]
	s_nop 0
	v_mul_f32_e32 v189, 0xbfb8aa3b, v178
	v_exp_f32_e32 v224, v189
	v_mul_f32_e32 v189, 0xbfb8aa3b, v179
	v_exp_f32_e32 v225, v189
	s_nop 0
	v_pk_add_f32 v[224:225], v[224:225], 1.0 op_sel_hi:[1,0]
	s_nop 0
	v_rcp_f32_e32 v191, v225
	s_nop 0
	v_mul_f32_e32 v189, v179, v191
	v_rcp_f32_e32 v191, v224
	s_mov_b64 s[26:27], -1
	v_mul_f32_e32 v179, v178, v191
	v_mov_b32_e32 v191, v179
	s_and_b64 vcc, exec, s[0:1]
	s_cbranch_vccnz .LBB0_1239
	s_and_b64 s[26:27], s[24:25], exec
	v_or_b32_e32 v178, v239, v158
	v_readlane_b32 s26, v252, 45
	v_readlane_b32 s28, v252, 47
	v_ashrrev_i32_e32 v179, 31, v178
	v_readlane_b32 s27, v252, 46
	v_readlane_b32 s29, v252, 48
	v_lshlrev_b64 v[178:179], 11, v[178:179]
	s_cselect_b32 s27, s27, s29
	s_cselect_b32 s26, s26, s28
	v_readlane_b32 s36, v252, 26
	s_movk_i32 s28, 0xf000
	v_readlane_b32 s37, v252, 27
	v_lshl_add_u64 v[178:179], s[26:27], 0, v[178:179]
	s_mov_b32 s29, s37
	s_cselect_b32 s28, s28, 0xffffe800
	v_lshl_add_u64 v[178:179], v[128:129], 1, v[178:179]
	v_lshl_add_u64 v[178:179], v[178:179], 0, s[28:29]
	v_cvt_pk_bf16_f32 v193, v187, s0
	global_store_short v[178:179], v193, off
	v_cvt_pk_bf16_f32 v193, v133, s0
	s_mov_b32 s27, s37
	global_store_short v[178:179], v193, off offset:2048
	v_add_co_u32_e32 v178, vcc, 0x1000, v178
	v_writelane_b32 v252, s26, 26
	v_cvt_pk_bf16_f32 v193, v191, s0
	v_addc_co_u32_e32 v179, vcc, 0, v179, vcc
	v_writelane_b32 v252, s27, 27
	global_store_short v[178:179], v193, off
	v_cvt_pk_bf16_f32 v193, v189, s0
	s_mov_b64 s[26:27], 0
	global_store_short v[178:179], v193, off offset:2048

.LBB0_1241:
	v_mov_b32_e32 v187, v186
	ds_bpermute_b32 v184, v244, v103
	v_mov_b32_e32 v193, v192
	v_mov_b32_e32 v225, v100
	v_mov_b32_e32 v189, v188
	v_mov_b32_e32 v191, v190
	s_waitcnt lgkmcnt(0)
	v_cndmask_b32_e64 v224, v184, v131, s[4:5]
	v_pk_fma_f32 v[224:225], v[186:187], v[224:225], v[192:193]
	v_mov_b32_e32 v226, v101
	v_pk_fma_f32 v[224:225], v[100:101], v[188:189], v[224:225]
	v_mov_b32_e32 v227, v102
	v_pk_fma_f32 v[224:225], v[226:227], v[190:191], v[224:225]
	v_mul_f32_e32 v131, 0xbfb8aa3b, v224
	v_exp_f32_e32 v240, v131
	v_mul_f32_e32 v131, 0xbfb8aa3b, v225
	v_exp_f32_e32 v241, v131
	s_nop 0
	v_pk_add_f32 v[240:241], v[240:241], 1.0 op_sel_hi:[1,0]
	ds_bpermute_b32 v185, v244, v104
	v_rcp_f32_e32 v133, v241
	s_waitcnt lgkmcnt(0)
	v_cndmask_b32_e64 v195, v185, v194, s[4:5]
	v_mul_f32_e32 v131, v225, v133
	v_rcp_f32_e32 v194, v240
	s_nop 0
	v_mul_f32_e32 v133, v224, v194
	v_pk_fma_f32 v[224:225], v[226:227], v[186:187], v[192:193]
	v_mov_b32_e32 v194, v103
	v_pk_fma_f32 v[224:225], v[102:103], v[188:189], v[224:225]
	s_nop 0
	v_pk_fma_f32 v[224:225], v[194:195], v[190:191], v[224:225]
	s_nop 0
	v_mul_f32_e32 v194, 0xbfb8aa3b, v224
	v_mul_f32_e32 v195, 0xbfb8aa3b, v225
	v_exp_f32_e32 v194, v194
	v_exp_f32_e32 v195, v195
	s_nop 0
	v_pk_add_f32 v[226:227], v[194:195], 1.0 op_sel_hi:[1,0]
	s_nop 0
	v_rcp_f32_e32 v195, v227
	s_nop 0
	v_mul_f32_e32 v194, v225, v195
	v_rcp_f32_e32 v222, v226
	s_mov_b64 s[26:27], -1
	v_mul_f32_e32 v195, v224, v222
	s_and_b64 vcc, exec, s[0:1]
	s_cbranch_vccnz .LBB0_1243
	s_and_b64 s[26:27], s[24:25], exec
	v_readlane_b32 s26, v252, 45
	v_readlane_b32 s28, v252, 47
	v_readlane_b32 s27, v252, 46
	v_readlane_b32 s29, v252, 48
	v_lshlrev_b64 v[182:183], 11, v[182:183]
	s_cselect_b32 s27, s27, s29
	s_cselect_b32 s26, s26, s28
	v_readlane_b32 s36, v252, 26
	s_movk_i32 s28, 0xf000
	v_readlane_b32 s37, v252, 27
	v_lshl_add_u64 v[182:183], s[26:27], 0, v[182:183]
	s_mov_b32 s29, s37
	s_cselect_b32 s28, s28, 0xffffe800
	v_lshl_add_u64 v[182:183], v[128:129], 1, v[182:183]
	v_lshl_add_u64 v[182:183], v[182:183], 0, s[28:29]
	v_cvt_pk_bf16_f32 v222, v133, s0
	global_store_short v[182:183], v222, off
	v_cvt_pk_bf16_f32 v222, v131, s0
	s_mov_b32 s27, s37
	global_store_short v[182:183], v222, off offset:2048
	v_add_co_u32_e32 v182, vcc, 0x1000, v182
	v_writelane_b32 v252, s26, 26
	v_cvt_pk_bf16_f32 v222, v195, s0
	v_addc_co_u32_e32 v183, vcc, 0, v183, vcc
	v_writelane_b32 v252, s27, 27
	global_store_short v[182:183], v222, off
	v_cvt_pk_bf16_f32 v222, v194, s0
	s_mov_b64 s[26:27], 0
	global_store_short v[182:183], v222, off offset:2048

.LBB0_1245:
	v_mov_b32_e32 v224, v105
	ds_bpermute_b32 v131, v244, v107
	ds_bpermute_b32 v182, v244, v108
	v_mov_b32_e32 v225, v106
	s_waitcnt lgkmcnt(1)
	v_cndmask_b32_e64 v184, v131, v184, s[4:5]
	s_waitcnt lgkmcnt(0)
	v_cndmask_b32_e64 v195, v182, v185, s[4:5]
	v_mov_b32_e32 v185, v104
	v_pk_fma_f32 v[184:185], v[186:187], v[184:185], v[192:193]
	s_nop 0
	v_pk_fma_f32 v[184:185], v[104:105], v[188:189], v[184:185]
	s_nop 0
	v_pk_fma_f32 v[184:185], v[224:225], v[190:191], v[184:185]
	s_nop 0
	v_mul_f32_e32 v133, 0xbfb8aa3b, v184
	v_exp_f32_e32 v226, v133
	v_mul_f32_e32 v133, 0xbfb8aa3b, v185
	v_exp_f32_e32 v227, v133
	s_nop 0
	v_pk_add_f32 v[226:227], v[226:227], 1.0 op_sel_hi:[1,0]
	s_nop 0
	v_rcp_f32_e32 v183, v227
	s_nop 0
	v_mul_f32_e32 v133, v185, v183
	v_rcp_f32_e32 v185, v226
	s_nop 0
	v_mul_f32_e32 v183, v184, v185
	v_pk_fma_f32 v[184:185], v[224:225], v[186:187], v[192:193]
	v_mov_b32_e32 v194, v107
	v_pk_fma_f32 v[184:185], v[106:107], v[188:189], v[184:185]
	s_nop 0
	v_pk_fma_f32 v[194:195], v[194:195], v[190:191], v[184:185]
	s_nop 0
	v_mul_f32_e32 v184, 0xbfb8aa3b, v194
	v_mul_f32_e32 v185, 0xbfb8aa3b, v195
	v_exp_f32_e32 v184, v184
	v_exp_f32_e32 v185, v185
	s_nop 0
	v_pk_add_f32 v[224:225], v[184:185], 1.0 op_sel_hi:[1,0]
	s_nop 0
	v_rcp_f32_e32 v185, v225
	s_nop 0
	v_mul_f32_e32 v184, v195, v185
	v_rcp_f32_e32 v195, v224
	s_mov_b64 s[26:27], -1
	v_mul_f32_e32 v185, v194, v195
	s_and_b64 vcc, exec, s[0:1]
	s_cbranch_vccnz .LBB0_1247
	s_and_b64 s[26:27], s[24:25], exec
	v_readlane_b32 s26, v252, 45
	v_readlane_b32 s28, v252, 47
	v_readlane_b32 s27, v252, 46
	v_readlane_b32 s29, v252, 48
	v_lshlrev_b64 v[180:181], 11, v[180:181]
	s_cselect_b32 s27, s27, s29
	s_cselect_b32 s26, s26, s28
	v_readlane_b32 s36, v252, 26
	s_movk_i32 s28, 0xf000
	v_readlane_b32 s37, v252, 27
	v_lshl_add_u64 v[180:181], s[26:27], 0, v[180:181]
	s_mov_b32 s29, s37
	s_cselect_b32 s28, s28, 0xffffe800
	v_lshl_add_u64 v[180:181], v[128:129], 1, v[180:181]
	v_lshl_add_u64 v[180:181], v[180:181], 0, s[28:29]
	v_cvt_pk_bf16_f32 v194, v183, s0
	global_store_short v[180:181], v194, off
	v_cvt_pk_bf16_f32 v194, v133, s0
	s_mov_b32 s27, s37
	global_store_short v[180:181], v194, off offset:2048
	v_add_co_u32_e32 v180, vcc, 0x1000, v180
	v_writelane_b32 v252, s26, 26
	v_cvt_pk_bf16_f32 v194, v185, s0
	v_addc_co_u32_e32 v181, vcc, 0, v181, vcc
	v_writelane_b32 v252, s27, 27
	global_store_short v[180:181], v194, off
	v_cvt_pk_bf16_f32 v194, v184, s0
	s_mov_b64 s[26:27], 0
	global_store_short v[180:181], v194, off offset:2048

.LBB0_1249:
	v_mov_b32_e32 v185, v108
	ds_bpermute_b32 v180, v244, v111
	v_mov_b32_e32 v194, v109
	v_mov_b32_e32 v195, v110
	s_waitcnt lgkmcnt(0)
	v_cndmask_b32_e64 v184, v180, v131, s[4:5]
	v_pk_fma_f32 v[184:185], v[186:187], v[184:185], v[192:193]
	v_pk_fma_f32 v[184:185], v[108:109], v[188:189], v[184:185]
	v_pk_fma_f32 v[184:185], v[194:195], v[190:191], v[184:185]
	ds_bpermute_b32 v181, v244, v64
	v_mul_f32_e32 v131, 0xbfb8aa3b, v184
	v_exp_f32_e32 v224, v131
	v_mul_f32_e32 v131, 0xbfb8aa3b, v185
	v_exp_f32_e32 v225, v131
	s_waitcnt lgkmcnt(0)
	v_cndmask_b32_e64 v183, v181, v182, s[4:5]
	v_pk_add_f32 v[224:225], v[224:225], 1.0 op_sel_hi:[1,0]
	s_nop 0
	v_rcp_f32_e32 v133, v225
	s_nop 0
	v_mul_f32_e32 v131, v185, v133
	v_rcp_f32_e32 v182, v224
	s_nop 0
	v_mul_f32_e32 v133, v184, v182
	v_pk_fma_f32 v[184:185], v[194:195], v[186:187], v[192:193]
	v_mov_b32_e32 v182, v111
	v_pk_fma_f32 v[184:185], v[110:111], v[188:189], v[184:185]
	s_nop 0
	v_pk_fma_f32 v[184:185], v[182:183], v[190:191], v[184:185]
	s_nop 0
	v_mul_f32_e32 v182, 0xbfb8aa3b, v184
	v_mul_f32_e32 v183, 0xbfb8aa3b, v185
	v_exp_f32_e32 v182, v182
	v_exp_f32_e32 v183, v183
	s_nop 0
	v_pk_add_f32 v[194:195], v[182:183], 1.0 op_sel_hi:[1,0]
	s_nop 0
	v_rcp_f32_e32 v183, v195
	s_nop 0
	v_mul_f32_e32 v182, v185, v183
	v_rcp_f32_e32 v185, v194
	s_mov_b64 s[26:27], -1
	v_mul_f32_e32 v183, v184, v185
	s_and_b64 vcc, exec, s[0:1]
	s_cbranch_vccnz .LBB0_1251
	s_and_b64 s[26:27], s[24:25], exec
	v_readlane_b32 s26, v252, 45
	v_readlane_b32 s28, v252, 47
	v_readlane_b32 s27, v252, 46
	v_readlane_b32 s29, v252, 48
	v_lshlrev_b64 v[176:177], 11, v[176:177]
	s_cselect_b32 s27, s27, s29
	s_cselect_b32 s26, s26, s28
	v_readlane_b32 s36, v252, 26
	s_movk_i32 s28, 0xf000
	v_readlane_b32 s37, v252, 27
	v_lshl_add_u64 v[176:177], s[26:27], 0, v[176:177]
	s_mov_b32 s29, s37
	s_cselect_b32 s28, s28, 0xffffe800
	v_lshl_add_u64 v[176:177], v[128:129], 1, v[176:177]
	v_lshl_add_u64 v[176:177], v[176:177], 0, s[28:29]
	v_cvt_pk_bf16_f32 v184, v133, s0
	global_store_short v[176:177], v184, off
	v_cvt_pk_bf16_f32 v184, v131, s0
	s_mov_b32 s27, s37
	global_store_short v[176:177], v184, off offset:2048
	v_add_co_u32_e32 v176, vcc, 0x1000, v176
	v_writelane_b32 v252, s26, 26
	v_cvt_pk_bf16_f32 v184, v183, s0
	v_addc_co_u32_e32 v177, vcc, 0, v177, vcc
	v_writelane_b32 v252, s27, 27
	global_store_short v[176:177], v184, off
	v_cvt_pk_bf16_f32 v184, v182, s0
	s_mov_b64 s[26:27], 0
	global_store_short v[176:177], v184, off offset:2048

.LBB0_1253:
	v_mov_b32_e32 v184, v65
	ds_bpermute_b32 v176, v244, v67
	v_mov_b32_e32 v185, v66
	ds_bpermute_b32 v177, v244, v68
	s_waitcnt lgkmcnt(1)
	v_cndmask_b32_e64 v180, v176, v180, s[4:5]
	s_waitcnt lgkmcnt(0)
	v_cndmask_b32_e64 v183, v177, v181, s[4:5]
	v_mov_b32_e32 v181, v64
	v_pk_fma_f32 v[180:181], v[186:187], v[180:181], v[192:193]
	s_nop 0
	v_pk_fma_f32 v[180:181], v[64:65], v[188:189], v[180:181]
	s_nop 0
	v_pk_fma_f32 v[180:181], v[184:185], v[190:191], v[180:181]
	s_nop 0
	v_mul_f32_e32 v131, 0xbfb8aa3b, v180
	v_exp_f32_e32 v194, v131
	v_mul_f32_e32 v131, 0xbfb8aa3b, v181
	v_exp_f32_e32 v195, v131
	s_nop 0
	v_pk_add_f32 v[194:195], v[194:195], 1.0 op_sel_hi:[1,0]
	s_nop 0
	v_rcp_f32_e32 v133, v195
	s_nop 0
	v_mul_f32_e32 v131, v181, v133
	v_rcp_f32_e32 v181, v194
	s_nop 0
	v_mul_f32_e32 v133, v180, v181
	v_pk_fma_f32 v[180:181], v[184:185], v[186:187], v[192:193]
	v_mov_b32_e32 v182, v67
	v_pk_fma_f32 v[180:181], v[66:67], v[188:189], v[180:181]
	s_nop 0
	v_pk_fma_f32 v[182:183], v[182:183], v[190:191], v[180:181]
	s_nop 0
	v_mul_f32_e32 v180, 0xbfb8aa3b, v182
	v_mul_f32_e32 v181, 0xbfb8aa3b, v183
	v_exp_f32_e32 v180, v180
	v_exp_f32_e32 v181, v181
	s_nop 0
	v_pk_add_f32 v[184:185], v[180:181], 1.0 op_sel_hi:[1,0]
	s_nop 0
	v_rcp_f32_e32 v181, v185
	s_nop 0
	v_mul_f32_e32 v180, v183, v181
	v_rcp_f32_e32 v183, v184
	s_mov_b64 s[26:27], -1
	v_mul_f32_e32 v181, v182, v183
	s_and_b64 vcc, exec, s[0:1]
	s_cbranch_vccnz .LBB0_1255
	s_and_b64 s[26:27], s[24:25], exec
	v_readlane_b32 s26, v252, 45
	v_readlane_b32 s28, v252, 47
	v_readlane_b32 s27, v252, 46
	v_readlane_b32 s29, v252, 48
	v_lshlrev_b64 v[174:175], 11, v[174:175]
	s_cselect_b32 s27, s27, s29
	s_cselect_b32 s26, s26, s28
	v_readlane_b32 s36, v252, 26
	s_movk_i32 s28, 0xf000
	v_readlane_b32 s37, v252, 27
	v_lshl_add_u64 v[174:175], s[26:27], 0, v[174:175]
	s_mov_b32 s29, s37
	s_cselect_b32 s28, s28, 0xffffe800
	v_lshl_add_u64 v[174:175], v[128:129], 1, v[174:175]
	v_lshl_add_u64 v[174:175], v[174:175], 0, s[28:29]
	v_cvt_pk_bf16_f32 v182, v133, s0
	global_store_short v[174:175], v182, off
	v_cvt_pk_bf16_f32 v182, v131, s0
	s_mov_b32 s27, s37
	global_store_short v[174:175], v182, off offset:2048
	v_add_co_u32_e32 v174, vcc, 0x1000, v174
	v_writelane_b32 v252, s26, 26
	v_cvt_pk_bf16_f32 v182, v181, s0
	v_addc_co_u32_e32 v175, vcc, 0, v175, vcc
	v_writelane_b32 v252, s27, 27
	global_store_short v[174:175], v182, off
	v_cvt_pk_bf16_f32 v182, v180, s0
	s_mov_b64 s[26:27], 0
	global_store_short v[174:175], v182, off offset:2048

.LBB0_1257:
	v_mov_b32_e32 v182, v69
	ds_bpermute_b32 v131, v244, v71
	ds_bpermute_b32 v174, v244, v72
	v_mov_b32_e32 v183, v70
	s_waitcnt lgkmcnt(1)
	v_cndmask_b32_e64 v176, v131, v176, s[4:5]
	s_waitcnt lgkmcnt(0)
	v_cndmask_b32_e64 v181, v174, v177, s[4:5]
	v_mov_b32_e32 v177, v68
	v_pk_fma_f32 v[176:177], v[186:187], v[176:177], v[192:193]
	s_nop 0
	v_pk_fma_f32 v[176:177], v[68:69], v[188:189], v[176:177]
	s_nop 0
	v_pk_fma_f32 v[176:177], v[182:183], v[190:191], v[176:177]
	s_nop 0
	v_mul_f32_e32 v133, 0xbfb8aa3b, v176
	v_exp_f32_e32 v184, v133
	v_mul_f32_e32 v133, 0xbfb8aa3b, v177
	v_exp_f32_e32 v185, v133
	s_nop 0
	v_pk_add_f32 v[184:185], v[184:185], 1.0 op_sel_hi:[1,0]
	s_nop 0
	v_rcp_f32_e32 v175, v185
	s_nop 0
	v_mul_f32_e32 v133, v177, v175
	v_rcp_f32_e32 v177, v184
	s_nop 0
	v_mul_f32_e32 v175, v176, v177
	v_pk_fma_f32 v[176:177], v[182:183], v[186:187], v[192:193]
	v_mov_b32_e32 v180, v71
	v_pk_fma_f32 v[176:177], v[70:71], v[188:189], v[176:177]
	s_nop 0
	v_pk_fma_f32 v[180:181], v[180:181], v[190:191], v[176:177]
	s_nop 0
	v_mul_f32_e32 v176, 0xbfb8aa3b, v180
	v_mul_f32_e32 v177, 0xbfb8aa3b, v181
	v_exp_f32_e32 v176, v176
	v_exp_f32_e32 v177, v177
	s_nop 0
	v_pk_add_f32 v[182:183], v[176:177], 1.0 op_sel_hi:[1,0]
	s_nop 0
	v_rcp_f32_e32 v177, v183
	s_nop 0
	v_mul_f32_e32 v176, v181, v177
	v_rcp_f32_e32 v181, v182
	s_mov_b64 s[26:27], -1
	v_mul_f32_e32 v177, v180, v181
	s_and_b64 vcc, exec, s[0:1]
	s_cbranch_vccnz .LBB0_1259
	s_and_b64 s[26:27], s[24:25], exec
	v_readlane_b32 s26, v252, 45
	v_readlane_b32 s28, v252, 47
	v_readlane_b32 s27, v252, 46
	v_readlane_b32 s29, v252, 48
	v_lshlrev_b64 v[172:173], 11, v[172:173]
	s_cselect_b32 s27, s27, s29
	s_cselect_b32 s26, s26, s28
	v_readlane_b32 s36, v252, 26
	s_movk_i32 s28, 0xf000
	v_readlane_b32 s37, v252, 27
	v_lshl_add_u64 v[172:173], s[26:27], 0, v[172:173]
	s_mov_b32 s29, s37
	s_cselect_b32 s28, s28, 0xffffe800
	v_lshl_add_u64 v[172:173], v[128:129], 1, v[172:173]
	v_lshl_add_u64 v[172:173], v[172:173], 0, s[28:29]
	v_cvt_pk_bf16_f32 v180, v175, s0
	global_store_short v[172:173], v180, off
	v_cvt_pk_bf16_f32 v180, v133, s0
	s_mov_b32 s27, s37
	global_store_short v[172:173], v180, off offset:2048
	v_add_co_u32_e32 v172, vcc, 0x1000, v172
	v_writelane_b32 v252, s26, 26
	v_cvt_pk_bf16_f32 v180, v177, s0
	v_addc_co_u32_e32 v173, vcc, 0, v173, vcc
	v_writelane_b32 v252, s27, 27
	global_store_short v[172:173], v180, off
	v_cvt_pk_bf16_f32 v180, v176, s0
	s_mov_b64 s[26:27], 0
	global_store_short v[172:173], v180, off offset:2048

.LBB0_1261:
	v_mov_b32_e32 v177, v72
	ds_bpermute_b32 v172, v244, v75
	v_mov_b32_e32 v180, v73
	v_mov_b32_e32 v181, v74
	s_waitcnt lgkmcnt(0)
	v_cndmask_b32_e64 v176, v172, v131, s[4:5]
	v_pk_fma_f32 v[176:177], v[186:187], v[176:177], v[192:193]
	v_pk_fma_f32 v[176:177], v[72:73], v[188:189], v[176:177]
	v_pk_fma_f32 v[176:177], v[180:181], v[190:191], v[176:177]
	ds_bpermute_b32 v173, v244, v76
	v_mul_f32_e32 v131, 0xbfb8aa3b, v176
	v_exp_f32_e32 v182, v131
	v_mul_f32_e32 v131, 0xbfb8aa3b, v177
	v_exp_f32_e32 v183, v131
	s_waitcnt lgkmcnt(0)
	v_cndmask_b32_e64 v175, v173, v174, s[4:5]
	v_pk_add_f32 v[182:183], v[182:183], 1.0 op_sel_hi:[1,0]
	s_nop 0
	v_rcp_f32_e32 v133, v183
	s_nop 0
	v_mul_f32_e32 v131, v177, v133
	v_rcp_f32_e32 v174, v182
	s_nop 0
	v_mul_f32_e32 v133, v176, v174
	v_pk_fma_f32 v[176:177], v[180:181], v[186:187], v[192:193]
	v_mov_b32_e32 v174, v75
	v_pk_fma_f32 v[176:177], v[74:75], v[188:189], v[176:177]
	s_nop 0
	v_pk_fma_f32 v[176:177], v[174:175], v[190:191], v[176:177]
	s_nop 0
	v_mul_f32_e32 v174, 0xbfb8aa3b, v176
	v_mul_f32_e32 v175, 0xbfb8aa3b, v177
	v_exp_f32_e32 v174, v174
	v_exp_f32_e32 v175, v175
	s_nop 0
	v_pk_add_f32 v[180:181], v[174:175], 1.0 op_sel_hi:[1,0]
	s_nop 0
	v_rcp_f32_e32 v175, v181
	s_nop 0
	v_mul_f32_e32 v174, v177, v175
	v_rcp_f32_e32 v177, v180
	s_mov_b64 s[26:27], -1
	v_mul_f32_e32 v175, v176, v177
	s_and_b64 vcc, exec, s[0:1]
	s_cbranch_vccnz .LBB0_1263
	s_and_b64 s[26:27], s[24:25], exec
	v_readlane_b32 s26, v252, 45
	v_readlane_b32 s28, v252, 47
	v_readlane_b32 s27, v252, 46
	v_readlane_b32 s29, v252, 48
	v_lshlrev_b64 v[152:153], 11, v[152:153]
	s_cselect_b32 s27, s27, s29
	s_cselect_b32 s26, s26, s28
	v_readlane_b32 s36, v252, 26
	s_movk_i32 s28, 0xf000
	v_readlane_b32 s37, v252, 27
	v_lshl_add_u64 v[152:153], s[26:27], 0, v[152:153]
	s_mov_b32 s29, s37
	s_cselect_b32 s28, s28, 0xffffe800
	v_lshl_add_u64 v[152:153], v[128:129], 1, v[152:153]
	v_lshl_add_u64 v[152:153], v[152:153], 0, s[28:29]
	v_cvt_pk_bf16_f32 v176, v133, s0
	global_store_short v[152:153], v176, off
	v_cvt_pk_bf16_f32 v176, v131, s0
	s_mov_b32 s27, s37
	global_store_short v[152:153], v176, off offset:2048
	v_add_co_u32_e32 v152, vcc, 0x1000, v152
	v_writelane_b32 v252, s26, 26
	v_cvt_pk_bf16_f32 v176, v175, s0
	v_addc_co_u32_e32 v153, vcc, 0, v153, vcc
	v_writelane_b32 v252, s27, 27
	global_store_short v[152:153], v176, off
	v_cvt_pk_bf16_f32 v176, v174, s0
	s_mov_b64 s[26:27], 0
	global_store_short v[152:153], v176, off offset:2048

.LBB0_1265:
	v_mov_b32_e32 v176, v77
	ds_bpermute_b32 v131, v244, v79
	ds_bpermute_b32 v152, v244, v32
	v_mov_b32_e32 v177, v78
	s_waitcnt lgkmcnt(1)
	v_cndmask_b32_e64 v172, v131, v172, s[4:5]
	s_waitcnt lgkmcnt(0)
	v_cndmask_b32_e64 v175, v152, v173, s[4:5]
	v_mov_b32_e32 v173, v76
	v_pk_fma_f32 v[172:173], v[186:187], v[172:173], v[192:193]
	s_nop 0
	v_pk_fma_f32 v[172:173], v[76:77], v[188:189], v[172:173]
	s_nop 0
	v_pk_fma_f32 v[172:173], v[176:177], v[190:191], v[172:173]
	s_nop 0
	v_mul_f32_e32 v133, 0xbfb8aa3b, v172
	v_exp_f32_e32 v180, v133
	v_mul_f32_e32 v133, 0xbfb8aa3b, v173
	v_exp_f32_e32 v181, v133
	s_nop 0
	v_pk_add_f32 v[180:181], v[180:181], 1.0 op_sel_hi:[1,0]
	s_nop 0
	v_rcp_f32_e32 v153, v181
	s_nop 0
	v_mul_f32_e32 v133, v173, v153
	v_rcp_f32_e32 v173, v180
	s_nop 0
	v_mul_f32_e32 v153, v172, v173
	v_pk_fma_f32 v[172:173], v[176:177], v[186:187], v[192:193]
	v_mov_b32_e32 v174, v79
	v_pk_fma_f32 v[172:173], v[78:79], v[188:189], v[172:173]
	s_nop 0
	v_pk_fma_f32 v[174:175], v[174:175], v[190:191], v[172:173]
	s_nop 0
	v_mul_f32_e32 v172, 0xbfb8aa3b, v174
	v_mul_f32_e32 v173, 0xbfb8aa3b, v175
	v_exp_f32_e32 v172, v172
	v_exp_f32_e32 v173, v173
	s_nop 0
	v_pk_add_f32 v[176:177], v[172:173], 1.0 op_sel_hi:[1,0]
	s_nop 0
	v_rcp_f32_e32 v173, v177
	s_nop 0
	v_mul_f32_e32 v172, v175, v173
	v_rcp_f32_e32 v175, v176
	s_mov_b64 s[26:27], -1
	v_mul_f32_e32 v173, v174, v175
	s_and_b64 vcc, exec, s[0:1]
	s_cbranch_vccnz .LBB0_1267
	s_and_b64 s[26:27], s[24:25], exec
	v_readlane_b32 s26, v252, 45
	v_readlane_b32 s28, v252, 47
	v_readlane_b32 s27, v252, 46
	v_readlane_b32 s29, v252, 48
	v_lshlrev_b64 v[150:151], 11, v[150:151]
	s_cselect_b32 s27, s27, s29
	s_cselect_b32 s26, s26, s28
	v_readlane_b32 s36, v252, 26
	s_movk_i32 s28, 0xf000
	v_readlane_b32 s37, v252, 27
	v_lshl_add_u64 v[150:151], s[26:27], 0, v[150:151]
	s_mov_b32 s29, s37
	s_cselect_b32 s28, s28, 0xffffe800
	v_lshl_add_u64 v[150:151], v[128:129], 1, v[150:151]
	v_lshl_add_u64 v[150:151], v[150:151], 0, s[28:29]
	v_cvt_pk_bf16_f32 v174, v153, s0
	global_store_short v[150:151], v174, off
	v_cvt_pk_bf16_f32 v174, v133, s0
	s_mov_b32 s27, s37
	global_store_short v[150:151], v174, off offset:2048
	v_add_co_u32_e32 v150, vcc, 0x1000, v150
	v_writelane_b32 v252, s26, 26
	v_cvt_pk_bf16_f32 v174, v173, s0
	v_addc_co_u32_e32 v151, vcc, 0, v151, vcc
	v_writelane_b32 v252, s27, 27
	global_store_short v[150:151], v174, off
	v_cvt_pk_bf16_f32 v174, v172, s0
	s_mov_b64 s[26:27], 0
	global_store_short v[150:151], v174, off offset:2048

.LBB0_1269:
	v_mov_b32_e32 v173, v32
	ds_bpermute_b32 v150, v244, v35
	v_mov_b32_e32 v174, v33
	v_mov_b32_e32 v175, v34
	s_waitcnt lgkmcnt(0)
	v_cndmask_b32_e64 v172, v150, v131, s[4:5]
	v_pk_fma_f32 v[172:173], v[186:187], v[172:173], v[192:193]
	v_pk_fma_f32 v[172:173], v[32:33], v[188:189], v[172:173]
	v_pk_fma_f32 v[172:173], v[174:175], v[190:191], v[172:173]
	ds_bpermute_b32 v151, v244, v36
	v_mul_f32_e32 v131, 0xbfb8aa3b, v172
	v_exp_f32_e32 v176, v131
	v_mul_f32_e32 v131, 0xbfb8aa3b, v173
	v_exp_f32_e32 v177, v131
	s_waitcnt lgkmcnt(0)
	v_cndmask_b32_e64 v153, v151, v152, s[4:5]
	v_pk_add_f32 v[176:177], v[176:177], 1.0 op_sel_hi:[1,0]
	s_nop 0
	v_rcp_f32_e32 v133, v177
	s_nop 0
	v_mul_f32_e32 v131, v173, v133
	v_rcp_f32_e32 v152, v176
	s_nop 0
	v_mul_f32_e32 v133, v172, v152
	v_pk_fma_f32 v[172:173], v[174:175], v[186:187], v[192:193]
	v_mov_b32_e32 v152, v35
	v_pk_fma_f32 v[172:173], v[34:35], v[188:189], v[172:173]
	s_nop 0
	v_pk_fma_f32 v[172:173], v[152:153], v[190:191], v[172:173]
	s_nop 0
	v_mul_f32_e32 v152, 0xbfb8aa3b, v172
	v_mul_f32_e32 v153, 0xbfb8aa3b, v173
	v_exp_f32_e32 v152, v152
	v_exp_f32_e32 v153, v153
	s_nop 0
	v_pk_add_f32 v[174:175], v[152:153], 1.0 op_sel_hi:[1,0]
	s_nop 0
	v_rcp_f32_e32 v153, v175
	s_nop 0
	v_mul_f32_e32 v152, v173, v153
	v_rcp_f32_e32 v173, v174
	s_mov_b64 s[26:27], -1
	v_mul_f32_e32 v153, v172, v173
	s_and_b64 vcc, exec, s[0:1]
	s_cbranch_vccnz .LBB0_1271
	s_and_b64 s[26:27], s[24:25], exec
	v_readlane_b32 s26, v252, 45
	v_readlane_b32 s28, v252, 47
	v_readlane_b32 s27, v252, 46
	v_readlane_b32 s29, v252, 48
	v_lshlrev_b64 v[148:149], 11, v[148:149]
	s_cselect_b32 s27, s27, s29
	s_cselect_b32 s26, s26, s28
	v_readlane_b32 s36, v252, 26
	s_movk_i32 s28, 0xf000
	v_readlane_b32 s37, v252, 27
	v_lshl_add_u64 v[148:149], s[26:27], 0, v[148:149]
	s_mov_b32 s29, s37
	s_cselect_b32 s28, s28, 0xffffe800
	v_lshl_add_u64 v[148:149], v[128:129], 1, v[148:149]
	v_lshl_add_u64 v[148:149], v[148:149], 0, s[28:29]
	v_cvt_pk_bf16_f32 v172, v133, s0
	global_store_short v[148:149], v172, off
	v_cvt_pk_bf16_f32 v172, v131, s0
	s_mov_b32 s27, s37
	global_store_short v[148:149], v172, off offset:2048
	v_add_co_u32_e32 v148, vcc, 0x1000, v148
	v_writelane_b32 v252, s26, 26
	v_cvt_pk_bf16_f32 v172, v153, s0
	v_addc_co_u32_e32 v149, vcc, 0, v149, vcc
	v_writelane_b32 v252, s27, 27
	global_store_short v[148:149], v172, off
	v_cvt_pk_bf16_f32 v172, v152, s0
	s_mov_b64 s[26:27], 0
	global_store_short v[148:149], v172, off offset:2048

.LBB0_1273:
	v_mov_b32_e32 v172, v37
	ds_bpermute_b32 v131, v244, v39
	ds_bpermute_b32 v148, v244, v40
	v_mov_b32_e32 v173, v38
	s_waitcnt lgkmcnt(1)
	v_cndmask_b32_e64 v150, v131, v150, s[4:5]
	s_waitcnt lgkmcnt(0)
	v_cndmask_b32_e64 v153, v148, v151, s[4:5]
	v_mov_b32_e32 v151, v36
	v_pk_fma_f32 v[150:151], v[186:187], v[150:151], v[192:193]
	s_nop 0
	v_pk_fma_f32 v[150:151], v[36:37], v[188:189], v[150:151]
	s_nop 0
	v_pk_fma_f32 v[150:151], v[172:173], v[190:191], v[150:151]
	s_nop 0
	v_mul_f32_e32 v133, 0xbfb8aa3b, v150
	v_exp_f32_e32 v174, v133
	v_mul_f32_e32 v133, 0xbfb8aa3b, v151
	v_exp_f32_e32 v175, v133
	s_nop 0
	v_pk_add_f32 v[174:175], v[174:175], 1.0 op_sel_hi:[1,0]
	s_nop 0
	v_rcp_f32_e32 v149, v175
	s_nop 0
	v_mul_f32_e32 v133, v151, v149
	v_rcp_f32_e32 v151, v174
	s_nop 0
	v_mul_f32_e32 v149, v150, v151
	v_pk_fma_f32 v[150:151], v[172:173], v[186:187], v[192:193]
	v_mov_b32_e32 v152, v39
	v_pk_fma_f32 v[150:151], v[38:39], v[188:189], v[150:151]
	s_nop 0
	v_pk_fma_f32 v[152:153], v[152:153], v[190:191], v[150:151]
	s_nop 0
	v_mul_f32_e32 v150, 0xbfb8aa3b, v152
	v_mul_f32_e32 v151, 0xbfb8aa3b, v153
	v_exp_f32_e32 v150, v150
	v_exp_f32_e32 v151, v151
	s_nop 0
	v_pk_add_f32 v[172:173], v[150:151], 1.0 op_sel_hi:[1,0]
	s_nop 0
	v_rcp_f32_e32 v151, v173
	s_nop 0
	v_mul_f32_e32 v150, v153, v151
	v_rcp_f32_e32 v153, v172
	s_mov_b64 s[26:27], -1
	v_mul_f32_e32 v151, v152, v153
	s_and_b64 vcc, exec, s[0:1]
	s_cbranch_vccnz .LBB0_1275
	s_and_b64 s[26:27], s[24:25], exec
	v_readlane_b32 s26, v252, 45
	v_readlane_b32 s28, v252, 47
	v_readlane_b32 s27, v252, 46
	v_readlane_b32 s29, v252, 48
	v_lshlrev_b64 v[146:147], 11, v[146:147]
	s_cselect_b32 s27, s27, s29
	s_cselect_b32 s26, s26, s28
	v_readlane_b32 s36, v252, 26
	s_movk_i32 s28, 0xf000
	v_readlane_b32 s37, v252, 27
	v_lshl_add_u64 v[146:147], s[26:27], 0, v[146:147]
	s_mov_b32 s29, s37
	s_cselect_b32 s28, s28, 0xffffe800
	v_lshl_add_u64 v[146:147], v[128:129], 1, v[146:147]
	v_lshl_add_u64 v[146:147], v[146:147], 0, s[28:29]
	v_cvt_pk_bf16_f32 v152, v149, s0
	global_store_short v[146:147], v152, off
	v_cvt_pk_bf16_f32 v152, v133, s0
	s_mov_b32 s27, s37
	global_store_short v[146:147], v152, off offset:2048
	v_add_co_u32_e32 v146, vcc, 0x1000, v146
	v_writelane_b32 v252, s26, 26
	v_cvt_pk_bf16_f32 v152, v151, s0
	v_addc_co_u32_e32 v147, vcc, 0, v147, vcc
	v_writelane_b32 v252, s27, 27
	global_store_short v[146:147], v152, off
	v_cvt_pk_bf16_f32 v152, v150, s0
	s_mov_b64 s[26:27], 0
	global_store_short v[146:147], v152, off offset:2048

.LBB0_1277:
	v_mov_b32_e32 v151, v40
	ds_bpermute_b32 v146, v244, v43
	v_mov_b32_e32 v152, v41
	v_mov_b32_e32 v153, v42
	s_waitcnt lgkmcnt(0)
	v_cndmask_b32_e64 v150, v146, v131, s[4:5]
	v_pk_fma_f32 v[150:151], v[186:187], v[150:151], v[192:193]
	v_pk_fma_f32 v[150:151], v[40:41], v[188:189], v[150:151]
	v_pk_fma_f32 v[150:151], v[152:153], v[190:191], v[150:151]
	ds_bpermute_b32 v147, v244, v44
	v_mul_f32_e32 v131, 0xbfb8aa3b, v150
	v_exp_f32_e32 v172, v131
	v_mul_f32_e32 v131, 0xbfb8aa3b, v151
	v_exp_f32_e32 v173, v131
	s_waitcnt lgkmcnt(0)
	v_cndmask_b32_e64 v149, v147, v148, s[4:5]
	v_pk_add_f32 v[172:173], v[172:173], 1.0 op_sel_hi:[1,0]
	s_nop 0
	v_rcp_f32_e32 v133, v173
	s_nop 0
	v_mul_f32_e32 v131, v151, v133
	v_rcp_f32_e32 v148, v172
	s_nop 0
	v_mul_f32_e32 v133, v150, v148
	v_pk_fma_f32 v[150:151], v[152:153], v[186:187], v[192:193]
	v_mov_b32_e32 v148, v43
	v_pk_fma_f32 v[150:151], v[42:43], v[188:189], v[150:151]
	s_nop 0
	v_pk_fma_f32 v[150:151], v[148:149], v[190:191], v[150:151]
	s_nop 0
	v_mul_f32_e32 v148, 0xbfb8aa3b, v150
	v_mul_f32_e32 v149, 0xbfb8aa3b, v151
	v_exp_f32_e32 v148, v148
	v_exp_f32_e32 v149, v149
	s_nop 0
	v_pk_add_f32 v[152:153], v[148:149], 1.0 op_sel_hi:[1,0]
	s_nop 0
	v_rcp_f32_e32 v149, v153
	s_nop 0
	v_mul_f32_e32 v148, v151, v149
	v_rcp_f32_e32 v151, v152
	s_mov_b64 s[26:27], -1
	v_mul_f32_e32 v149, v150, v151
	s_and_b64 vcc, exec, s[0:1]
	s_cbranch_vccnz .LBB0_1279
	s_and_b64 s[26:27], s[24:25], exec
	v_readlane_b32 s26, v252, 45
	v_readlane_b32 s28, v252, 47
	v_readlane_b32 s27, v252, 46
	v_readlane_b32 s29, v252, 48
	v_lshlrev_b64 v[144:145], 11, v[144:145]
	s_cselect_b32 s27, s27, s29
	s_cselect_b32 s26, s26, s28
	v_readlane_b32 s36, v252, 26
	s_movk_i32 s28, 0xf000
	v_readlane_b32 s37, v252, 27
	v_lshl_add_u64 v[144:145], s[26:27], 0, v[144:145]
	s_mov_b32 s29, s37
	s_cselect_b32 s28, s28, 0xffffe800
	v_lshl_add_u64 v[144:145], v[128:129], 1, v[144:145]
	v_lshl_add_u64 v[144:145], v[144:145], 0, s[28:29]
	v_cvt_pk_bf16_f32 v150, v133, s0
	global_store_short v[144:145], v150, off
	v_cvt_pk_bf16_f32 v150, v131, s0
	s_mov_b32 s27, s37
	global_store_short v[144:145], v150, off offset:2048
	v_add_co_u32_e32 v144, vcc, 0x1000, v144
	v_writelane_b32 v252, s26, 26
	v_cvt_pk_bf16_f32 v150, v149, s0
	v_addc_co_u32_e32 v145, vcc, 0, v145, vcc
	v_writelane_b32 v252, s27, 27
	global_store_short v[144:145], v150, off
	v_cvt_pk_bf16_f32 v150, v148, s0
	s_mov_b64 s[26:27], 0
	global_store_short v[144:145], v150, off offset:2048

.LBB0_1281:
	v_mov_b32_e32 v150, v45
	ds_bpermute_b32 v131, v244, v47
	ds_bpermute_b32 v144, v244, v0
	v_mov_b32_e32 v151, v46
	s_waitcnt lgkmcnt(1)
	v_cndmask_b32_e64 v146, v131, v146, s[4:5]
	s_waitcnt lgkmcnt(0)
	v_cndmask_b32_e64 v149, v144, v147, s[4:5]
	v_mov_b32_e32 v147, v44
	v_pk_fma_f32 v[146:147], v[186:187], v[146:147], v[192:193]
	s_nop 0
	v_pk_fma_f32 v[146:147], v[44:45], v[188:189], v[146:147]
	s_nop 0
	v_pk_fma_f32 v[146:147], v[150:151], v[190:191], v[146:147]
	s_nop 0
	v_mul_f32_e32 v133, 0xbfb8aa3b, v146
	v_exp_f32_e32 v152, v133
	v_mul_f32_e32 v133, 0xbfb8aa3b, v147
	v_exp_f32_e32 v153, v133
	s_nop 0
	v_pk_add_f32 v[152:153], v[152:153], 1.0 op_sel_hi:[1,0]
	s_nop 0
	v_rcp_f32_e32 v145, v153
	s_nop 0
	v_mul_f32_e32 v133, v147, v145
	v_rcp_f32_e32 v147, v152
	s_nop 0
	v_mul_f32_e32 v145, v146, v147
	v_pk_fma_f32 v[146:147], v[150:151], v[186:187], v[192:193]
	v_mov_b32_e32 v148, v47
	v_pk_fma_f32 v[146:147], v[46:47], v[188:189], v[146:147]
	s_nop 0
	v_pk_fma_f32 v[148:149], v[148:149], v[190:191], v[146:147]
	s_nop 0
	v_mul_f32_e32 v146, 0xbfb8aa3b, v148
	v_mul_f32_e32 v147, 0xbfb8aa3b, v149
	v_exp_f32_e32 v146, v146
	v_exp_f32_e32 v147, v147
	s_nop 0
	v_pk_add_f32 v[150:151], v[146:147], 1.0 op_sel_hi:[1,0]
	s_nop 0
	v_rcp_f32_e32 v147, v151
	s_nop 0
	v_mul_f32_e32 v146, v149, v147
	v_rcp_f32_e32 v149, v150
	s_mov_b64 s[26:27], -1
	v_mul_f32_e32 v147, v148, v149
	s_and_b64 vcc, exec, s[0:1]
	s_cbranch_vccnz .LBB0_1283
	s_and_b64 s[26:27], s[24:25], exec
	v_readlane_b32 s26, v252, 45
	v_readlane_b32 s28, v252, 47
	v_readlane_b32 s27, v252, 46
	v_readlane_b32 s29, v252, 48
	v_lshlrev_b64 v[142:143], 11, v[142:143]
	s_cselect_b32 s27, s27, s29
	s_cselect_b32 s26, s26, s28
	v_readlane_b32 s36, v252, 26
	s_movk_i32 s28, 0xf000
	v_readlane_b32 s37, v252, 27
	v_lshl_add_u64 v[142:143], s[26:27], 0, v[142:143]
	s_mov_b32 s29, s37
	s_cselect_b32 s28, s28, 0xffffe800
	v_lshl_add_u64 v[142:143], v[128:129], 1, v[142:143]
	v_lshl_add_u64 v[142:143], v[142:143], 0, s[28:29]
	v_cvt_pk_bf16_f32 v148, v145, s0
	global_store_short v[142:143], v148, off
	v_cvt_pk_bf16_f32 v148, v133, s0
	s_mov_b32 s27, s37
	global_store_short v[142:143], v148, off offset:2048
	v_add_co_u32_e32 v142, vcc, 0x1000, v142
	v_writelane_b32 v252, s26, 26
	v_cvt_pk_bf16_f32 v148, v147, s0
	v_addc_co_u32_e32 v143, vcc, 0, v143, vcc
	v_writelane_b32 v252, s27, 27
	global_store_short v[142:143], v148, off
	v_cvt_pk_bf16_f32 v148, v146, s0
	s_mov_b64 s[26:27], 0
	global_store_short v[142:143], v148, off offset:2048

.LBB0_1285:
	v_mov_b32_e32 v147, v0
	ds_bpermute_b32 v142, v244, v3
	v_mov_b32_e32 v148, v1
	v_mov_b32_e32 v149, v2
	s_waitcnt lgkmcnt(0)
	v_cndmask_b32_e64 v146, v142, v131, s[4:5]
	v_pk_fma_f32 v[146:147], v[186:187], v[146:147], v[192:193]
	v_pk_fma_f32 v[146:147], v[0:1], v[188:189], v[146:147]
	v_pk_fma_f32 v[146:147], v[148:149], v[190:191], v[146:147]
	ds_bpermute_b32 v143, v244, v4
	v_mul_f32_e32 v131, 0xbfb8aa3b, v146
	v_exp_f32_e32 v150, v131
	v_mul_f32_e32 v131, 0xbfb8aa3b, v147
	v_exp_f32_e32 v151, v131
	s_waitcnt lgkmcnt(0)
	v_cndmask_b32_e64 v145, v143, v144, s[4:5]
	v_pk_add_f32 v[150:151], v[150:151], 1.0 op_sel_hi:[1,0]
	s_nop 0
	v_rcp_f32_e32 v133, v151
	s_nop 0
	v_mul_f32_e32 v131, v147, v133
	v_rcp_f32_e32 v144, v150
	s_nop 0
	v_mul_f32_e32 v133, v146, v144
	v_pk_fma_f32 v[146:147], v[148:149], v[186:187], v[192:193]
	v_mov_b32_e32 v144, v3
	v_pk_fma_f32 v[146:147], v[2:3], v[188:189], v[146:147]
	s_nop 0
	v_pk_fma_f32 v[146:147], v[144:145], v[190:191], v[146:147]
	s_nop 0
	v_mul_f32_e32 v144, 0xbfb8aa3b, v146
	v_mul_f32_e32 v145, 0xbfb8aa3b, v147
	v_exp_f32_e32 v144, v144
	v_exp_f32_e32 v145, v145
	s_nop 0
	v_pk_add_f32 v[148:149], v[144:145], 1.0 op_sel_hi:[1,0]
	s_nop 0
	v_rcp_f32_e32 v145, v149
	s_nop 0
	v_mul_f32_e32 v144, v147, v145
	v_rcp_f32_e32 v147, v148
	s_mov_b64 s[26:27], -1
	v_mul_f32_e32 v145, v146, v147
	s_and_b64 vcc, exec, s[0:1]
	s_cbranch_vccnz .LBB0_1287
	s_and_b64 s[26:27], s[24:25], exec
	v_readlane_b32 s26, v252, 45
	v_readlane_b32 s28, v252, 47
	v_readlane_b32 s27, v252, 46
	v_readlane_b32 s29, v252, 48
	v_lshlrev_b64 v[140:141], 11, v[140:141]
	s_cselect_b32 s27, s27, s29
	s_cselect_b32 s26, s26, s28
	v_readlane_b32 s36, v252, 26
	s_movk_i32 s28, 0xf000
	v_readlane_b32 s37, v252, 27
	v_lshl_add_u64 v[140:141], s[26:27], 0, v[140:141]
	s_mov_b32 s29, s37
	s_cselect_b32 s28, s28, 0xffffe800
	v_lshl_add_u64 v[140:141], v[128:129], 1, v[140:141]
	v_lshl_add_u64 v[140:141], v[140:141], 0, s[28:29]
	v_cvt_pk_bf16_f32 v146, v133, s0
	global_store_short v[140:141], v146, off
	v_cvt_pk_bf16_f32 v146, v131, s0
	s_mov_b32 s27, s37
	global_store_short v[140:141], v146, off offset:2048
	v_add_co_u32_e32 v140, vcc, 0x1000, v140
	v_writelane_b32 v252, s26, 26
	v_cvt_pk_bf16_f32 v146, v145, s0
	v_addc_co_u32_e32 v141, vcc, 0, v141, vcc
	v_writelane_b32 v252, s27, 27
	global_store_short v[140:141], v146, off
	v_cvt_pk_bf16_f32 v146, v144, s0
	s_mov_b64 s[26:27], 0
	global_store_short v[140:141], v146, off offset:2048

.LBB0_1289:
	v_mov_b32_e32 v146, v5
	ds_bpermute_b32 v131, v244, v7
	ds_bpermute_b32 v140, v244, v8
	v_mov_b32_e32 v147, v6
	s_waitcnt lgkmcnt(1)
	v_cndmask_b32_e64 v142, v131, v142, s[4:5]
	s_waitcnt lgkmcnt(0)
	v_cndmask_b32_e64 v145, v140, v143, s[4:5]
	v_mov_b32_e32 v143, v4
	v_pk_fma_f32 v[142:143], v[186:187], v[142:143], v[192:193]
	s_nop 0
	v_pk_fma_f32 v[142:143], v[4:5], v[188:189], v[142:143]
	s_nop 0
	v_pk_fma_f32 v[142:143], v[146:147], v[190:191], v[142:143]
	s_nop 0
	v_mul_f32_e32 v133, 0xbfb8aa3b, v142
	v_exp_f32_e32 v148, v133
	v_mul_f32_e32 v133, 0xbfb8aa3b, v143
	v_exp_f32_e32 v149, v133
	s_nop 0
	v_pk_add_f32 v[148:149], v[148:149], 1.0 op_sel_hi:[1,0]
	s_nop 0
	v_rcp_f32_e32 v141, v149
	s_nop 0
	v_mul_f32_e32 v133, v143, v141
	v_rcp_f32_e32 v143, v148
	s_nop 0
	v_mul_f32_e32 v141, v142, v143
	v_pk_fma_f32 v[142:143], v[146:147], v[186:187], v[192:193]
	v_mov_b32_e32 v144, v7
	v_pk_fma_f32 v[142:143], v[6:7], v[188:189], v[142:143]
	s_nop 0
	v_pk_fma_f32 v[144:145], v[144:145], v[190:191], v[142:143]
	s_nop 0
	v_mul_f32_e32 v142, 0xbfb8aa3b, v144
	v_mul_f32_e32 v143, 0xbfb8aa3b, v145
	v_exp_f32_e32 v142, v142
	v_exp_f32_e32 v143, v143
	s_nop 0
	v_pk_add_f32 v[146:147], v[142:143], 1.0 op_sel_hi:[1,0]
	s_nop 0
	v_rcp_f32_e32 v143, v147
	s_nop 0
	v_mul_f32_e32 v142, v145, v143
	v_rcp_f32_e32 v145, v146
	s_mov_b64 s[26:27], -1
	v_mul_f32_e32 v143, v144, v145
	s_and_b64 vcc, exec, s[0:1]
	s_cbranch_vccnz .LBB0_1291
	s_and_b64 s[26:27], s[24:25], exec
	v_readlane_b32 s26, v252, 45
	v_readlane_b32 s28, v252, 47
	v_readlane_b32 s27, v252, 46
	v_readlane_b32 s29, v252, 48
	v_lshlrev_b64 v[138:139], 11, v[138:139]
	s_cselect_b32 s27, s27, s29
	s_cselect_b32 s26, s26, s28
	v_readlane_b32 s36, v252, 26
	s_movk_i32 s28, 0xf000
	v_readlane_b32 s37, v252, 27
	v_lshl_add_u64 v[138:139], s[26:27], 0, v[138:139]
	s_mov_b32 s29, s37
	s_cselect_b32 s28, s28, 0xffffe800
	v_lshl_add_u64 v[138:139], v[128:129], 1, v[138:139]
	v_lshl_add_u64 v[138:139], v[138:139], 0, s[28:29]
	v_cvt_pk_bf16_f32 v144, v141, s0
	global_store_short v[138:139], v144, off
	v_cvt_pk_bf16_f32 v144, v133, s0
	s_mov_b32 s27, s37
	global_store_short v[138:139], v144, off offset:2048
	v_add_co_u32_e32 v138, vcc, 0x1000, v138
	v_writelane_b32 v252, s26, 26
	v_cvt_pk_bf16_f32 v144, v143, s0
	v_addc_co_u32_e32 v139, vcc, 0, v139, vcc
	v_writelane_b32 v252, s27, 27
	global_store_short v[138:139], v144, off
	v_cvt_pk_bf16_f32 v144, v142, s0
	s_mov_b64 s[26:27], 0
	global_store_short v[138:139], v144, off offset:2048

.LBB0_1293:
	v_mov_b32_e32 v143, v8
	ds_bpermute_b32 v138, v244, v11
	v_mov_b32_e32 v144, v9
	v_mov_b32_e32 v145, v10
	s_waitcnt lgkmcnt(0)
	v_cndmask_b32_e64 v142, v138, v131, s[4:5]
	v_pk_fma_f32 v[142:143], v[186:187], v[142:143], v[192:193]
	v_pk_fma_f32 v[142:143], v[8:9], v[188:189], v[142:143]
	v_pk_fma_f32 v[142:143], v[144:145], v[190:191], v[142:143]
	ds_bpermute_b32 v139, v244, v12
	v_mul_f32_e32 v131, 0xbfb8aa3b, v142
	v_exp_f32_e32 v146, v131
	v_mul_f32_e32 v131, 0xbfb8aa3b, v143
	v_exp_f32_e32 v147, v131
	s_waitcnt lgkmcnt(0)
	v_cndmask_b32_e64 v141, v139, v140, s[4:5]
	v_pk_add_f32 v[146:147], v[146:147], 1.0 op_sel_hi:[1,0]
	s_nop 0
	v_rcp_f32_e32 v133, v147
	s_nop 0
	v_mul_f32_e32 v131, v143, v133
	v_rcp_f32_e32 v140, v146
	s_nop 0
	v_mul_f32_e32 v133, v142, v140
	v_pk_fma_f32 v[142:143], v[144:145], v[186:187], v[192:193]
	v_mov_b32_e32 v140, v11
	v_pk_fma_f32 v[142:143], v[10:11], v[188:189], v[142:143]
	s_nop 0
	v_pk_fma_f32 v[142:143], v[140:141], v[190:191], v[142:143]
	s_nop 0
	v_mul_f32_e32 v140, 0xbfb8aa3b, v142
	v_mul_f32_e32 v141, 0xbfb8aa3b, v143
	v_exp_f32_e32 v140, v140
	v_exp_f32_e32 v141, v141
	s_nop 0
	v_pk_add_f32 v[144:145], v[140:141], 1.0 op_sel_hi:[1,0]
	s_nop 0
	v_rcp_f32_e32 v141, v145
	s_nop 0
	v_mul_f32_e32 v140, v143, v141
	v_rcp_f32_e32 v143, v144
	s_mov_b64 s[26:27], -1
	v_mul_f32_e32 v141, v142, v143
	s_and_b64 vcc, exec, s[0:1]
	s_cbranch_vccnz .LBB0_1295
	s_and_b64 s[26:27], s[24:25], exec
	v_readlane_b32 s26, v252, 45
	v_readlane_b32 s28, v252, 47
	v_readlane_b32 s27, v252, 46
	v_readlane_b32 s29, v252, 48
	v_lshlrev_b64 v[136:137], 11, v[136:137]
	s_cselect_b32 s27, s27, s29
	s_cselect_b32 s26, s26, s28
	v_readlane_b32 s36, v252, 26
	s_movk_i32 s28, 0xf000
	v_readlane_b32 s37, v252, 27
	v_lshl_add_u64 v[136:137], s[26:27], 0, v[136:137]
	s_mov_b32 s29, s37
	s_cselect_b32 s28, s28, 0xffffe800
	v_lshl_add_u64 v[136:137], v[128:129], 1, v[136:137]
	v_lshl_add_u64 v[136:137], v[136:137], 0, s[28:29]
	v_cvt_pk_bf16_f32 v142, v133, s0
	global_store_short v[136:137], v142, off
	v_cvt_pk_bf16_f32 v142, v131, s0
	s_mov_b32 s27, s37
	global_store_short v[136:137], v142, off offset:2048
	v_add_co_u32_e32 v136, vcc, 0x1000, v136
	v_writelane_b32 v252, s26, 26
	v_cvt_pk_bf16_f32 v142, v141, s0
	v_addc_co_u32_e32 v137, vcc, 0, v137, vcc
	v_writelane_b32 v252, s27, 27
	global_store_short v[136:137], v142, off
	v_cvt_pk_bf16_f32 v142, v140, s0
	s_mov_b64 s[26:27], 0
	global_store_short v[136:137], v142, off offset:2048

.LBB0_1297:
	v_mov_b32_e32 v137, v12
	ds_bpermute_b32 v131, v244, v15
	v_mov_b32_e32 v140, v13
	v_mov_b32_e32 v141, v14
	v_cndmask_b32_e64 v139, 0, v139, s[4:5]
	s_waitcnt lgkmcnt(0)
	v_cndmask_b32_e64 v136, v131, v138, s[4:5]
	v_pk_fma_f32 v[136:137], v[186:187], v[136:137], v[192:193]
	s_nop 0
	v_pk_fma_f32 v[136:137], v[12:13], v[188:189], v[136:137]
	s_nop 0
	v_pk_fma_f32 v[136:137], v[140:141], v[190:191], v[136:137]
	s_nop 0
	v_mul_f32_e32 v131, 0xbfb8aa3b, v136
	v_exp_f32_e32 v142, v131
	v_mul_f32_e32 v131, 0xbfb8aa3b, v137
	v_exp_f32_e32 v143, v131
	s_nop 0
	v_pk_add_f32 v[142:143], v[142:143], 1.0 op_sel_hi:[1,0]
	s_nop 0
	v_rcp_f32_e32 v133, v143
	s_nop 0
	v_mul_f32_e32 v131, v137, v133
	v_rcp_f32_e32 v137, v142
	s_nop 0
	v_mul_f32_e32 v133, v136, v137
	v_pk_fma_f32 v[136:137], v[140:141], v[186:187], v[192:193]
	v_mov_b32_e32 v138, v15
	v_pk_fma_f32 v[136:137], v[14:15], v[188:189], v[136:137]
	s_nop 0
	v_pk_fma_f32 v[138:139], v[138:139], v[190:191], v[136:137]
	s_nop 0
	v_mul_f32_e32 v136, 0xbfb8aa3b, v138
	v_mul_f32_e32 v137, 0xbfb8aa3b, v139
	v_exp_f32_e32 v136, v136
	v_exp_f32_e32 v137, v137
	s_nop 0
	v_pk_add_f32 v[140:141], v[136:137], 1.0 op_sel_hi:[1,0]
	s_nop 0
	v_rcp_f32_e32 v137, v141
	s_nop 0
	v_mul_f32_e32 v136, v139, v137
	v_rcp_f32_e32 v139, v140
	s_mov_b64 s[26:27], -1
	v_mul_f32_e32 v137, v138, v139
	s_and_b64 vcc, exec, s[0:1]
	s_cbranch_vccnz .LBB0_1299
	s_and_b64 s[0:1], s[24:25], exec
	v_readlane_b32 s0, v252, 45
	v_readlane_b32 s24, v252, 47
	v_readlane_b32 s1, v252, 46
	v_readlane_b32 s25, v252, 48
	v_lshlrev_b64 v[134:135], 11, v[134:135]
	s_cselect_b32 s1, s1, s25
	s_cselect_b32 s0, s0, s24
	v_readlane_b32 s26, v252, 26
	s_movk_i32 s24, 0xf000
	v_readlane_b32 s27, v252, 27
	v_lshl_add_u64 v[134:135], s[0:1], 0, v[134:135]
	s_mov_b32 s25, s27
	s_cselect_b32 s24, s24, 0xffffe800
	v_lshl_add_u64 v[134:135], v[128:129], 1, v[134:135]
	s_mov_b32 s1, s27
	v_writelane_b32 v252, s0, 26
	v_lshl_add_u64 v[134:135], v[134:135], 0, s[24:25]
	s_mov_b64 s[26:27], 0
	v_cvt_pk_bf16_f32 v128, v133, s0
	global_store_short v[134:135], v128, off
	v_cvt_pk_bf16_f32 v128, v131, s0
	global_store_short v[134:135], v128, off offset:2048
	v_add_co_u32_e32 v134, vcc, 0x1000, v134
	v_cvt_pk_bf16_f32 v128, v137, s0
	s_nop 0
	v_addc_co_u32_e32 v135, vcc, 0, v135, vcc
	v_writelane_b32 v252, s1, 27
	global_store_short v[134:135], v128, off
	v_cvt_pk_bf16_f32 v128, v136, s0
	global_store_short v[134:135], v128, off offset:2048

.LBB0_2336:
	s_or_b64 exec, exec, s[0:1]
	s_mov_b64 s[10:11], s[60:61]
	s_mov_b64 s[8:9], s[60:61]
	s_mov_b64 s[2:3], s[60:61]
	s_mov_b64 s[6:7], s[60:61]
	s_mov_b64 s[0:1], s[60:61]
	s_waitcnt lgkmcnt(0)
	v_mov_b32_e32 v0, v163
	v_mov_b32_e32 v1, v228
	s_barrier
	v_readlane_b32 s4, v252, 32
	v_readfirstlane_b32 s12, v1
	s_ashr_i32 s14, s12, 3
	s_mul_hi_u32 s5, s4, 0x4200
	s_cmpk_gt_i32 s14, 0xaf
	s_mulk_i32 s4, 0x4200
	s_cbranch_scc1 .LBB0_2345
	s_load_dwordx2 s[10:11], s[10:11], 0xe8
	s_nop 0
	s_load_dwordx2 s[8:9], s[8:9], 0xe8
	s_nop 0
	s_load_dwordx2 s[2:3], s[2:3], 0xd0
	s_nop 0
	s_load_dwordx2 s[18:19], s[6:7], 0xe8
	v_ashrrev_i32_e32 v2, 1, v0
	s_waitcnt lgkmcnt(0)
	s_add_u32 s6, s10, 0x11210000
	v_and_b32_e32 v155, 0xffffff80, v2
	v_bfe_u32 v2, v0, 5, 1
	v_lshrrev_b32_e32 v3, 2, v0
	v_bfe_u32 v4, v0, 2, 2
	s_addc_u32 s7, s11, 0
	v_bitop3_b32 v3, v2, v3, 3 bitop3:0x78
	v_bitop3_b32 v2, v2, v4, 2 bitop3:0x36
	s_add_u32 s8, s8, 0x19213600
	s_load_dwordx2 s[20:21], s[0:1], 0xe8
	v_lshlrev_b32_e32 v178, 4, v2
	v_lshlrev_b32_e32 v2, 6, v0
	v_lshrrev_b32_e32 v6, 4, v0
	s_addc_u32 s9, s9, 0
	s_lshl_b64 s[10:11], s[4:5], 2
	v_and_b32_e32 v179, 0x37c0, v2
	v_xor_b32_e32 v2, v6, v0
	s_add_u32 s10, s2, s10
	v_and_b32_e32 v154, 31, v0
	v_lshlrev_b32_e32 v2, 4, v2
	s_addc_u32 s11, s3, s11
	v_or_b32_e32 v5, v155, v154
	v_lshlrev_b32_e32 v177, 4, v3
	s_lshl_b32 s0, s12, 3
	v_and_b32_e32 v2, 48, v2
	v_mov_b32_e32 v3, v129
	v_lshlrev_b32_e32 v176, 6, v5
	s_and_b32 s16, s0, 56
	v_lshl_add_u64 v[4:5], s[18:19], 0, v[2:3]
	s_mov_b64 s[0:1], 0x3210000
	v_and_b32_e32 v1, 63, v0
	v_lshl_add_u64 v[156:157], v[4:5], 0, s[0:1]
	s_waitcnt lgkmcnt(0)
	v_lshl_add_u64 v[2:3], s[20:21], 0, v[2:3]
	s_mov_b64 s[0:1], 0x2190000
	v_and_b32_e32 v174, 0xc0, v0
	v_ashrrev_i32_e32 v175, 2, v0
	v_lshl_add_u64 v[158:159], v[2:3], 0, s[0:1]
	v_lshlrev_b32_e32 v2, 4, v0
	v_cmp_gt_u32_e64 s[0:1], 32, v1
	v_cmp_lt_u32_e64 s[2:3], 31, v1
	v_lshrrev_b32_e32 v1, 3, v0
	v_bitop3_b32 v0, v6, 3, v0 bitop3:0x48
	s_lshr_b32 s15, s12, 3
	v_and_b32_e32 v181, 4, v1
	v_lshlrev_b32_e32 v0, 4, v0
	v_mov_b32_e32 v1, v129
	s_and_b32 s12, s12, 7
	v_and_b32_e32 v180, 0xfffffc00, v2
	v_lshl_add_u64 v[2:3], s[18:19], 0, v[0:1]
	s_mov_b64 s[18:19], 0x32100c0
	v_lshl_add_u32 v186, s12, 11, v175
	v_lshl_add_u64 v[0:1], s[20:21], 0, v[0:1]
	s_mov_b64 s[12:13], 0x21900c0
	v_or_b32_e32 v182, 0x18000, v179
	v_add_u32_e32 v183, 0x18000, v176
	v_or_b32_e32 v184, 0x10000, v179
	v_add_u32_e32 v185, 0x10000, v176
	v_lshl_add_u64 v[160:161], v[2:3], 0, s[18:19]
	v_lshl_add_u64 v[168:169], v[0:1], 0, s[12:13]
	s_lshl_b32 s17, s14, 5
	v_lshlrev_b32_e32 v128, 1, v154
	s_mov_b32 s101, 0
	v_xor_b32_e32 v244, 32, v221
	v_lshlrev_b32_e32 v244, 2, v244
	s_branch .LBB0_2339
.LBB0_2338:
	s_or_b64 exec, exec, s[12:13]
	v_cvt_pk_bf16_f32 v143, v143, s0
	v_lshl_add_u64 v[132:133], v[132:133], 0, v[134:135]
	global_store_short v[132:133], v143, off
	v_or_b32_e32 v134, v142, v181
	v_mov_b64_e32 v[132:133], s[6:7]
	s_movk_i32 s12, 0x1600
	v_mad_i64_i32 v[132:133], s[12:13], v134, s12, v[132:133]
	v_lshl_add_u64 v[130:131], v[130:131], 1, v[132:133]
	ds_bpermute_b32 v134, v244, v115
	s_waitcnt lgkmcnt(0)
	v_cndmask_b32_e64 v144, v134, 0, s[0:1]
	s_waitcnt vmcnt(17)
	v_mul_f32_e32 v144, v136, v144
	v_fmac_f32_e32 v144, v137, v112
	s_waitcnt vmcnt(16)
	v_fmac_f32_e32 v144, v139, v113
	v_mul_f32_e32 v145, 0xbfb8aa3b, v144
	v_exp_f32_e32 v145, v145
	ds_bpermute_b32 v135, v244, v99
	ds_bpermute_b32 v132, v244, v112
	v_add_f32_e32 v145, 1.0, v145
	v_rcp_f32_e32 v148, v145
	s_waitcnt lgkmcnt(1)
	v_cndmask_b32_e64 v146, v135, 0, s[0:1]
	s_waitcnt vmcnt(15)
	v_mul_f32_e32 v146, v138, v146
	s_waitcnt vmcnt(14)
	v_fmac_f32_e32 v146, v140, v96
	v_mul_f32_e32 v147, v144, v148
	v_mov_b32_e32 v144, v147
	v_mul_f32_e32 v145, v137, v113
	v_fmac_f32_e32 v145, v136, v112
	v_fmac_f32_e32 v145, v114, v139
	v_mul_f32_e32 v112, 0xbfb8aa3b, v145
	v_exp_f32_e32 v112, v112
	s_waitcnt vmcnt(13)
	v_fmac_f32_e32 v146, v141, v97
	v_mul_f32_e32 v144, v146, v144
	v_cvt_pk_bf16_f32 v144, v144, s0
	v_add_f32_e32 v112, 1.0, v112
	global_store_short v[130:131], v144, off
	v_rcp_f32_e32 v146, v112
	v_mul_f32_e32 v147, v140, v97
	ds_bpermute_b32 v133, v244, v96
	v_fmac_f32_e32 v147, v138, v96
	v_mul_f32_e32 v144, v136, v113
	v_fmac_f32_e32 v144, v114, v137
	v_mul_f32_e32 v96, v145, v146
	v_fmac_f32_e32 v144, v115, v139
	v_mul_f32_e32 v112, 0xbfb8aa3b, v144
	v_exp_f32_e32 v145, v112
	v_fmac_f32_e32 v147, v98, v141
	s_movk_i32 s12, 0x1000
	v_mul_f32_e32 v96, v147, v96
	v_add_co_u32_e32 v112, vcc, s12, v130
	v_cvt_pk_bf16_f32 v96, v96, s0
	s_nop 0
	v_addc_co_u32_e32 v113, vcc, 0, v131, vcc
	global_store_short v[112:113], v96, off offset:1536
	v_add_f32_e32 v96, 1.0, v145
	v_rcp_f32_e32 v113, v96
	ds_bpermute_b32 v142, v244, v116
	v_mul_f32_e32 v97, v138, v97
	v_fmac_f32_e32 v97, v98, v140
	v_mul_f32_e32 v112, v144, v113
	v_mul_f32_e32 v113, v115, v137
	s_waitcnt lgkmcnt(0)
	v_cndmask_b32_e64 v132, v142, v132, s[0:1]
	v_fmac_f32_e32 v97, v99, v141
	v_mov_b32_e32 v96, v112
	v_fmac_f32_e32 v113, v114, v136
	v_mul_f32_e32 v96, v97, v96
	v_fmac_f32_e32 v113, v139, v132
	v_cvt_pk_bf16_f32 v112, v96, s0
	v_mul_f32_e32 v96, 0xbfb8aa3b, v113
	v_exp_f32_e32 v114, v96
	v_add_co_u32_e32 v96, vcc, s47, v130
	s_nop 0
	s_nop 0
	v_addc_co_u32_e32 v97, vcc, 0, v131, vcc
	global_store_short v[96:97], v112, off offset:3072
	v_add_f32_e32 v96, 1.0, v114
	v_rcp_f32_e32 v112, v96
	v_mul_f32_e32 v99, v99, v140
	v_fmac_f32_e32 v99, v98, v138
	ds_bpermute_b32 v143, v244, v100
	s_waitcnt lgkmcnt(0)
	v_cndmask_b32_e64 v133, v143, v133, s[0:1]
	v_mul_f32_e32 v97, v113, v112
	v_fmac_f32_e32 v99, v141, v133
	v_mov_b32_e32 v96, v97
	v_mul_f32_e32 v96, v99, v96
	s_movk_i32 s12, 0x4000
	v_cvt_pk_bf16_f32 v98, v96, s0
	v_add_co_u32_e32 v96, vcc, s12, v130
	s_nop 1
	v_addc_co_u32_e32 v97, vcc, 0, v131, vcc
	global_store_short v[96:97], v98, off offset:512
	s_nop 0
	ds_bpermute_b32 v98, v244, v119
	s_nop 0
	ds_bpermute_b32 v99, v244, v103
	s_waitcnt lgkmcnt(0)
	v_cndmask_b32_e64 v114, v99, v135, s[0:1]
	ds_bpermute_b32 v112, v244, v120
	v_mul_f32_e32 v114, v138, v114
	ds_bpermute_b32 v113, v244, v104
	v_cndmask_b32_e64 v96, v98, v134, s[0:1]
	v_mul_f32_e32 v96, v136, v96
	v_fmac_f32_e32 v96, v116, v137
	v_fmac_f32_e32 v96, v117, v139
	v_mul_f32_e32 v97, 0xbfb8aa3b, v96
	v_exp_f32_e32 v97, v97
	s_waitcnt lgkmcnt(1)
	v_cndmask_b32_e64 v115, v112, v142, s[0:1]
	s_waitcnt lgkmcnt(0)
	v_cndmask_b32_e64 v132, v113, v143, s[0:1]
	v_fmac_f32_e32 v114, v100, v140
	v_add_f32_e32 v97, 1.0, v97
	v_rcp_f32_e32 v134, v97
	v_fmac_f32_e32 v114, v101, v141
	s_mov_b32 s12, 0xb000
	v_mul_f32_e32 v133, v96, v134
	v_mov_b32_e32 v96, v133
	v_mul_f32_e32 v133, v117, v137
	v_fmac_f32_e32 v133, v116, v136
	v_mul_f32_e32 v96, v114, v96
	v_fmac_f32_e32 v133, v118, v139
	v_cvt_pk_bf16_f32 v114, v96, s0
	v_mul_f32_e32 v96, 0xbfb8aa3b, v133
	v_exp_f32_e32 v116, v96
	v_add_co_u32_e32 v96, vcc, s12, v130
	s_nop 1
	v_addc_co_u32_e32 v97, vcc, 0, v131, vcc
	global_store_short v[96:97], v114, off
	v_add_f32_e32 v96, 1.0, v116
	v_rcp_f32_e32 v114, v96
	v_mul_f32_e32 v116, v101, v140
	v_fmac_f32_e32 v116, v100, v138
	v_fmac_f32_e32 v116, v102, v141
	v_mul_f32_e32 v97, v133, v114
	v_mul_f32_e32 v114, v118, v137
	v_mov_b32_e32 v96, v97
	v_fmac_f32_e32 v114, v117, v136
	v_mul_f32_e32 v96, v116, v96
	v_fmac_f32_e32 v114, v119, v139
	v_cvt_pk_bf16_f32 v100, v96, s0
	v_mul_f32_e32 v96, 0xbfb8aa3b, v114
	v_exp_f32_e32 v116, v96
	s_mov_b32 s12, 0xc000
	v_add_co_u32_e32 v96, vcc, s12, v130
	s_nop 1
	v_addc_co_u32_e32 v97, vcc, 0, v131, vcc
	global_store_short v[96:97], v100, off offset:1536
	v_add_f32_e32 v96, 1.0, v116
	v_rcp_f32_e32 v100, v96
	v_mul_f32_e32 v116, v102, v140
	v_fmac_f32_e32 v116, v101, v138
	v_fmac_f32_e32 v116, v103, v141
	v_mul_f32_e32 v97, v114, v100
	v_mul_f32_e32 v101, v119, v137
	v_mov_b32_e32 v96, v97
	v_fmac_f32_e32 v101, v118, v136
	v_mul_f32_e32 v96, v116, v96
	v_fmac_f32_e32 v101, v139, v115
	v_cvt_pk_bf16_f32 v100, v96, s0
	v_mul_f32_e32 v96, 0xbfb8aa3b, v101
	v_exp_f32_e32 v114, v96
	s_mov_b32 s12, 0xd000
	v_add_co_u32_e32 v96, vcc, s12, v130
	v_mul_f32_e32 v103, v103, v140
	s_nop 0
	v_addc_co_u32_e32 v97, vcc, 0, v131, vcc
	global_store_short v[96:97], v100, off offset:3072
	v_add_f32_e32 v96, 1.0, v114
	v_rcp_f32_e32 v100, v96
	v_fmac_f32_e32 v103, v102, v138
	v_fmac_f32_e32 v103, v141, v132
	s_mov_b32 s12, 0xf000
	v_mul_f32_e32 v97, v101, v100
	v_mov_b32_e32 v96, v97
	v_mul_f32_e32 v96, v103, v96
	v_cvt_pk_bf16_f32 v100, v96, s0
	v_add_co_u32_e32 v96, vcc, s12, v130
	s_nop 1
	v_addc_co_u32_e32 v97, vcc, 0, v131, vcc
	global_store_short v[96:97], v100, off offset:512
	s_nop 0
	ds_bpermute_b32 v100, v244, v123
	s_nop 0
	ds_bpermute_b32 v101, v244, v107
	s_nop 0
	ds_bpermute_b32 v102, v244, v124
	s_nop 0
	ds_bpermute_b32 v103, v244, v108
	s_waitcnt lgkmcnt(3)
	v_cndmask_b32_e64 v96, v100, v98, s[0:1]
	v_mul_f32_e32 v96, v136, v96
	v_fmac_f32_e32 v96, v120, v137
	v_fmac_f32_e32 v96, v121, v139
	v_mul_f32_e32 v97, 0xbfb8aa3b, v96
	v_exp_f32_e32 v97, v97
	s_waitcnt lgkmcnt(2)
	v_cndmask_b32_e64 v98, v101, v99, s[0:1]
	s_waitcnt lgkmcnt(1)
	v_cndmask_b32_e64 v99, v102, v112, s[0:1]
	s_waitcnt lgkmcnt(0)
	v_cndmask_b32_e64 v112, v103, v113, s[0:1]
	v_add_f32_e32 v97, 1.0, v97
	v_rcp_f32_e32 v114, v97
	v_mul_f32_e32 v98, v138, v98
	v_fmac_f32_e32 v98, v104, v140
	v_fmac_f32_e32 v98, v105, v141
	v_mul_f32_e32 v113, v96, v114
	v_mov_b32_e32 v96, v113
	v_mul_f32_e32 v113, v121, v137
	v_fmac_f32_e32 v113, v120, v136
	v_mul_f32_e32 v96, v98, v96
	v_fmac_f32_e32 v113, v122, v139
	v_cvt_pk_bf16_f32 v98, v96, s0
	v_mul_f32_e32 v96, 0xbfb8aa3b, v113
	v_exp_f32_e32 v114, v96
	s_mov_b32 s12, 0x16000
	v_add_co_u32_e32 v96, vcc, s12, v130
	s_nop 1
	v_addc_co_u32_e32 v97, vcc, 0, v131, vcc
	global_store_short v[96:97], v98, off
	v_add_f32_e32 v96, 1.0, v114
	v_rcp_f32_e32 v98, v96
	v_mul_f32_e32 v114, v105, v140
	v_fmac_f32_e32 v114, v104, v138
	v_fmac_f32_e32 v114, v106, v141
	v_mul_f32_e32 v97, v113, v98
	v_mul_f32_e32 v104, v122, v137
	v_mov_b32_e32 v96, v97
	v_fmac_f32_e32 v104, v121, v136
	v_mul_f32_e32 v96, v114, v96
	v_fmac_f32_e32 v104, v123, v139
	v_cvt_pk_bf16_f32 v98, v96, s0
	v_mul_f32_e32 v96, 0xbfb8aa3b, v104
	v_exp_f32_e32 v113, v96
	s_mov_b32 s12, 0x17000
	v_add_co_u32_e32 v96, vcc, s12, v130
	s_nop 1
	v_addc_co_u32_e32 v97, vcc, 0, v131, vcc
	global_store_short v[96:97], v98, off offset:1536
	v_add_f32_e32 v96, 1.0, v113
	v_rcp_f32_e32 v98, v96
	v_mul_f32_e32 v113, v106, v140
	v_fmac_f32_e32 v113, v105, v138
	v_fmac_f32_e32 v113, v107, v141
	v_mul_f32_e32 v97, v104, v98
	v_mov_b32_e32 v96, v97
	v_mul_f32_e32 v104, v123, v137
	v_fmac_f32_e32 v104, v122, v136
	v_mul_f32_e32 v96, v113, v96
	v_fmac_f32_e32 v104, v139, v99
	v_cvt_pk_bf16_f32 v98, v96, s0
	v_mul_f32_e32 v96, 0xbfb8aa3b, v104
	v_exp_f32_e32 v99, v96
	s_mov_b32 s12, 0x18000
	v_add_co_u32_e32 v96, vcc, s12, v130
	s_nop 1
	v_addc_co_u32_e32 v97, vcc, 0, v131, vcc
	global_store_short v[96:97], v98, off offset:3072
	v_add_f32_e32 v96, 1.0, v99
	v_rcp_f32_e32 v98, v96
	v_mul_f32_e32 v99, v107, v140
	v_fmac_f32_e32 v99, v106, v138
	v_fmac_f32_e32 v99, v141, v112
	v_mul_f32_e32 v97, v104, v98
	v_mov_b32_e32 v96, v97
	v_mul_f32_e32 v96, v99, v96
	s_mov_b32 s12, 0x1a000
	v_cvt_pk_bf16_f32 v98, v96, s0
	v_add_co_u32_e32 v96, vcc, s12, v130
	s_nop 1
	v_addc_co_u32_e32 v97, vcc, 0, v131, vcc
	global_store_short v[96:97], v98, off offset:512
	s_nop 0
	ds_bpermute_b32 v98, v244, v127
	s_nop 0
	ds_bpermute_b32 v99, v244, v111
	s_nop 0
	ds_bpermute_b32 v104, v244, v80
	s_nop 0
	ds_bpermute_b32 v105, v244, v64
	s_waitcnt lgkmcnt(3)
	v_cndmask_b32_e64 v96, v98, v100, s[0:1]
	v_mul_f32_e32 v96, v136, v96
	v_fmac_f32_e32 v96, v124, v137
	v_fmac_f32_e32 v96, v125, v139
	v_mul_f32_e32 v97, 0xbfb8aa3b, v96
	v_exp_f32_e32 v97, v97
	s_waitcnt lgkmcnt(2)
	v_cndmask_b32_e64 v100, v99, v101, s[0:1]
	s_waitcnt lgkmcnt(1)
	v_cndmask_b32_e64 v101, v104, v102, s[0:1]
	s_waitcnt lgkmcnt(0)
	v_cndmask_b32_e64 v102, v105, v103, s[0:1]
	v_add_f32_e32 v97, 1.0, v97
	v_rcp_f32_e32 v106, v97
	v_mul_f32_e32 v100, v138, v100
	v_fmac_f32_e32 v100, v108, v140
	v_fmac_f32_e32 v100, v109, v141
	v_mul_f32_e32 v103, v96, v106
	v_mov_b32_e32 v96, v103
	v_mul_f32_e32 v103, v125, v137
	v_fmac_f32_e32 v103, v124, v136
	v_mul_f32_e32 v96, v100, v96
	v_fmac_f32_e32 v103, v126, v139
	v_cvt_pk_bf16_f32 v100, v96, s0
	v_mul_f32_e32 v96, 0xbfb8aa3b, v103
	v_exp_f32_e32 v106, v96
	s_mov_b32 s12, 0x21000
	v_add_co_u32_e32 v96, vcc, s12, v130
	s_nop 1
	v_addc_co_u32_e32 v97, vcc, 0, v131, vcc
	global_store_short v[96:97], v100, off
	v_add_f32_e32 v96, 1.0, v106
	v_rcp_f32_e32 v100, v96
	v_mul_f32_e32 v106, v109, v140
	v_fmac_f32_e32 v106, v108, v138
	v_fmac_f32_e32 v106, v110, v141
	v_mul_f32_e32 v97, v103, v100
	v_mov_b32_e32 v96, v97
	v_mul_f32_e32 v103, v126, v137
	v_fmac_f32_e32 v103, v125, v136
	v_mul_f32_e32 v96, v106, v96
	v_fmac_f32_e32 v103, v127, v139
	v_cvt_pk_bf16_f32 v100, v96, s0
	v_mul_f32_e32 v96, 0xbfb8aa3b, v103
	v_exp_f32_e32 v106, v96
	s_mov_b32 s12, 0x22000
	v_add_co_u32_e32 v96, vcc, s12, v130
	s_nop 1
	v_addc_co_u32_e32 v97, vcc, 0, v131, vcc
	global_store_short v[96:97], v100, off offset:1536
	v_add_f32_e32 v96, 1.0, v106
	v_rcp_f32_e32 v100, v96
	v_mul_f32_e32 v106, v110, v140
	v_fmac_f32_e32 v106, v109, v138
	v_fmac_f32_e32 v106, v111, v141
	v_mul_f32_e32 v97, v103, v100
	v_mov_b32_e32 v96, v97
	v_mul_f32_e32 v103, v127, v137
	v_fmac_f32_e32 v103, v126, v136
	v_mul_f32_e32 v96, v106, v96
	v_fmac_f32_e32 v103, v139, v101
	v_cvt_pk_bf16_f32 v100, v96, s0
	v_mul_f32_e32 v96, 0xbfb8aa3b, v103
	v_exp_f32_e32 v101, v96
	s_mov_b32 s12, 0x23000
	v_add_co_u32_e32 v96, vcc, s12, v130
	s_nop 1
	v_addc_co_u32_e32 v97, vcc, 0, v131, vcc
	global_store_short v[96:97], v100, off offset:3072
	v_add_f32_e32 v96, 1.0, v101
	v_rcp_f32_e32 v100, v96
	v_mul_f32_e32 v101, v111, v140
	v_fmac_f32_e32 v101, v110, v138
	v_fmac_f32_e32 v101, v141, v102
	v_mul_f32_e32 v97, v103, v100
	v_mov_b32_e32 v96, v97
	v_mul_f32_e32 v96, v101, v96
	s_mov_b32 s12, 0x25000
	v_cvt_pk_bf16_f32 v100, v96, s0
	v_add_co_u32_e32 v96, vcc, s12, v130
	s_nop 1
	v_addc_co_u32_e32 v97, vcc, 0, v131, vcc
	global_store_short v[96:97], v100, off offset:512
	s_nop 0
	ds_bpermute_b32 v100, v244, v83
	s_nop 0
	ds_bpermute_b32 v101, v244, v67
	s_nop 0
	ds_bpermute_b32 v102, v244, v84
	s_nop 0
	ds_bpermute_b32 v103, v244, v68
	s_waitcnt lgkmcnt(3)
	v_cndmask_b32_e64 v96, v100, v98, s[0:1]
	v_mul_f32_e32 v96, v136, v96
	v_fmac_f32_e32 v96, v80, v137
	v_fmac_f32_e32 v96, v81, v139
	v_mul_f32_e32 v97, 0xbfb8aa3b, v96
	v_exp_f32_e32 v97, v97
	s_waitcnt lgkmcnt(2)
	v_cndmask_b32_e64 v98, v101, v99, s[0:1]
	s_waitcnt lgkmcnt(1)
	v_cndmask_b32_e64 v99, v102, v104, s[0:1]
	s_waitcnt lgkmcnt(0)
	v_cndmask_b32_e64 v104, v103, v105, s[0:1]
	v_add_f32_e32 v97, 1.0, v97
	v_rcp_f32_e32 v106, v97
	v_mul_f32_e32 v98, v138, v98
	v_fmac_f32_e32 v98, v64, v140
	v_fmac_f32_e32 v98, v65, v141
	v_mul_f32_e32 v105, v96, v106
	v_mov_b32_e32 v96, v105
	v_mul_f32_e32 v105, v81, v137
	v_fmac_f32_e32 v105, v80, v136
	v_fmac_f32_e32 v105, v82, v139
	v_mul_f32_e32 v80, 0xbfb8aa3b, v105
	v_exp_f32_e32 v80, v80
	v_mul_f32_e32 v96, v98, v96
	s_mov_b32 s12, 0x2c000
	v_cvt_pk_bf16_f32 v98, v96, s0
	v_add_co_u32_e32 v96, vcc, s12, v130
	v_add_f32_e32 v80, 1.0, v80
	s_nop 0
	v_addc_co_u32_e32 v97, vcc, 0, v131, vcc
	global_store_short v[96:97], v98, off
	v_rcp_f32_e32 v97, v80
	v_mul_f32_e32 v98, v65, v140
	v_fmac_f32_e32 v98, v64, v138
	v_fmac_f32_e32 v98, v66, v141
	v_mul_f32_e32 v96, v82, v137
	v_fmac_f32_e32 v96, v81, v136
	v_mul_f32_e32 v64, v105, v97
	v_fmac_f32_e32 v96, v83, v139
	v_mul_f32_e32 v80, 0xbfb8aa3b, v96
	v_exp_f32_e32 v97, v80
	s_mov_b32 s12, 0x2d000
	v_mul_f32_e32 v64, v98, v64
	v_add_co_u32_e32 v80, vcc, s12, v130
	v_cvt_pk_bf16_f32 v64, v64, s0
	s_nop 0
	v_addc_co_u32_e32 v81, vcc, 0, v131, vcc
	global_store_short v[80:81], v64, off offset:1536
	v_add_f32_e32 v64, 1.0, v97
	v_rcp_f32_e32 v81, v64
	v_mul_f32_e32 v97, v66, v140
	v_fmac_f32_e32 v97, v65, v138
	v_fmac_f32_e32 v97, v67, v141
	v_mul_f32_e32 v65, v96, v81
	v_mul_f32_e32 v81, v83, v137
	v_mov_b32_e32 v64, v65
	v_fmac_f32_e32 v81, v82, v136
	v_mul_f32_e32 v64, v97, v64
	v_fmac_f32_e32 v81, v139, v99
	v_cvt_pk_bf16_f32 v80, v64, s0
	v_mul_f32_e32 v64, 0xbfb8aa3b, v81
	v_exp_f32_e32 v82, v64
	s_mov_b32 s12, 0x2e000
	v_add_co_u32_e32 v64, vcc, s12, v130
	v_mul_f32_e32 v67, v67, v140
	s_nop 0
	v_addc_co_u32_e32 v65, vcc, 0, v131, vcc
	global_store_short v[64:65], v80, off offset:3072
	v_add_f32_e32 v64, 1.0, v82
	v_rcp_f32_e32 v80, v64
	v_fmac_f32_e32 v67, v66, v138
	v_fmac_f32_e32 v67, v141, v104
	s_mov_b32 s12, 0x30000
	v_mul_f32_e32 v65, v81, v80
	v_mov_b32_e32 v64, v65
	v_mul_f32_e32 v64, v67, v64
	v_cvt_pk_bf16_f32 v66, v64, s0
	v_add_co_u32_e32 v64, vcc, s12, v130
	s_nop 1
	v_addc_co_u32_e32 v65, vcc, 0, v131, vcc
	global_store_short v[64:65], v66, off offset:512
	s_nop 0
	ds_bpermute_b32 v66, v244, v87
	s_nop 0
	ds_bpermute_b32 v67, v244, v71
	s_waitcnt lgkmcnt(0)
	v_cndmask_b32_e64 v82, v67, v101, s[0:1]
	ds_bpermute_b32 v80, v244, v88
	v_mul_f32_e32 v82, v138, v82
	ds_bpermute_b32 v81, v244, v72
	v_cndmask_b32_e64 v64, v66, v100, s[0:1]
	v_mul_f32_e32 v64, v136, v64
	v_fmac_f32_e32 v64, v84, v137
	v_fmac_f32_e32 v64, v85, v139
	v_mul_f32_e32 v65, 0xbfb8aa3b, v64
	v_exp_f32_e32 v65, v65
	v_fmac_f32_e32 v82, v68, v140
	v_fmac_f32_e32 v82, v69, v141
	s_waitcnt lgkmcnt(1)
	v_cndmask_b32_e64 v83, v80, v102, s[0:1]
	v_add_f32_e32 v65, 1.0, v65
	v_rcp_f32_e32 v98, v65
	s_mov_b32 s12, 0x37000
	s_waitcnt lgkmcnt(0)
	v_cndmask_b32_e64 v96, v81, v103, s[0:1]
	v_mul_f32_e32 v97, v64, v98
	v_mov_b32_e32 v64, v97
	v_mul_f32_e32 v97, v85, v137
	v_fmac_f32_e32 v97, v84, v136
	v_mul_f32_e32 v64, v82, v64
	v_fmac_f32_e32 v97, v86, v139
	v_cvt_pk_bf16_f32 v82, v64, s0
	v_mul_f32_e32 v64, 0xbfb8aa3b, v97
	v_exp_f32_e32 v84, v64
	v_add_co_u32_e32 v64, vcc, s12, v130
	s_nop 1
	v_addc_co_u32_e32 v65, vcc, 0, v131, vcc
	global_store_short v[64:65], v82, off
	v_add_f32_e32 v64, 1.0, v84
	v_rcp_f32_e32 v82, v64
	v_mul_f32_e32 v84, v69, v140
	v_fmac_f32_e32 v84, v68, v138
	v_fmac_f32_e32 v84, v70, v141
	v_mul_f32_e32 v65, v97, v82
	v_mul_f32_e32 v82, v86, v137
	v_mov_b32_e32 v64, v65
	v_fmac_f32_e32 v82, v85, v136
	v_mul_f32_e32 v64, v84, v64
	v_fmac_f32_e32 v82, v87, v139
	v_cvt_pk_bf16_f32 v68, v64, s0
	v_mul_f32_e32 v64, 0xbfb8aa3b, v82
	v_exp_f32_e32 v84, v64
	s_mov_b32 s12, 0x38000
	v_add_co_u32_e32 v64, vcc, s12, v130
	s_nop 1
	v_addc_co_u32_e32 v65, vcc, 0, v131, vcc
	global_store_short v[64:65], v68, off offset:1536
	v_add_f32_e32 v64, 1.0, v84
	v_rcp_f32_e32 v68, v64
	v_mul_f32_e32 v84, v70, v140
	v_fmac_f32_e32 v84, v69, v138
	v_fmac_f32_e32 v84, v71, v141
	v_mul_f32_e32 v65, v82, v68
	v_mul_f32_e32 v69, v87, v137
	v_mov_b32_e32 v64, v65
	v_fmac_f32_e32 v69, v86, v136
	v_mul_f32_e32 v64, v84, v64
	v_fmac_f32_e32 v69, v139, v83
	v_cvt_pk_bf16_f32 v68, v64, s0
	v_mul_f32_e32 v64, 0xbfb8aa3b, v69
	v_exp_f32_e32 v82, v64
	s_mov_b32 s12, 0x39000
	v_add_co_u32_e32 v64, vcc, s12, v130
	v_mul_f32_e32 v71, v71, v140
	s_nop 0
	v_addc_co_u32_e32 v65, vcc, 0, v131, vcc
	global_store_short v[64:65], v68, off offset:3072
	v_add_f32_e32 v64, 1.0, v82
	v_rcp_f32_e32 v68, v64
	v_fmac_f32_e32 v71, v70, v138
	v_fmac_f32_e32 v71, v141, v96
	s_mov_b32 s12, 0x3b000
	v_mul_f32_e32 v65, v69, v68
	v_mov_b32_e32 v64, v65
	v_mul_f32_e32 v64, v71, v64
	v_cvt_pk_bf16_f32 v68, v64, s0
	v_add_co_u32_e32 v64, vcc, s12, v130
	s_nop 1
	v_addc_co_u32_e32 v65, vcc, 0, v131, vcc
	global_store_short v[64:65], v68, off offset:512
	s_nop 0
	ds_bpermute_b32 v68, v244, v91
	s_nop 0
	ds_bpermute_b32 v69, v244, v75
	s_nop 0
	ds_bpermute_b32 v70, v244, v92
	s_nop 0
	ds_bpermute_b32 v71, v244, v76
	s_waitcnt lgkmcnt(3)
	v_cndmask_b32_e64 v64, v68, v66, s[0:1]
	v_mul_f32_e32 v64, v136, v64
	v_fmac_f32_e32 v64, v88, v137
	v_fmac_f32_e32 v64, v89, v139
	v_mul_f32_e32 v65, 0xbfb8aa3b, v64
	v_exp_f32_e32 v65, v65
	s_waitcnt lgkmcnt(2)
	v_cndmask_b32_e64 v66, v69, v67, s[0:1]
	s_waitcnt lgkmcnt(1)
	v_cndmask_b32_e64 v67, v70, v80, s[0:1]
	s_waitcnt lgkmcnt(0)
	v_cndmask_b32_e64 v80, v71, v81, s[0:1]
	v_add_f32_e32 v65, 1.0, v65
	v_rcp_f32_e32 v82, v65
	v_mul_f32_e32 v66, v138, v66
	v_fmac_f32_e32 v66, v72, v140
	v_fmac_f32_e32 v66, v73, v141
	v_mul_f32_e32 v81, v64, v82
	v_mov_b32_e32 v64, v81
	v_mul_f32_e32 v81, v89, v137
	v_fmac_f32_e32 v81, v88, v136
	v_mul_f32_e32 v64, v66, v64
	v_fmac_f32_e32 v81, v90, v139
	v_cvt_pk_bf16_f32 v66, v64, s0
	v_mul_f32_e32 v64, 0xbfb8aa3b, v81
	v_exp_f32_e32 v82, v64
	s_mov_b32 s12, 0x42000
	v_add_co_u32_e32 v64, vcc, s12, v130
	s_nop 1
	v_addc_co_u32_e32 v65, vcc, 0, v131, vcc
	global_store_short v[64:65], v66, off
	v_add_f32_e32 v64, 1.0, v82
	v_rcp_f32_e32 v66, v64
	v_mul_f32_e32 v82, v73, v140
	v_fmac_f32_e32 v82, v72, v138
	v_fmac_f32_e32 v82, v74, v141
	v_mul_f32_e32 v65, v81, v66
	v_mul_f32_e32 v72, v90, v137
	v_mov_b32_e32 v64, v65
	v_fmac_f32_e32 v72, v89, v136
	v_mul_f32_e32 v64, v82, v64
	v_fmac_f32_e32 v72, v91, v139
	v_cvt_pk_bf16_f32 v66, v64, s0
	v_mul_f32_e32 v64, 0xbfb8aa3b, v72
	v_exp_f32_e32 v81, v64
	s_mov_b32 s12, 0x43000
	v_add_co_u32_e32 v64, vcc, s12, v130
	s_nop 1
	v_addc_co_u32_e32 v65, vcc, 0, v131, vcc
	global_store_short v[64:65], v66, off offset:1536
	v_add_f32_e32 v64, 1.0, v81
	v_rcp_f32_e32 v66, v64
	v_mul_f32_e32 v81, v74, v140
	v_fmac_f32_e32 v81, v73, v138
	v_fmac_f32_e32 v81, v75, v141
	v_mul_f32_e32 v65, v72, v66
	v_mov_b32_e32 v64, v65
	v_mul_f32_e32 v72, v91, v137
	v_fmac_f32_e32 v72, v90, v136
	v_mul_f32_e32 v64, v81, v64
	v_fmac_f32_e32 v72, v139, v67
	v_cvt_pk_bf16_f32 v66, v64, s0
	v_mul_f32_e32 v64, 0xbfb8aa3b, v72
	v_exp_f32_e32 v67, v64
	s_mov_b32 s12, 0x44000
	v_add_co_u32_e32 v64, vcc, s12, v130
	s_nop 1
	v_addc_co_u32_e32 v65, vcc, 0, v131, vcc
	global_store_short v[64:65], v66, off offset:3072
	v_add_f32_e32 v64, 1.0, v67
	v_rcp_f32_e32 v66, v64
	v_mul_f32_e32 v67, v75, v140
	v_fmac_f32_e32 v67, v74, v138
	v_fmac_f32_e32 v67, v141, v80
	v_mul_f32_e32 v65, v72, v66
	v_mov_b32_e32 v64, v65
	v_mul_f32_e32 v64, v67, v64
	s_mov_b32 s12, 0x46000
	v_cvt_pk_bf16_f32 v66, v64, s0
	v_add_co_u32_e32 v64, vcc, s12, v130
	s_nop 1
	v_addc_co_u32_e32 v65, vcc, 0, v131, vcc
	global_store_short v[64:65], v66, off offset:512
	s_nop 0
	ds_bpermute_b32 v66, v244, v95
	s_nop 0
	ds_bpermute_b32 v67, v244, v79
	s_nop 0
	ds_bpermute_b32 v72, v244, v48
	s_nop 0
	ds_bpermute_b32 v73, v244, v32
	s_waitcnt lgkmcnt(3)
	v_cndmask_b32_e64 v64, v66, v68, s[0:1]
	v_mul_f32_e32 v64, v136, v64
	v_fmac_f32_e32 v64, v92, v137
	v_fmac_f32_e32 v64, v93, v139
	v_mul_f32_e32 v65, 0xbfb8aa3b, v64
	v_exp_f32_e32 v65, v65
	s_waitcnt lgkmcnt(2)
	v_cndmask_b32_e64 v68, v67, v69, s[0:1]
	s_waitcnt lgkmcnt(1)
	v_cndmask_b32_e64 v69, v72, v70, s[0:1]
	s_waitcnt lgkmcnt(0)
	v_cndmask_b32_e64 v70, v73, v71, s[0:1]
	v_add_f32_e32 v65, 1.0, v65
	v_rcp_f32_e32 v74, v65
	v_mul_f32_e32 v68, v138, v68
	v_fmac_f32_e32 v68, v76, v140
	v_fmac_f32_e32 v68, v77, v141
	v_mul_f32_e32 v71, v64, v74
	v_mov_b32_e32 v64, v71
	v_mul_f32_e32 v71, v93, v137
	v_fmac_f32_e32 v71, v92, v136
	v_mul_f32_e32 v64, v68, v64
	v_fmac_f32_e32 v71, v94, v139
	v_cvt_pk_bf16_f32 v68, v64, s0
	v_mul_f32_e32 v64, 0xbfb8aa3b, v71
	v_exp_f32_e32 v74, v64
	s_mov_b32 s12, 0x4d000
	v_add_co_u32_e32 v64, vcc, s12, v130
	s_nop 1
	v_addc_co_u32_e32 v65, vcc, 0, v131, vcc
	global_store_short v[64:65], v68, off
	v_add_f32_e32 v64, 1.0, v74
	v_rcp_f32_e32 v68, v64
	v_mul_f32_e32 v74, v77, v140
	v_fmac_f32_e32 v74, v76, v138
	v_fmac_f32_e32 v74, v78, v141
	v_mul_f32_e32 v65, v71, v68
	v_mov_b32_e32 v64, v65
	v_mul_f32_e32 v71, v94, v137
	v_fmac_f32_e32 v71, v93, v136
	v_mul_f32_e32 v64, v74, v64
	v_fmac_f32_e32 v71, v95, v139
	v_cvt_pk_bf16_f32 v68, v64, s0
	v_mul_f32_e32 v64, 0xbfb8aa3b, v71
	v_exp_f32_e32 v74, v64
	s_mov_b32 s12, 0x4e000
	v_add_co_u32_e32 v64, vcc, s12, v130
	s_nop 1
	v_addc_co_u32_e32 v65, vcc, 0, v131, vcc
	global_store_short v[64:65], v68, off offset:1536
	v_add_f32_e32 v64, 1.0, v74
	v_rcp_f32_e32 v68, v64
	v_mul_f32_e32 v74, v78, v140
	v_fmac_f32_e32 v74, v77, v138
	v_fmac_f32_e32 v74, v79, v141
	v_mul_f32_e32 v65, v71, v68
	v_mov_b32_e32 v64, v65
	v_mul_f32_e32 v71, v95, v137
	v_fmac_f32_e32 v71, v94, v136
	v_mul_f32_e32 v64, v74, v64
	v_fmac_f32_e32 v71, v139, v69
	v_cvt_pk_bf16_f32 v68, v64, s0
	v_mul_f32_e32 v64, 0xbfb8aa3b, v71
	v_exp_f32_e32 v69, v64
	s_mov_b32 s12, 0x4f000
	v_add_co_u32_e32 v64, vcc, s12, v130
	s_nop 1
	v_addc_co_u32_e32 v65, vcc, 0, v131, vcc
	global_store_short v[64:65], v68, off offset:3072
	v_add_f32_e32 v64, 1.0, v69
	v_rcp_f32_e32 v68, v64
	v_mul_f32_e32 v69, v79, v140
	v_fmac_f32_e32 v69, v78, v138
	v_fmac_f32_e32 v69, v141, v70
	v_mul_f32_e32 v65, v71, v68
	v_mov_b32_e32 v64, v65
	v_mul_f32_e32 v64, v69, v64
	s_mov_b32 s12, 0x51000
	v_cvt_pk_bf16_f32 v68, v64, s0
	v_add_co_u32_e32 v64, vcc, s12, v130
	s_nop 1
	v_addc_co_u32_e32 v65, vcc, 0, v131, vcc
	global_store_short v[64:65], v68, off offset:512
	s_nop 0
	ds_bpermute_b32 v68, v244, v51
	s_nop 0
	ds_bpermute_b32 v69, v244, v35
	s_nop 0
	ds_bpermute_b32 v70, v244, v52
	s_nop 0
	ds_bpermute_b32 v71, v244, v36
	s_waitcnt lgkmcnt(3)
	v_cndmask_b32_e64 v64, v68, v66, s[0:1]
	v_mul_f32_e32 v64, v136, v64
	v_fmac_f32_e32 v64, v48, v137
	v_fmac_f32_e32 v64, v49, v139
	v_mul_f32_e32 v65, 0xbfb8aa3b, v64
	v_exp_f32_e32 v65, v65
	s_waitcnt lgkmcnt(2)
	v_cndmask_b32_e64 v66, v69, v67, s[0:1]
	s_waitcnt lgkmcnt(1)
	v_cndmask_b32_e64 v67, v70, v72, s[0:1]
	s_waitcnt lgkmcnt(0)
	v_cndmask_b32_e64 v72, v71, v73, s[0:1]
	v_add_f32_e32 v65, 1.0, v65
	v_rcp_f32_e32 v74, v65
	v_mul_f32_e32 v66, v138, v66
	v_fmac_f32_e32 v66, v32, v140
	v_fmac_f32_e32 v66, v33, v141
	v_mul_f32_e32 v73, v64, v74
	v_mov_b32_e32 v64, v73
	v_mul_f32_e32 v73, v49, v137
	v_fmac_f32_e32 v73, v48, v136
	v_fmac_f32_e32 v73, v50, v139
	v_mul_f32_e32 v48, 0xbfb8aa3b, v73
	v_exp_f32_e32 v48, v48
	v_mul_f32_e32 v64, v66, v64
	s_mov_b32 s12, 0x58000
	v_cvt_pk_bf16_f32 v66, v64, s0
	v_add_co_u32_e32 v64, vcc, s12, v130
	v_add_f32_e32 v48, 1.0, v48
	s_nop 0
	v_addc_co_u32_e32 v65, vcc, 0, v131, vcc
	global_store_short v[64:65], v66, off
	v_rcp_f32_e32 v65, v48
	v_mul_f32_e32 v66, v33, v140
	v_fmac_f32_e32 v66, v32, v138
	v_fmac_f32_e32 v66, v34, v141
	v_mul_f32_e32 v64, v50, v137
	v_fmac_f32_e32 v64, v49, v136
	v_mul_f32_e32 v32, v73, v65
	v_fmac_f32_e32 v64, v51, v139
	v_mul_f32_e32 v48, 0xbfb8aa3b, v64
	v_exp_f32_e32 v65, v48
	s_mov_b32 s12, 0x59000
	v_mul_f32_e32 v32, v66, v32
	v_add_co_u32_e32 v48, vcc, s12, v130
	v_cvt_pk_bf16_f32 v32, v32, s0
	s_nop 0
	v_addc_co_u32_e32 v49, vcc, 0, v131, vcc
	global_store_short v[48:49], v32, off offset:1536
	v_add_f32_e32 v32, 1.0, v65
	v_rcp_f32_e32 v49, v32
	v_mul_f32_e32 v65, v34, v140
	v_fmac_f32_e32 v65, v33, v138
	v_fmac_f32_e32 v65, v35, v141
	v_mul_f32_e32 v33, v64, v49
	v_mul_f32_e32 v49, v51, v137
	v_mov_b32_e32 v32, v33
	v_fmac_f32_e32 v49, v50, v136
	v_mul_f32_e32 v32, v65, v32
	v_fmac_f32_e32 v49, v139, v67
	v_cvt_pk_bf16_f32 v48, v32, s0
	v_mul_f32_e32 v32, 0xbfb8aa3b, v49
	v_exp_f32_e32 v50, v32
	s_mov_b32 s12, 0x5a000
	v_add_co_u32_e32 v32, vcc, s12, v130
	v_mul_f32_e32 v35, v35, v140
	s_nop 0
	v_addc_co_u32_e32 v33, vcc, 0, v131, vcc
	global_store_short v[32:33], v48, off offset:3072
	v_add_f32_e32 v32, 1.0, v50
	v_rcp_f32_e32 v48, v32
	v_fmac_f32_e32 v35, v34, v138
	v_fmac_f32_e32 v35, v141, v72
	s_mov_b32 s12, 0x5c000
	v_mul_f32_e32 v33, v49, v48
	v_mov_b32_e32 v32, v33
	v_mul_f32_e32 v32, v35, v32
	v_cvt_pk_bf16_f32 v34, v32, s0
	v_add_co_u32_e32 v32, vcc, s12, v130
	s_nop 1
	v_addc_co_u32_e32 v33, vcc, 0, v131, vcc
	global_store_short v[32:33], v34, off offset:512
	s_nop 0
	ds_bpermute_b32 v34, v244, v55
	s_nop 0
	ds_bpermute_b32 v35, v244, v39
	s_waitcnt lgkmcnt(0)
	v_cndmask_b32_e64 v50, v35, v69, s[0:1]
	ds_bpermute_b32 v48, v244, v56
	v_mul_f32_e32 v50, v138, v50
	ds_bpermute_b32 v49, v244, v40
	v_cndmask_b32_e64 v32, v34, v68, s[0:1]
	v_mul_f32_e32 v32, v136, v32
	v_fmac_f32_e32 v32, v52, v137
	v_fmac_f32_e32 v32, v53, v139
	v_mul_f32_e32 v33, 0xbfb8aa3b, v32
	v_exp_f32_e32 v33, v33
	v_fmac_f32_e32 v50, v36, v140
	v_fmac_f32_e32 v50, v37, v141
	s_waitcnt lgkmcnt(1)
	v_cndmask_b32_e64 v51, v48, v70, s[0:1]
	v_add_f32_e32 v33, 1.0, v33
	v_rcp_f32_e32 v66, v33
	s_mov_b32 s12, 0x63000
	s_waitcnt lgkmcnt(0)
	v_cndmask_b32_e64 v64, v49, v71, s[0:1]
	v_mul_f32_e32 v65, v32, v66
	v_mov_b32_e32 v32, v65
	v_mul_f32_e32 v65, v53, v137
	v_fmac_f32_e32 v65, v52, v136
	v_mul_f32_e32 v32, v50, v32
	v_fmac_f32_e32 v65, v54, v139
	v_cvt_pk_bf16_f32 v50, v32, s0
	v_mul_f32_e32 v32, 0xbfb8aa3b, v65
	v_exp_f32_e32 v52, v32
	v_add_co_u32_e32 v32, vcc, s12, v130
	s_nop 1
	v_addc_co_u32_e32 v33, vcc, 0, v131, vcc
	global_store_short v[32:33], v50, off
	v_add_f32_e32 v32, 1.0, v52
	v_rcp_f32_e32 v50, v32
	v_mul_f32_e32 v52, v37, v140
	v_fmac_f32_e32 v52, v36, v138
	v_fmac_f32_e32 v52, v38, v141
	v_mul_f32_e32 v33, v65, v50
	v_mul_f32_e32 v50, v54, v137
	v_mov_b32_e32 v32, v33
	v_fmac_f32_e32 v50, v53, v136
	v_mul_f32_e32 v32, v52, v32
	v_fmac_f32_e32 v50, v55, v139
	v_cvt_pk_bf16_f32 v36, v32, s0
	v_mul_f32_e32 v32, 0xbfb8aa3b, v50
	v_exp_f32_e32 v52, v32
	s_mov_b32 s12, 0x64000
	v_add_co_u32_e32 v32, vcc, s12, v130
	s_nop 1
	v_addc_co_u32_e32 v33, vcc, 0, v131, vcc
	global_store_short v[32:33], v36, off offset:1536
	v_add_f32_e32 v32, 1.0, v52
	v_rcp_f32_e32 v36, v32
	v_mul_f32_e32 v52, v38, v140
	v_fmac_f32_e32 v52, v37, v138
	v_fmac_f32_e32 v52, v39, v141
	v_mul_f32_e32 v33, v50, v36
	v_mul_f32_e32 v37, v55, v137
	v_mov_b32_e32 v32, v33
	v_fmac_f32_e32 v37, v54, v136
	v_mul_f32_e32 v32, v52, v32
	v_fmac_f32_e32 v37, v139, v51
	v_cvt_pk_bf16_f32 v36, v32, s0
	v_mul_f32_e32 v32, 0xbfb8aa3b, v37
	v_exp_f32_e32 v50, v32
	s_mov_b32 s12, 0x65000
	v_add_co_u32_e32 v32, vcc, s12, v130
	v_mul_f32_e32 v39, v39, v140
	s_nop 0
	v_addc_co_u32_e32 v33, vcc, 0, v131, vcc
	global_store_short v[32:33], v36, off offset:3072
	v_add_f32_e32 v32, 1.0, v50
	v_rcp_f32_e32 v36, v32
	v_fmac_f32_e32 v39, v38, v138
	v_fmac_f32_e32 v39, v141, v64
	s_mov_b32 s12, 0x67000
	v_mul_f32_e32 v33, v37, v36
	v_mov_b32_e32 v32, v33
	v_mul_f32_e32 v32, v39, v32
	v_cvt_pk_bf16_f32 v36, v32, s0
	v_add_co_u32_e32 v32, vcc, s12, v130
	s_nop 1
	v_addc_co_u32_e32 v33, vcc, 0, v131, vcc
	global_store_short v[32:33], v36, off offset:512
	s_nop 0
	ds_bpermute_b32 v36, v244, v59
	s_nop 0
	ds_bpermute_b32 v37, v244, v43
	s_nop 0
	ds_bpermute_b32 v38, v244, v60
	s_nop 0
	ds_bpermute_b32 v39, v244, v44
	s_waitcnt lgkmcnt(3)
	v_cndmask_b32_e64 v32, v36, v34, s[0:1]
	v_mul_f32_e32 v32, v136, v32
	v_fmac_f32_e32 v32, v56, v137
	v_fmac_f32_e32 v32, v57, v139
	v_mul_f32_e32 v33, 0xbfb8aa3b, v32
	v_exp_f32_e32 v33, v33
	s_waitcnt lgkmcnt(2)
	v_cndmask_b32_e64 v34, v37, v35, s[0:1]
	s_waitcnt lgkmcnt(1)
	v_cndmask_b32_e64 v35, v38, v48, s[0:1]
	s_waitcnt lgkmcnt(0)
	v_cndmask_b32_e64 v48, v39, v49, s[0:1]
	v_add_f32_e32 v33, 1.0, v33
	v_rcp_f32_e32 v50, v33
	v_mul_f32_e32 v34, v138, v34
	v_fmac_f32_e32 v34, v40, v140
	v_fmac_f32_e32 v34, v41, v141
	v_mul_f32_e32 v49, v32, v50
	v_mov_b32_e32 v32, v49
	v_mul_f32_e32 v49, v57, v137
	v_fmac_f32_e32 v49, v56, v136
	v_mul_f32_e32 v32, v34, v32
	v_fmac_f32_e32 v49, v58, v139
	v_cvt_pk_bf16_f32 v34, v32, s0
	v_mul_f32_e32 v32, 0xbfb8aa3b, v49
	v_exp_f32_e32 v50, v32
	s_mov_b32 s12, 0x6e000
	v_add_co_u32_e32 v32, vcc, s12, v130
	s_nop 1
	v_addc_co_u32_e32 v33, vcc, 0, v131, vcc
	global_store_short v[32:33], v34, off
	v_add_f32_e32 v32, 1.0, v50
	v_rcp_f32_e32 v34, v32
	v_mul_f32_e32 v50, v41, v140
	v_fmac_f32_e32 v50, v40, v138
	v_fmac_f32_e32 v50, v42, v141
	v_mul_f32_e32 v33, v49, v34
	v_mul_f32_e32 v40, v58, v137
	v_mov_b32_e32 v32, v33
	v_fmac_f32_e32 v40, v57, v136
	v_mul_f32_e32 v32, v50, v32
	v_fmac_f32_e32 v40, v59, v139
	v_cvt_pk_bf16_f32 v34, v32, s0
	v_mul_f32_e32 v32, 0xbfb8aa3b, v40
	v_exp_f32_e32 v49, v32
	s_mov_b32 s12, 0x6f000
	v_add_co_u32_e32 v32, vcc, s12, v130
	s_nop 1
	v_addc_co_u32_e32 v33, vcc, 0, v131, vcc
	global_store_short v[32:33], v34, off offset:1536
	v_add_f32_e32 v32, 1.0, v49
	v_rcp_f32_e32 v34, v32
	v_mul_f32_e32 v49, v42, v140
	v_fmac_f32_e32 v49, v41, v138
	v_fmac_f32_e32 v49, v43, v141
	v_mul_f32_e32 v33, v40, v34
	v_mov_b32_e32 v32, v33
	v_mul_f32_e32 v40, v59, v137
	v_fmac_f32_e32 v40, v58, v136
	v_mul_f32_e32 v32, v49, v32
	v_fmac_f32_e32 v40, v139, v35
	v_cvt_pk_bf16_f32 v34, v32, s0
	v_mul_f32_e32 v32, 0xbfb8aa3b, v40
	v_exp_f32_e32 v35, v32
	s_mov_b32 s12, 0x70000
	v_add_co_u32_e32 v32, vcc, s12, v130
	s_nop 1
	v_addc_co_u32_e32 v33, vcc, 0, v131, vcc
	global_store_short v[32:33], v34, off offset:3072
	v_add_f32_e32 v32, 1.0, v35
	v_rcp_f32_e32 v34, v32
	v_mul_f32_e32 v35, v43, v140
	v_fmac_f32_e32 v35, v42, v138
	v_fmac_f32_e32 v35, v141, v48
	v_mul_f32_e32 v33, v40, v34
	v_mov_b32_e32 v32, v33
	v_mul_f32_e32 v32, v35, v32
	s_mov_b32 s12, 0x72000
	v_cvt_pk_bf16_f32 v34, v32, s0
	v_add_co_u32_e32 v32, vcc, s12, v130
	s_nop 1
	v_addc_co_u32_e32 v33, vcc, 0, v131, vcc
	global_store_short v[32:33], v34, off offset:512
	s_nop 0
	ds_bpermute_b32 v34, v244, v63
	s_nop 0
	ds_bpermute_b32 v35, v244, v47
	s_nop 0
	ds_bpermute_b32 v40, v244, v16
	s_nop 0
	ds_bpermute_b32 v41, v244, v0
	s_waitcnt lgkmcnt(3)
	v_cndmask_b32_e64 v32, v34, v36, s[0:1]
	v_mul_f32_e32 v32, v136, v32
	v_fmac_f32_e32 v32, v60, v137
	v_fmac_f32_e32 v32, v61, v139
	v_mul_f32_e32 v33, 0xbfb8aa3b, v32
	v_exp_f32_e32 v33, v33
	s_waitcnt lgkmcnt(2)
	v_cndmask_b32_e64 v36, v35, v37, s[0:1]
	s_waitcnt lgkmcnt(1)
	v_cndmask_b32_e64 v37, v40, v38, s[0:1]
	s_waitcnt lgkmcnt(0)
	v_cndmask_b32_e64 v38, v41, v39, s[0:1]
	v_add_f32_e32 v33, 1.0, v33
	v_rcp_f32_e32 v42, v33
	v_mul_f32_e32 v36, v138, v36
	v_fmac_f32_e32 v36, v44, v140
	v_fmac_f32_e32 v36, v45, v141
	v_mul_f32_e32 v39, v32, v42
	v_mov_b32_e32 v32, v39
	v_mul_f32_e32 v39, v61, v137
	v_fmac_f32_e32 v39, v60, v136
	v_mul_f32_e32 v32, v36, v32
	v_fmac_f32_e32 v39, v62, v139
	v_cvt_pk_bf16_f32 v36, v32, s0
	v_mul_f32_e32 v32, 0xbfb8aa3b, v39
	v_exp_f32_e32 v42, v32
	s_mov_b32 s12, 0x79000
	v_add_co_u32_e32 v32, vcc, s12, v130
	s_nop 1
	v_addc_co_u32_e32 v33, vcc, 0, v131, vcc
	global_store_short v[32:33], v36, off
	v_add_f32_e32 v32, 1.0, v42
	v_rcp_f32_e32 v36, v32
	v_mul_f32_e32 v42, v45, v140
	v_fmac_f32_e32 v42, v44, v138
	v_fmac_f32_e32 v42, v46, v141
	v_mul_f32_e32 v33, v39, v36
	v_mov_b32_e32 v32, v33
	v_mul_f32_e32 v39, v62, v137
	v_fmac_f32_e32 v39, v61, v136
	v_mul_f32_e32 v32, v42, v32
	v_fmac_f32_e32 v39, v63, v139
	v_cvt_pk_bf16_f32 v36, v32, s0
	v_mul_f32_e32 v32, 0xbfb8aa3b, v39
	v_exp_f32_e32 v42, v32
	s_mov_b32 s12, 0x7a000
	v_add_co_u32_e32 v32, vcc, s12, v130
	s_nop 1
	v_addc_co_u32_e32 v33, vcc, 0, v131, vcc
	global_store_short v[32:33], v36, off offset:1536
	v_add_f32_e32 v32, 1.0, v42
	v_rcp_f32_e32 v36, v32
	v_mul_f32_e32 v42, v46, v140
	v_fmac_f32_e32 v42, v45, v138
	v_fmac_f32_e32 v42, v47, v141
	v_mul_f32_e32 v33, v39, v36
	v_mov_b32_e32 v32, v33
	v_mul_f32_e32 v39, v63, v137
	v_fmac_f32_e32 v39, v62, v136
	v_mul_f32_e32 v32, v42, v32
	v_fmac_f32_e32 v39, v139, v37
	v_cvt_pk_bf16_f32 v36, v32, s0
	v_mul_f32_e32 v32, 0xbfb8aa3b, v39
	v_exp_f32_e32 v37, v32
	s_mov_b32 s12, 0x7b000
	v_add_co_u32_e32 v32, vcc, s12, v130
	s_nop 1
	v_addc_co_u32_e32 v33, vcc, 0, v131, vcc
	global_store_short v[32:33], v36, off offset:3072
	v_add_f32_e32 v32, 1.0, v37
	v_rcp_f32_e32 v36, v32
	v_mul_f32_e32 v37, v47, v140
	v_fmac_f32_e32 v37, v46, v138
	v_fmac_f32_e32 v37, v141, v38
	v_mul_f32_e32 v33, v39, v36
	v_mov_b32_e32 v32, v33
	v_mul_f32_e32 v32, v37, v32
	s_mov_b32 s12, 0x7d000
	v_cvt_pk_bf16_f32 v36, v32, s0
	v_add_co_u32_e32 v32, vcc, s12, v130
	s_nop 1
	v_addc_co_u32_e32 v33, vcc, 0, v131, vcc
	global_store_short v[32:33], v36, off offset:512
	s_nop 0
	ds_bpermute_b32 v36, v244, v19
	s_nop 0
	ds_bpermute_b32 v37, v244, v3
	s_nop 0
	ds_bpermute_b32 v38, v244, v20
	s_nop 0
	ds_bpermute_b32 v39, v244, v4
	s_waitcnt lgkmcnt(3)
	v_cndmask_b32_e64 v32, v36, v34, s[0:1]
	v_mul_f32_e32 v32, v136, v32
	v_fmac_f32_e32 v32, v16, v137
	v_fmac_f32_e32 v32, v17, v139
	v_mul_f32_e32 v33, 0xbfb8aa3b, v32
	v_exp_f32_e32 v33, v33
	s_waitcnt lgkmcnt(2)
	v_cndmask_b32_e64 v34, v37, v35, s[0:1]
	s_waitcnt lgkmcnt(1)
	v_cndmask_b32_e64 v35, v38, v40, s[0:1]
	s_waitcnt lgkmcnt(0)
	v_cndmask_b32_e64 v40, v39, v41, s[0:1]
	v_add_f32_e32 v33, 1.0, v33
	v_rcp_f32_e32 v42, v33
	v_mul_f32_e32 v34, v138, v34
	v_fmac_f32_e32 v34, v0, v140
	v_fmac_f32_e32 v34, v1, v141
	v_mul_f32_e32 v41, v32, v42
	v_mov_b32_e32 v32, v41
	v_mul_f32_e32 v41, v17, v137
	v_fmac_f32_e32 v41, v16, v136
	v_fmac_f32_e32 v41, v18, v139
	v_mul_f32_e32 v16, 0xbfb8aa3b, v41
	v_exp_f32_e32 v16, v16
	v_mul_f32_e32 v32, v34, v32
	s_mov_b32 s12, 0x84000
	v_cvt_pk_bf16_f32 v34, v32, s0
	v_add_co_u32_e32 v32, vcc, s12, v130
	v_add_f32_e32 v16, 1.0, v16
	s_nop 0
	v_addc_co_u32_e32 v33, vcc, 0, v131, vcc
	global_store_short v[32:33], v34, off
	v_rcp_f32_e32 v33, v16
	v_mul_f32_e32 v34, v1, v140
	v_fmac_f32_e32 v34, v0, v138
	v_fmac_f32_e32 v34, v2, v141
	v_mul_f32_e32 v32, v18, v137
	v_fmac_f32_e32 v32, v17, v136
	v_mul_f32_e32 v0, v41, v33
	v_fmac_f32_e32 v32, v19, v139
	v_mul_f32_e32 v16, 0xbfb8aa3b, v32
	v_exp_f32_e32 v33, v16
	s_mov_b32 s12, 0x85000
	v_mul_f32_e32 v0, v34, v0
	v_add_co_u32_e32 v16, vcc, s12, v130
	v_cvt_pk_bf16_f32 v0, v0, s0
	s_nop 0
	v_addc_co_u32_e32 v17, vcc, 0, v131, vcc
	global_store_short v[16:17], v0, off offset:1536
	v_add_f32_e32 v0, 1.0, v33
	v_rcp_f32_e32 v17, v0
	v_mul_f32_e32 v33, v2, v140
	v_fmac_f32_e32 v33, v1, v138
	v_fmac_f32_e32 v33, v3, v141
	v_mul_f32_e32 v1, v32, v17
	v_mul_f32_e32 v17, v19, v137
	v_mov_b32_e32 v0, v1
	v_fmac_f32_e32 v17, v18, v136
	v_mul_f32_e32 v0, v33, v0
	v_fmac_f32_e32 v17, v139, v35
	v_cvt_pk_bf16_f32 v16, v0, s0
	v_mul_f32_e32 v0, 0xbfb8aa3b, v17
	v_exp_f32_e32 v18, v0
	s_mov_b32 s12, 0x86000
	v_add_co_u32_e32 v0, vcc, s12, v130
	v_mul_f32_e32 v3, v3, v140
	s_nop 0
	v_addc_co_u32_e32 v1, vcc, 0, v131, vcc
	global_store_short v[0:1], v16, off offset:3072
	v_add_f32_e32 v0, 1.0, v18
	v_rcp_f32_e32 v16, v0
	v_fmac_f32_e32 v3, v2, v138
	v_fmac_f32_e32 v3, v141, v40
	s_mov_b32 s12, 0x88000
	v_mul_f32_e32 v1, v17, v16
	v_mov_b32_e32 v0, v1
	v_mul_f32_e32 v0, v3, v0
	v_cvt_pk_bf16_f32 v2, v0, s0
	v_add_co_u32_e32 v0, vcc, s12, v130
	s_nop 1
	v_addc_co_u32_e32 v1, vcc, 0, v131, vcc
	global_store_short v[0:1], v2, off offset:512
	s_nop 0
	ds_bpermute_b32 v2, v244, v23
	s_nop 0
	ds_bpermute_b32 v3, v244, v7
	s_waitcnt lgkmcnt(0)
	v_cndmask_b32_e64 v18, v3, v37, s[0:1]
	ds_bpermute_b32 v16, v244, v24
	v_mul_f32_e32 v18, v138, v18
	ds_bpermute_b32 v17, v244, v8
	v_cndmask_b32_e64 v0, v2, v36, s[0:1]
	v_mul_f32_e32 v0, v136, v0
	v_fmac_f32_e32 v0, v20, v137
	v_fmac_f32_e32 v0, v21, v139
	v_mul_f32_e32 v1, 0xbfb8aa3b, v0
	v_exp_f32_e32 v1, v1
	v_fmac_f32_e32 v18, v4, v140
	v_fmac_f32_e32 v18, v5, v141
	s_waitcnt lgkmcnt(1)
	v_cndmask_b32_e64 v19, v16, v38, s[0:1]
	v_add_f32_e32 v1, 1.0, v1
	v_rcp_f32_e32 v34, v1
	s_mov_b32 s12, 0x8f000
	s_waitcnt lgkmcnt(0)
	v_cndmask_b32_e64 v32, v17, v39, s[0:1]
	v_mul_f32_e32 v33, v0, v34
	v_mov_b32_e32 v0, v33
	v_mul_f32_e32 v33, v21, v137
	v_fmac_f32_e32 v33, v20, v136
	v_mul_f32_e32 v0, v18, v0
	v_fmac_f32_e32 v33, v22, v139
	v_cvt_pk_bf16_f32 v18, v0, s0
	v_mul_f32_e32 v0, 0xbfb8aa3b, v33
	v_exp_f32_e32 v20, v0
	v_add_co_u32_e32 v0, vcc, s12, v130
	s_nop 1
	v_addc_co_u32_e32 v1, vcc, 0, v131, vcc
	global_store_short v[0:1], v18, off
	v_add_f32_e32 v0, 1.0, v20
	v_rcp_f32_e32 v18, v0
	v_mul_f32_e32 v20, v5, v140
	v_fmac_f32_e32 v20, v4, v138
	v_fmac_f32_e32 v20, v6, v141
	v_mul_f32_e32 v1, v33, v18
	v_mul_f32_e32 v18, v22, v137
	v_mov_b32_e32 v0, v1
	v_fmac_f32_e32 v18, v21, v136
	v_mul_f32_e32 v0, v20, v0
	v_fmac_f32_e32 v18, v23, v139
	v_cvt_pk_bf16_f32 v4, v0, s0
	v_mul_f32_e32 v0, 0xbfb8aa3b, v18
	v_exp_f32_e32 v20, v0
	s_mov_b32 s12, 0x90000
	v_add_co_u32_e32 v0, vcc, s12, v130
	s_nop 1
	v_addc_co_u32_e32 v1, vcc, 0, v131, vcc
	global_store_short v[0:1], v4, off offset:1536
	v_add_f32_e32 v0, 1.0, v20
	v_rcp_f32_e32 v4, v0
	v_mul_f32_e32 v20, v6, v140
	v_fmac_f32_e32 v20, v5, v138
	v_fmac_f32_e32 v20, v7, v141
	v_mul_f32_e32 v1, v18, v4
	v_mul_f32_e32 v5, v23, v137
	v_mov_b32_e32 v0, v1
	v_fmac_f32_e32 v5, v22, v136
	v_mul_f32_e32 v0, v20, v0
	v_fmac_f32_e32 v5, v139, v19
	v_cvt_pk_bf16_f32 v4, v0, s0
	v_mul_f32_e32 v0, 0xbfb8aa3b, v5
	v_exp_f32_e32 v18, v0
	s_mov_b32 s12, 0x91000
	v_add_co_u32_e32 v0, vcc, s12, v130
	v_mul_f32_e32 v7, v7, v140
	s_nop 0
	v_addc_co_u32_e32 v1, vcc, 0, v131, vcc
	global_store_short v[0:1], v4, off offset:3072
	v_add_f32_e32 v0, 1.0, v18
	v_rcp_f32_e32 v4, v0
	v_fmac_f32_e32 v7, v6, v138
	v_fmac_f32_e32 v7, v141, v32
	s_mov_b32 s12, 0x93000
	v_mul_f32_e32 v1, v5, v4
	v_mov_b32_e32 v0, v1
	v_mul_f32_e32 v0, v7, v0
	v_cvt_pk_bf16_f32 v4, v0, s0
	v_add_co_u32_e32 v0, vcc, s12, v130
	s_nop 1
	v_addc_co_u32_e32 v1, vcc, 0, v131, vcc
	global_store_short v[0:1], v4, off offset:512
	s_nop 0
	ds_bpermute_b32 v4, v244, v27
	s_nop 0
	ds_bpermute_b32 v5, v244, v11
	s_nop 0
	ds_bpermute_b32 v6, v244, v28
	s_nop 0
	ds_bpermute_b32 v7, v244, v12
	s_waitcnt lgkmcnt(3)
	v_cndmask_b32_e64 v0, v4, v2, s[0:1]
	v_mul_f32_e32 v0, v136, v0
	v_fmac_f32_e32 v0, v24, v137
	v_fmac_f32_e32 v0, v25, v139
	v_mul_f32_e32 v1, 0xbfb8aa3b, v0
	v_exp_f32_e32 v1, v1
	s_waitcnt lgkmcnt(2)
	v_cndmask_b32_e64 v2, v5, v3, s[0:1]
	s_waitcnt lgkmcnt(1)
	v_cndmask_b32_e64 v3, v6, v16, s[0:1]
	s_waitcnt lgkmcnt(0)
	v_cndmask_b32_e64 v16, v7, v17, s[0:1]
	v_add_f32_e32 v1, 1.0, v1
	v_rcp_f32_e32 v18, v1
	v_mul_f32_e32 v2, v138, v2
	v_fmac_f32_e32 v2, v8, v140
	v_fmac_f32_e32 v2, v9, v141
	v_mul_f32_e32 v17, v0, v18
	v_mov_b32_e32 v0, v17
	v_mul_f32_e32 v17, v25, v137
	v_fmac_f32_e32 v17, v24, v136
	v_mul_f32_e32 v0, v2, v0
	v_fmac_f32_e32 v17, v26, v139
	v_cvt_pk_bf16_f32 v2, v0, s0
	v_mul_f32_e32 v0, 0xbfb8aa3b, v17
	v_exp_f32_e32 v18, v0
	s_mov_b32 s12, 0x9a000
	v_add_co_u32_e32 v0, vcc, s12, v130
	s_nop 1
	v_addc_co_u32_e32 v1, vcc, 0, v131, vcc
	global_store_short v[0:1], v2, off
	v_add_f32_e32 v0, 1.0, v18
	v_rcp_f32_e32 v2, v0
	v_mul_f32_e32 v18, v9, v140
	v_fmac_f32_e32 v18, v8, v138
	v_fmac_f32_e32 v18, v10, v141
	v_mul_f32_e32 v1, v17, v2
	v_mul_f32_e32 v8, v26, v137
	v_mov_b32_e32 v0, v1
	v_fmac_f32_e32 v8, v25, v136
	v_mul_f32_e32 v0, v18, v0
	v_fmac_f32_e32 v8, v27, v139
	v_cvt_pk_bf16_f32 v2, v0, s0
	v_mul_f32_e32 v0, 0xbfb8aa3b, v8
	v_exp_f32_e32 v17, v0
	s_mov_b32 s12, 0x9b000
	v_add_co_u32_e32 v0, vcc, s12, v130
	s_nop 1
	v_addc_co_u32_e32 v1, vcc, 0, v131, vcc
	global_store_short v[0:1], v2, off offset:1536
	v_add_f32_e32 v0, 1.0, v17
	v_rcp_f32_e32 v2, v0
	v_mul_f32_e32 v17, v10, v140
	v_fmac_f32_e32 v17, v9, v138
	v_fmac_f32_e32 v17, v11, v141
	v_mul_f32_e32 v1, v8, v2
	v_mov_b32_e32 v0, v1
	v_mul_f32_e32 v8, v27, v137
	v_fmac_f32_e32 v8, v26, v136
	v_mul_f32_e32 v0, v17, v0
	v_fmac_f32_e32 v8, v139, v3
	v_cvt_pk_bf16_f32 v2, v0, s0
	v_mul_f32_e32 v0, 0xbfb8aa3b, v8
	v_exp_f32_e32 v3, v0
	s_mov_b32 s12, 0x9c000
	v_add_co_u32_e32 v0, vcc, s12, v130
	s_nop 1
	v_addc_co_u32_e32 v1, vcc, 0, v131, vcc
	global_store_short v[0:1], v2, off offset:3072
	v_add_f32_e32 v0, 1.0, v3
	v_rcp_f32_e32 v2, v0
	v_mul_f32_e32 v3, v11, v140
	v_fmac_f32_e32 v3, v10, v138
	v_fmac_f32_e32 v3, v141, v16
	v_mul_f32_e32 v1, v8, v2
	v_mov_b32_e32 v0, v1
	v_mul_f32_e32 v0, v3, v0
	s_mov_b32 s12, 0x9e000
	v_cvt_pk_bf16_f32 v2, v0, s0
	v_add_co_u32_e32 v0, vcc, s12, v130
	s_nop 1
	v_addc_co_u32_e32 v1, vcc, 0, v131, vcc
	global_store_short v[0:1], v2, off offset:512
	ds_bpermute_b32 v0, v244, v31
	s_waitcnt lgkmcnt(0)
	v_cndmask_b32_e64 v0, v0, v4, s[0:1]
	v_mul_f32_e32 v0, v136, v0
	v_fmac_f32_e32 v0, v28, v137
	v_fmac_f32_e32 v0, v29, v139
	v_mul_f32_e32 v2, 0xbfb8aa3b, v0
	v_exp_f32_e32 v2, v2
	ds_bpermute_b32 v1, v244, v15
	v_add_f32_e32 v2, 1.0, v2
	v_rcp_f32_e32 v4, v2
	s_waitcnt lgkmcnt(0)
	v_cndmask_b32_e64 v1, v1, v5, s[0:1]
	v_mul_f32_e32 v1, v138, v1
	v_fmac_f32_e32 v1, v12, v140
	v_mul_f32_e32 v3, v0, v4
	v_mov_b32_e32 v0, v3
	v_mul_f32_e32 v3, v29, v137
	v_fmac_f32_e32 v1, v13, v141
	v_fmac_f32_e32 v3, v28, v136
	v_mul_f32_e32 v0, v1, v0
	v_fmac_f32_e32 v3, v139, v30
	v_cvt_pk_bf16_f32 v2, v0, s0
	v_mul_f32_e32 v0, 0xbfb8aa3b, v3
	v_exp_f32_e32 v4, v0
	s_mov_b32 s12, 0xa5000
	v_add_co_u32_e32 v0, vcc, s12, v130
	s_nop 1
	v_addc_co_u32_e32 v1, vcc, 0, v131, vcc
	global_store_short v[0:1], v2, off
	v_add_f32_e32 v0, 1.0, v4
	v_rcp_f32_e32 v2, v0
	v_mul_f32_e32 v4, v13, v140
	v_fmac_f32_e32 v4, v12, v138
	v_fmac_f32_e32 v4, v141, v14
	v_mul_f32_e32 v1, v3, v2
	v_mov_b32_e32 v0, v1
	v_mul_f32_e32 v3, v137, v30
	v_fmac_f32_e32 v3, v29, v136
	v_mul_f32_e32 v0, v4, v0
	v_fmac_f32_e32 v3, v139, v31
	v_cvt_pk_bf16_f32 v2, v0, s0
	v_mul_f32_e32 v0, 0xbfb8aa3b, v3
	v_exp_f32_e32 v4, v0
	s_mov_b32 s12, 0xa6000
	v_add_co_u32_e32 v0, vcc, s12, v130
	s_nop 1
	v_addc_co_u32_e32 v1, vcc, 0, v131, vcc
	global_store_short v[0:1], v2, off offset:1536
	v_add_f32_e32 v0, 1.0, v4
	v_rcp_f32_e32 v2, v0
	v_mul_f32_e32 v4, v140, v14
	v_fmac_f32_e32 v4, v13, v138
	v_fmac_f32_e32 v4, v141, v15
	v_mul_f32_e32 v1, v3, v2
	v_mov_b32_e32 v0, v1
	v_mul_f32_e32 v0, v4, v0
	v_mul_f32_e32 v3, v136, v30
	v_cvt_pk_bf16_f32 v2, v0, s0
	v_cndmask_b32_e64 v0, 0, v6, s[0:1]
	v_fmac_f32_e32 v3, v137, v31
	v_fmac_f32_e32 v3, v139, v0
	v_mul_f32_e32 v0, 0xbfb8aa3b, v3
	v_exp_f32_e32 v4, v0
	s_mov_b32 s12, 0xa7000
	v_add_co_u32_e32 v0, vcc, s12, v130
	v_mul_f32_e32 v5, v138, v14
	s_nop 0
	v_addc_co_u32_e32 v1, vcc, 0, v131, vcc
	global_store_short v[0:1], v2, off offset:3072
	v_add_f32_e32 v1, 1.0, v4
	v_rcp_f32_e32 v4, v1
	v_cndmask_b32_e64 v0, 0, v7, s[0:1]
	v_fmac_f32_e32 v5, v140, v15
	v_fmac_f32_e32 v5, v141, v0
	v_mul_f32_e32 v0, v3, v4
	v_readlane_b32 s12, v252, 7
	v_mul_f32_e32 v0, v5, v0
	s_add_i32 s14, s14, s12
	s_add_i32 s15, s15, s12
	v_readlane_b32 s12, v252, 8
	v_cvt_pk_bf16_f32 v2, v0, s0
	v_add_co_u32_e32 v0, vcc, 0xa9000, v130
	s_add_i32 s17, s17, s12
	s_nop 0
	v_addc_co_u32_e32 v1, vcc, 0, v131, vcc
	s_cmpk_lt_i32 s14, 0xb0
	global_store_short v[0:1], v2, off offset:512
	s_cbranch_scc0 .LBB0_2345
